# v6 + loop-edge edits in the diff-attention tile loop: rescale branch taken from SCC of the all-lanes test (second VALU compare dropped), centre-out hi/lo counters updated with SALU instead of v_cndmas
# speedup vs baseline: 1.0077x; 1.0011x over previous
; #define ALAS __attribute__((address_space(3)))
; __device__ __forceinline__ void qkt(f32x16& p0, f32x16& p1, const ALAS char* Ks, const bf16x8* qr, int r32, int hi) {
;   p0 = f32x16{}; p1 = f32x16{};
; #pragma unroll
;   for (int d0 = 0; d0 < 8; ++d0) { int cb = (d0 * 16 + hi * 8) * 2;
;     bf16x8 b0 = *(const ALAS bf16x8*)(Ks + KSWZ(r32, cb));
;     bf16x8 b1 = *(const ALAS bf16x8*)(Ks + KSWZ(32 + r32, cb));
;     p0 = __builtin_amdgcn_mfma_f32_32x32x16_bf16(b0, qr[d0], p0, 0, 0, 0);
;     p1 = __builtin_amdgcn_mfma_f32_32x32x16_bf16(b1, qr[d0], p1, 0, 0, 0); }
; }
; template <int MODE> __device__ __forceinline__ void modify2(f32x16& p0, f32x16& p1, const Mod& M, int j, float& boff) {
;   const float dq = M.a0 - (float)(j * 64); const float nsl = -M.a1;
; #pragma unroll
;   for (int r = 0; r < 16; ++r) { const float cr = (float)((r & 3) + 8 * (r >> 2));
;     p0[r] = fmaf(fabsf(dq - cr), nsl, p0[r]); p1[r] = fmaf(fabsf(dq - (cr + 32.f)), nsl, p1[r]); }
;   boff = 0.f;
.LBB0_301:
	s_and_b32 s63, s13, 1
	v_mov_b32_e32 v128, v215
	v_mov_b32_e32 v129, v214
	s_lshl_b32 s4, s63, 14
	s_add_i32 s4, s4, 0
	s_add_i32 s4, s4, 0x10000
	v_lshlrev_b32_e32 v242, 4, v128
	v_lshlrev_b32_e32 v243, 4, v129
	v_and_b32_e32 v243, 0x70, v243
	v_lshl_add_u32 v241, v129, 8, s4
	v_xad_u32 v244, v242, v243, v241
	v_add_u32_e32 v240, 32, v242
	v_xad_u32 v245, v240, v243, v241
	v_add_u32_e32 v240, 64, v242
	v_xad_u32 v246, v240, v243, v241
	v_add_u32_e32 v240, 0x60, v242
	v_xad_u32 v247, v240, v243, v241
	s_lshl_b32 s4, s12, 6
	ds_read_b128 v[148:151], v244
	ds_read_b128 v[152:155], v245
	ds_read_b128 v[156:159], v246
	ds_read_b128 v[230:233], v247
	ds_read_b128 v[234:237], v244 offset:128
	ds_read_b128 v[238:241], v245 offset:128
	s_waitcnt lgkmcnt(5)
	v_mfma_f32_32x32x16_bf16 v[128:143], v[148:151], v[160:163], 0
	ds_read_b128 v[148:151], v246 offset:128
	s_waitcnt lgkmcnt(5)
	v_mfma_f32_32x32x16_bf16 v[128:143], v[152:155], v[164:167], v[128:143]
	ds_read_b128 v[152:155], v247 offset:128
	s_waitcnt lgkmcnt(5)
	v_mfma_f32_32x32x16_bf16 v[128:143], v[156:159], v[168:171], v[128:143]
	ds_read_b128 v[144:147], v244 offset:8192
	s_waitcnt lgkmcnt(5)
	v_mfma_f32_32x32x16_bf16 v[128:143], v[230:233], v[172:175], v[128:143]
	ds_read_b128 v[230:233], v245 offset:8192
	s_waitcnt lgkmcnt(5)
	v_mfma_f32_32x32x16_bf16 v[128:143], v[234:237], v[176:179], v[128:143]
	ds_read_b128 v[234:237], v246 offset:8192
	s_waitcnt lgkmcnt(5)
	v_mfma_f32_32x32x16_bf16 v[128:143], v[238:241], v[180:183], v[128:143]
	ds_read_b128 v[238:241], v247 offset:8192
	s_waitcnt lgkmcnt(5)
	v_mfma_f32_32x32x16_bf16 v[128:143], v[148:151], v[184:187], v[128:143]
	s_waitcnt lgkmcnt(4)
	v_mfma_f32_32x32x16_bf16 v[128:143], v[152:155], v[188:191], v[128:143]
	s_waitcnt lgkmcnt(3)
	v_mfma_f32_32x32x16_bf16 v[144:159], v[144:147], v[160:163], 0
	s_waitcnt lgkmcnt(2)
	v_mfma_f32_32x32x16_bf16 v[144:159], v[230:233], v[164:167], v[144:159]
	ds_read_b128 v[230:233], v244 offset:8320
	s_waitcnt lgkmcnt(2)
	v_mfma_f32_32x32x16_bf16 v[144:159], v[234:237], v[168:171], v[144:159]
	ds_read_b128 v[234:237], v245 offset:8320
	s_waitcnt lgkmcnt(2)
	v_mfma_f32_32x32x16_bf16 v[144:159], v[238:241], v[172:175], v[144:159]
	ds_read_b128 v[238:241], v246 offset:8320
	s_waitcnt lgkmcnt(2)
	v_mfma_f32_32x32x16_bf16 v[144:159], v[230:233], v[176:179], v[144:159]
	ds_read_b128 v[230:233], v247 offset:8320
	s_waitcnt lgkmcnt(2)
	v_mfma_f32_32x32x16_bf16 v[144:159], v[234:237], v[180:183], v[144:159]
	s_waitcnt lgkmcnt(1)
	v_mfma_f32_32x32x16_bf16 v[144:159], v[238:241], v[184:187], v[144:159]
	s_waitcnt lgkmcnt(0)
	v_mfma_f32_32x32x16_bf16 v[144:159], v[230:233], v[188:191], v[144:159]
	v_cvt_f32_i32_e32 v230, s4
	v_mov_b32_e32 v231, v212
	s_nop 0
	v_sub_f32_e32 v247, v231, v230
	v_fma_f32 v231, |v247|, v213, v128
	v_add_f32_e32 v128, -1.0, v247
	v_fma_f32 v232, |v128|, v213, v129
	v_add_f32_e32 v128, -2.0, v247
	v_fma_f32 v233, |v128|, v213, v130
	v_add_f32_e32 v128, 0xc0400000, v247
	v_fma_f32 v234, |v128|, v213, v131
	v_add_f32_e32 v128, 0xc1000000, v247
	v_fma_f32 v235, |v128|, v213, v132
	v_add_f32_e32 v128, 0xc1100000, v247
	v_fma_f32 v236, |v128|, v213, v133
	v_add_f32_e32 v128, 0xc1200000, v247
	v_fma_f32 v237, |v128|, v213, v134
	v_add_f32_e32 v128, 0xc1300000, v247
	v_fma_f32 v238, |v128|, v213, v135
	v_add_f32_e32 v128, 0xc1800000, v247
	v_fma_f32 v239, |v128|, v213, v136
	v_add_f32_e32 v128, 0xc1880000, v247
	v_fma_f32 v240, |v128|, v213, v137
	v_add_f32_e32 v128, 0xc1900000, v247
	v_fma_f32 v241, |v128|, v213, v138
	v_add_f32_e32 v128, 0xc1980000, v247
	v_fma_f32 v242, |v128|, v213, v139
	v_add_f32_e32 v128, 0xc1c00000, v247
	v_fma_f32 v243, |v128|, v213, v140
	v_add_f32_e32 v128, 0xc1c80000, v247
	v_fma_f32 v244, |v128|, v213, v141
	v_add_f32_e32 v128, 0xc1d00000, v247
	v_fma_f32 v245, |v128|, v213, v142
	v_add_f32_e32 v128, 0xc1d80000, v247
	v_fma_f32 v246, |v128|, v213, v143
	v_add_f32_e32 v128, 0xc2000000, v247
	v_fma_f32 v144, |v128|, v213, v144
	v_add_f32_e32 v128, 0xc2040000, v247
	v_fma_f32 v230, |v128|, v213, v145
	v_add_f32_e32 v128, 0xc2080000, v247
	v_fma_f32 v146, |v128|, v213, v146
	v_add_f32_e32 v128, 0xc20c0000, v247
	v_fma_f32 v147, |v128|, v213, v147
	v_add_f32_e32 v128, 0xc2200000, v247
	v_fma_f32 v148, |v128|, v213, v148
	v_add_f32_e32 v128, 0xc2240000, v247
	v_fma_f32 v149, |v128|, v213, v149
	v_add_f32_e32 v128, 0xc2280000, v247
	v_fma_f32 v150, |v128|, v213, v150
	v_add_f32_e32 v128, 0xc22c0000, v247
	v_fma_f32 v151, |v128|, v213, v151
	v_add_f32_e32 v128, 0xc2400000, v247
	v_fma_f32 v152, |v128|, v213, v152
	v_add_f32_e32 v128, 0xc2440000, v247
	v_fma_f32 v153, |v128|, v213, v153
	v_add_f32_e32 v128, 0xc2480000, v247
	v_fma_f32 v154, |v128|, v213, v154
	v_add_f32_e32 v128, 0xc24c0000, v247
	v_fma_f32 v155, |v128|, v213, v155
	v_add_f32_e32 v128, 0xc2600000, v247
	v_fma_f32 v156, |v128|, v213, v156
	v_add_f32_e32 v128, 0xc2640000, v247
	v_fma_f32 v157, |v128|, v213, v157
	v_add_f32_e32 v128, 0xc2680000, v247
	v_fma_f32 v158, |v128|, v213, v158
	v_add_f32_e32 v128, 0xc26c0000, v247
	v_fma_f32 v159, |v128|, v213, v159
	v_max_f32_e32 v128, v231, v232
	v_max3_f32 v128, v128, v233, v234
	v_max3_f32 v128, v128, v235, v236
	v_max3_f32 v128, v128, v237, v238
	v_max3_f32 v128, v128, v239, v240
	v_max3_f32 v128, v128, v241, v242
	v_max3_f32 v128, v128, v243, v244
	v_max3_f32 v128, v128, v245, v246
	v_max3_f32 v128, v128, v144, v230
	v_max3_f32 v128, v128, v146, v147
	v_max3_f32 v128, v128, v148, v149
	v_max3_f32 v128, v128, v150, v151
	v_max3_f32 v128, v128, v152, v153
	v_max3_f32 v128, v128, v154, v155
	v_max3_f32 v128, v128, v156, v157
	v_max3_f32 v128, v128, v158, v159
	v_mov_b32_e32 v129, v128
	s_nop 1
	v_permlane32_swap_b32_e32 v128, v129
	v_max_f32_e32 v129, v129, v129
	v_max_f32_e32 v128, v128, v128
	v_max_f32_e32 v128, v128, v129
	v_max_f32_e32 v130, v228, v228
	v_max_f32_e32 v247, v130, v128
	v_sub_f32_e32 v129, v128, v228
	v_sub_f32_e32 v128, v228, v247
	v_mul_f32_e32 v128, 0x3e0293ee, v128
	v_exp_f32_e32 v128, v128
	v_cmp_ge_f32_e32 vcc, s87, v129
	s_cmp_eq_u64 vcc, exec
	s_cselect_b64 s[4:5], -1, 0
	v_cndmask_b32_e64 v145, v128, 1.0, s[4:5]
	s_cbranch_scc1 .LBB0_305
; __device__ __forceinline__ int crow(int r, int hi) { return (r & 3) + 8 * (r >> 2) + 4 * hi; }
; template <bool OFF>
; __device__ __forceinline__ void partialSM(f32x16& p0, f32x16& p1, float& m_reg, float& mn, float& alpha, float boff) {
;     ...
;   const float mnC = (OFF ? boff - mn : -mn) * C;
; #pragma unroll
;   for (int r = 0; r < 16; ++r) p0[r] = fmaf(p0[r], C, mnC);
; #pragma unroll
;   for (int r = 0; r < 16; ++r) p1[r] = fmaf(p1[r], C, mnC);
; #pragma unroll
;   for (int r = 0; r < 16; ++r) p0[r] = __builtin_amdgcn_exp2f(p0[r]);
; }
; __device__ __forceinline__ void finishSM(f32x16& p0, f32x16& p1, float alpha, float& l_reg, bf16x8& pa0, bf16x8& pa1, bf16x8& pa2, bf16x8& pa3) {
; #pragma unroll
;   for (int r = 0; r < 16; ++r) p1[r] = __builtin_amdgcn_exp2f(p1[r]);
; __device__ __forceinline__ void b3_map(f32x16 (&o0)[4], f32x16 (&o1)[4], const AGAS bf16* __restrict__ Qb, const AGAS bf16* __restrict__ Kh, const AGAS bf16* __restrict__ V0h, const AGAS bf16* __restrict__ V1h, int NT, Mod M, ALAS char* lds) {
;     ...
;     if (__any(alpha < 1.f)) { if (hi == 0) al_l[r32] = alpha; asm volatile("s_waitcnt lgkmcnt(0)" ::: "memory");
; #pragma unroll
;       for (int r = 0; r < 16; ++r) { const float al = al_l[crow(r, hi)];
; #pragma unroll
;         for (int d = 0; d < 4; ++d) { o0[d][r] *= al; o1[d][r] *= al; } } }
	s_and_saveexec_b64 s[78:79], s[6:7]
	ds_write_b32 v218, v145 offset:128
	s_or_b64 exec, exec, s[78:79]
	s_waitcnt lgkmcnt(0)
	v_add_u32_e32 v128, s90, v196
	ds_read_b128 v[140:143], v128 offset:224
	ds_read_b128 v[136:139], v128 offset:192
	ds_read_b128 v[132:135], v128 offset:160
	ds_read_b128 v[128:131], v128 offset:128
	s_waitcnt lgkmcnt(0)
	v_pk_mul_f32 v[124:125], v[124:125], v[140:141]
	v_pk_mul_f32 v[120:121], v[120:121], v[136:137]
	v_pk_mul_f32 v[116:117], v[116:117], v[132:133]
	v_pk_mul_f32 v[126:127], v[126:127], v[142:143]
	v_pk_mul_f32 v[122:123], v[122:123], v[138:139]
	v_pk_mul_f32 v[118:119], v[118:119], v[134:135]
	v_pk_mul_f32 v[114:115], v[114:115], v[130:131]
	v_pk_mul_f32 v[112:113], v[112:113], v[128:129]
	v_pk_mul_f32 v[12:13], v[12:13], v[140:141]
	v_pk_mul_f32 v[8:9], v[8:9], v[136:137]
	v_pk_mul_f32 v[4:5], v[4:5], v[132:133]
	v_pk_mul_f32 v[14:15], v[14:15], v[142:143]
	v_pk_mul_f32 v[10:11], v[10:11], v[138:139]
	v_pk_mul_f32 v[6:7], v[6:7], v[134:135]
	v_pk_mul_f32 v[2:3], v[2:3], v[130:131]
	v_pk_mul_f32 v[0:1], v[0:1], v[128:129]
	v_pk_mul_f32 v[108:109], v[108:109], v[140:141]
	v_pk_mul_f32 v[104:105], v[104:105], v[136:137]
	v_pk_mul_f32 v[100:101], v[100:101], v[132:133]
	v_pk_mul_f32 v[110:111], v[110:111], v[142:143]
	v_pk_mul_f32 v[106:107], v[106:107], v[138:139]
	v_pk_mul_f32 v[102:103], v[102:103], v[134:135]
	v_pk_mul_f32 v[98:99], v[98:99], v[130:131]
	v_pk_mul_f32 v[96:97], v[96:97], v[128:129]
	v_pk_mul_f32 v[60:61], v[60:61], v[140:141]
	v_pk_mul_f32 v[56:57], v[56:57], v[136:137]
	v_pk_mul_f32 v[52:53], v[52:53], v[132:133]
	v_pk_mul_f32 v[62:63], v[62:63], v[142:143]
	v_pk_mul_f32 v[58:59], v[58:59], v[138:139]
	v_pk_mul_f32 v[54:55], v[54:55], v[134:135]
	v_pk_mul_f32 v[50:51], v[50:51], v[130:131]
	v_pk_mul_f32 v[48:49], v[48:49], v[128:129]
	v_pk_mul_f32 v[92:93], v[92:93], v[140:141]
	v_pk_mul_f32 v[88:89], v[88:89], v[136:137]
	v_pk_mul_f32 v[84:85], v[84:85], v[132:133]
	v_pk_mul_f32 v[94:95], v[94:95], v[142:143]
	v_pk_mul_f32 v[90:91], v[90:91], v[138:139]
	v_pk_mul_f32 v[86:87], v[86:87], v[134:135]
	v_pk_mul_f32 v[82:83], v[82:83], v[130:131]
	v_pk_mul_f32 v[80:81], v[80:81], v[128:129]
	v_pk_mul_f32 v[44:45], v[44:45], v[140:141]
	v_pk_mul_f32 v[40:41], v[40:41], v[136:137]
	v_pk_mul_f32 v[36:37], v[36:37], v[132:133]
	v_pk_mul_f32 v[46:47], v[46:47], v[142:143]
	v_pk_mul_f32 v[42:43], v[42:43], v[138:139]
	v_pk_mul_f32 v[38:39], v[38:39], v[134:135]
	v_pk_mul_f32 v[34:35], v[34:35], v[130:131]
	v_pk_mul_f32 v[32:33], v[32:33], v[128:129]
	v_pk_mul_f32 v[76:77], v[76:77], v[140:141]
	v_pk_mul_f32 v[72:73], v[72:73], v[136:137]
	v_pk_mul_f32 v[68:69], v[68:69], v[132:133]
	v_pk_mul_f32 v[78:79], v[78:79], v[142:143]
	v_pk_mul_f32 v[74:75], v[74:75], v[138:139]
	v_pk_mul_f32 v[70:71], v[70:71], v[134:135]
	v_pk_mul_f32 v[66:67], v[66:67], v[130:131]
	v_pk_mul_f32 v[64:65], v[64:65], v[128:129]
	v_pk_mul_f32 v[28:29], v[28:29], v[140:141]
	v_pk_mul_f32 v[24:25], v[24:25], v[136:137]
	v_pk_mul_f32 v[20:21], v[20:21], v[132:133]
	v_pk_mul_f32 v[30:31], v[30:31], v[142:143]
	v_pk_mul_f32 v[26:27], v[26:27], v[138:139]
	v_pk_mul_f32 v[22:23], v[22:23], v[134:135]
	v_pk_mul_f32 v[18:19], v[18:19], v[130:131]
	v_pk_mul_f32 v[16:17], v[16:17], v[128:129]
.LBB0_305:
	v_cndmask_b32_e64 v228, v247, v228, s[4:5]
	v_mul_f32_e32 v128, 0xbe0293ee, v228
	v_fmamk_f32 v129, v231, 0x3e0293ee, v128
	v_fmamk_f32 v130, v232, 0x3e0293ee, v128
	v_exp_f32_e32 v129, v129
	v_fmamk_f32 v131, v233, 0x3e0293ee, v128
	v_exp_f32_e32 v130, v130
	v_fmamk_f32 v132, v234, 0x3e0293ee, v128
	v_exp_f32_e32 v131, v131
	v_fmamk_f32 v133, v235, 0x3e0293ee, v128
	v_fmamk_f32 v134, v236, 0x3e0293ee, v128
	v_fmamk_f32 v135, v237, 0x3e0293ee, v128
	v_fmamk_f32 v136, v238, 0x3e0293ee, v128
	v_fmamk_f32 v137, v239, 0x3e0293ee, v128
	v_fmamk_f32 v138, v240, 0x3e0293ee, v128
	v_fmamk_f32 v139, v241, 0x3e0293ee, v128
	v_fmamk_f32 v140, v242, 0x3e0293ee, v128
	v_fmamk_f32 v141, v243, 0x3e0293ee, v128
	v_fmamk_f32 v142, v244, 0x3e0293ee, v128
	v_fmamk_f32 v143, v245, 0x3e0293ee, v128
	v_fmamk_f32 v231, v246, 0x3e0293ee, v128
	v_fmamk_f32 v144, v144, 0x3e0293ee, v128
	v_fmamk_f32 v230, v230, 0x3e0293ee, v128
	v_fmamk_f32 v146, v146, 0x3e0293ee, v128
	v_fmamk_f32 v147, v147, 0x3e0293ee, v128
	v_fmamk_f32 v148, v148, 0x3e0293ee, v128
	v_fmamk_f32 v149, v149, 0x3e0293ee, v128
	v_fmamk_f32 v150, v150, 0x3e0293ee, v128
	v_fmamk_f32 v151, v151, 0x3e0293ee, v128
	v_fmamk_f32 v152, v152, 0x3e0293ee, v128
	v_fmamk_f32 v153, v153, 0x3e0293ee, v128
	v_fmamk_f32 v154, v154, 0x3e0293ee, v128
	v_fmamk_f32 v155, v155, 0x3e0293ee, v128
	v_fmamk_f32 v156, v156, 0x3e0293ee, v128
	v_fmamk_f32 v157, v157, 0x3e0293ee, v128
	v_fmamk_f32 v158, v158, 0x3e0293ee, v128
	v_fmac_f32_e32 v128, 0x3e0293ee, v159
	v_exp_f32_e32 v132, v132
	v_exp_f32_e32 v133, v133
	v_exp_f32_e32 v236, v128
	v_add_f32_e32 v128, 0, v129
	v_exp_f32_e32 v134, v134
	v_add_f32_e32 v128, v130, v128
	v_exp_f32_e32 v135, v135
	v_add_f32_e32 v128, v131, v128
	v_exp_f32_e32 v136, v136
	v_add_f32_e32 v128, v132, v128
	v_exp_f32_e32 v137, v137
	v_add_f32_e32 v128, v133, v128
	v_exp_f32_e32 v138, v138
	v_add_f32_e32 v128, v134, v128
	v_exp_f32_e32 v139, v139
	v_add_f32_e32 v128, v135, v128
	v_exp_f32_e32 v159, v140
	v_add_f32_e32 v128, v136, v128
	v_exp_f32_e32 v232, v141
	v_add_f32_e32 v128, v137, v128
	v_exp_f32_e32 v233, v142
	v_add_f32_e32 v128, v138, v128
	v_exp_f32_e32 v234, v143
	v_add_f32_e32 v128, v139, v128
	v_exp_f32_e32 v231, v231
	v_add_f32_e32 v128, v159, v128
	v_exp_f32_e32 v235, v144
	v_add_f32_e32 v128, v232, v128
	v_exp_f32_e32 v230, v230
	v_add_f32_e32 v128, v233, v128
; __device__ __forceinline__ void finishSM(f32x16& p0, f32x16& p1, float alpha, float& l_reg, bf16x8& pa0, bf16x8& pa1, bf16x8& pa2, bf16x8& pa3) {
; #pragma unroll
;   for (int r = 0; r < 16; ++r) p1[r] = __builtin_amdgcn_exp2f(p1[r]);
;   float ps = 0;
; #pragma unroll
;   for (int r = 0; r < 16; ++r) ps += p0[r];
; #pragma unroll
;   for (int r = 0; r < 16; ++r) ps += p1[r];
;   { auto rr = __builtin_amdgcn_permlane32_swap(__float_as_uint(ps), __float_as_uint(ps), false, false);
;     ps = __uint_as_float(rr[0]) + __uint_as_float(rr[1]); }
;   l_reg = l_reg * alpha + ps;
;     ...
;   PK4(p0, 0, pa0); PK4(p0, 8, pa1); PK4(p1, 0, pa2); PK4(p1, 8, pa3);
	v_exp_f32_e32 v146, v146
	v_add_f32_e32 v128, v234, v128
	v_exp_f32_e32 v147, v147
	v_add_f32_e32 v128, v231, v128
	v_exp_f32_e32 v148, v148
	v_add_f32_e32 v128, v235, v128
	v_exp_f32_e32 v149, v149
	v_add_f32_e32 v128, v230, v128
	v_exp_f32_e32 v150, v150
	v_add_f32_e32 v128, v146, v128
	v_exp_f32_e32 v151, v151
	v_add_f32_e32 v128, v147, v128
	v_exp_f32_e32 v152, v152
	v_add_f32_e32 v128, v148, v128
	v_exp_f32_e32 v153, v153
	v_add_f32_e32 v128, v149, v128
	v_exp_f32_e32 v154, v154
	v_add_f32_e32 v128, v150, v128
	v_exp_f32_e32 v155, v155
	v_add_f32_e32 v128, v151, v128
	v_exp_f32_e32 v156, v156
	v_add_f32_e32 v128, v152, v128
	v_exp_f32_e32 v157, v157
	v_add_f32_e32 v128, v153, v128
	v_exp_f32_e32 v158, v158
	v_add_f32_e32 v128, v154, v128
	v_add_f32_e32 v128, v155, v128
	v_add_f32_e32 v128, v156, v128
	v_add_f32_e32 v128, v157, v128
	s_sub_i32 s93, s93, s76
	s_xor_b64 s[4:5], s[76:77], -1
	v_add_f32_e32 v128, v158, v128
	v_add_f32_e32 v128, v236, v128
	v_mov_b32_e32 v140, v128
	s_nop 1
	v_permlane32_swap_b32_e32 v128, v140
	v_add_f32_e32 v144, v128, v140
	v_cvt_pk_bf16_f32 v140, v129, v130
	v_cvt_pk_bf16_f32 v141, v131, v132
	v_cvt_pk_bf16_f32 v142, v133, v134
	v_cvt_pk_bf16_f32 v143, v135, v136
	v_cvt_pk_bf16_f32 v132, v137, v138
	v_cvt_pk_bf16_f32 v133, v139, v159
	v_cvt_pk_bf16_f32 v134, v232, v233
	v_cvt_pk_bf16_f32 v135, v234, v231
	v_cvt_pk_bf16_f32 v128, v235, v230
	v_cvt_pk_bf16_f32 v129, v146, v147
	v_cvt_pk_bf16_f32 v130, v148, v149
	v_cvt_pk_bf16_f32 v131, v150, v151
	v_cvt_pk_bf16_f32 v136, v152, v153
	v_cvt_pk_bf16_f32 v137, v154, v155
	v_cvt_pk_bf16_f32 v138, v156, v157
	v_cvt_pk_bf16_f32 v139, v158, v236
	s_waitcnt lgkmcnt(0)
	v_fmac_f32_e32 v144, v229, v145
	v_lshl_add_u32 v145, s63, 15, v227
	ds_read_b64_tr_b16 v[146:147], v145 offset:0
	ds_read_b64_tr_b16 v[148:149], v145 offset:0x800
	ds_read_b64_tr_b16 v[150:151], v145 offset:0x1000
	v_permlane32_swap_b32_e32 v140, v142
	v_permlane32_swap_b32_e32 v141, v143
	ds_read_b64_tr_b16 v[152:153], v145 offset:0x1800
	ds_read_b64_tr_b16 v[154:155], v145 offset:0x2000
	ds_read_b64_tr_b16 v[156:157], v145 offset:0x2800
	ds_read_b64_tr_b16 v[230:231], v145 offset:0x3000
	ds_read_b64_tr_b16 v[232:233], v145 offset:0x3800
	v_permlane32_swap_b32_e32 v132, v134
	s_waitcnt lgkmcnt(4)
	v_permlane32_swap_b32_e32 v133, v135
	v_mfma_f32_32x32x16_bf16 v[112:127], v[140:143], v[146:149], v[112:127]
	v_permlane32_swap_b32_e32 v128, v130
	v_permlane32_swap_b32_e32 v129, v131
	ds_read_b64_tr_b16 v[146:147], v145 offset:0x200
	ds_read_b64_tr_b16 v[148:149], v145 offset:0xa00
	v_permlane32_swap_b32_e32 v136, v138
	v_mfma_f32_32x32x16_bf16 v[112:127], v[132:135], v[150:153], v[112:127]
	ds_read_b64_tr_b16 v[150:151], v145 offset:0x1200
	ds_read_b64_tr_b16 v[152:153], v145 offset:0x1a00
	s_waitcnt lgkmcnt(4)
	v_permlane32_swap_b32_e32 v137, v139
	v_add_u32_e32 v158, 0x4000, v145
	s_add_i32 s92, s92, s4
	v_mfma_f32_32x32x16_bf16 v[112:127], v[128:131], v[154:157], v[112:127]
	ds_read_b64_tr_b16 v[154:155], v145 offset:0x2200
	ds_read_b64_tr_b16 v[156:157], v145 offset:0x2a00
	s_xor_b64 s[58:59], s[58:59], -1
	s_cmp_eq_u32 s95, 64
	v_mfma_f32_32x32x16_bf16 v[112:127], v[136:139], v[230:233], v[112:127]
	ds_read_b64_tr_b16 v[230:231], v145 offset:0x3200
	ds_read_b64_tr_b16 v[232:233], v145 offset:0x3a00
	s_waitcnt lgkmcnt(4)
	s_nop 0
	v_mfma_f32_32x32x16_bf16 v[96:111], v[140:143], v[146:149], v[96:111]
	ds_read_b64_tr_b16 v[146:147], v145 offset:0x400
	ds_read_b64_tr_b16 v[148:149], v145 offset:0xc00
	v_mfma_f32_32x32x16_bf16 v[96:111], v[132:135], v[150:153], v[96:111]
	ds_read_b64_tr_b16 v[150:151], v145 offset:0x1400
	ds_read_b64_tr_b16 v[152:153], v145 offset:0x1c00
	s_waitcnt lgkmcnt(4)
	s_nop 0
	v_mfma_f32_32x32x16_bf16 v[96:111], v[128:131], v[154:157], v[96:111]
	ds_read_b64_tr_b16 v[154:155], v145 offset:0x2400
	ds_read_b64_tr_b16 v[156:157], v145 offset:0x2c00
	v_mfma_f32_32x32x16_bf16 v[96:111], v[136:139], v[230:233], v[96:111]
	ds_read_b64_tr_b16 v[230:231], v145 offset:0x3400
	ds_read_b64_tr_b16 v[232:233], v145 offset:0x3c00
	s_waitcnt lgkmcnt(4)
; #define PVR(S, VB, D0, K0) do { S##l0 = tr_read<v_rd_off(D0, K0, 0)>(VB); S##h0 = tr_read<v_rd_off(D0, K0, 1)>(VB); S##l1 = tr_read<v_rd_off(D0, (K0) + 1, 0)>(VB); S##h1 = tr_read<v_rd_off(D0, (K0) + 1, 1)>(VB); } while (0)
; #define PVW(S, N) asm volatile("s_waitcnt lgkmcnt(" #N ")" : "+v"(S##l0), "+v"(S##h0), "+v"(S##l1), "+v"(S##h1) :: "memory")
; #define PVM(O, S, PA, PB) do { O = __builtin_amdgcn_mfma_f32_32x32x16_bf16(PA, PVK(S##l0, S##h0), O, 0, 0, 0); O = __builtin_amdgcn_mfma_f32_32x32x16_bf16(PB, PVK(S##l1, S##h1), O, 0, 0, 0); } while (0)
; __device__ __forceinline__ void pv_256(f32x16* o0, f32x16* o1, int v0, int v1, bf16x8 pa0, bf16x8 pa1, bf16x8 pa2, bf16x8 pa3) {
;   s16x4 Al0, Ah0, Al1, Ah1, Bl0, Bh0, Bl1, Bh1;
;   PVR(A, v0, 0, 0); PVR(B, v0, 0, 2);
;   PVW(A, 4); PVM(o0[0], A, pa0, pa1); PVR(A, v0, 1, 0);
;   PVW(B, 4); PVM(o0[0], B, pa2, pa3); PVR(B, v0, 1, 2);
;   PVW(A, 4); PVM(o0[1], A, pa0, pa1); PVR(A, v0, 2, 0);
;   PVW(B, 4); PVM(o0[1], B, pa2, pa3); PVR(B, v0, 2, 2);
;   PVW(A, 4); PVM(o0[2], A, pa0, pa1); PVR(A, v0, 3, 0);
;   PVW(B, 4); PVM(o0[2], B, pa2, pa3); PVR(B, v0, 3, 2);
;   PVW(A, 4); PVM(o0[3], A, pa0, pa1); PVR(A, v1, 0, 0);
;   PVW(B, 4); PVM(o0[3], B, pa2, pa3); PVR(B, v1, 0, 2);
;   PVW(A, 4); PVM(o1[0], A, pa0, pa1); PVR(A, v1, 1, 0);
;   PVW(B, 4); PVM(o1[0], B, pa2, pa3); PVR(B, v1, 1, 2);
;   PVW(A, 4); PVM(o1[1], A, pa0, pa1); PVR(A, v1, 2, 0);
;   PVW(B, 4); PVM(o1[1], B, pa2, pa3); PVR(B, v1, 2, 2);
;   PVW(A, 4); PVM(o1[2], A, pa0, pa1); PVR(A, v1, 3, 0);
;   PVW(B, 4); PVM(o1[2], B, pa2, pa3); PVR(B, v1, 3, 2);
;   PVW(A, 4); PVM(o1[3], A, pa0, pa1);
;   PVW(B, 0); PVM(o1[3], B, pa2, pa3);
; }
	s_nop 0
	v_mfma_f32_32x32x16_bf16 v[80:95], v[140:143], v[146:149], v[80:95]
	ds_read_b64_tr_b16 v[146:147], v145 offset:0x600
	ds_read_b64_tr_b16 v[148:149], v145 offset:0xe00
	v_mfma_f32_32x32x16_bf16 v[80:95], v[132:135], v[150:153], v[80:95]
	ds_read_b64_tr_b16 v[150:151], v145 offset:0x1600
	ds_read_b64_tr_b16 v[152:153], v145 offset:0x1e00
	s_waitcnt lgkmcnt(4)
	s_nop 0
	v_mfma_f32_32x32x16_bf16 v[80:95], v[128:131], v[154:157], v[80:95]
	ds_read_b64_tr_b16 v[154:155], v145 offset:0x2600
	ds_read_b64_tr_b16 v[156:157], v145 offset:0x2e00
	v_mfma_f32_32x32x16_bf16 v[80:95], v[136:139], v[230:233], v[80:95]
	ds_read_b64_tr_b16 v[230:231], v145 offset:0x3600
	ds_read_b64_tr_b16 v[232:233], v145 offset:0x3e00
	s_waitcnt lgkmcnt(4)
	s_nop 0
	v_mfma_f32_32x32x16_bf16 v[64:79], v[140:143], v[146:149], v[64:79]
	ds_read_b64_tr_b16 v[146:147], v158 offset:0
	ds_read_b64_tr_b16 v[148:149], v158 offset:0x800
	v_mfma_f32_32x32x16_bf16 v[64:79], v[132:135], v[150:153], v[64:79]
	ds_read_b64_tr_b16 v[150:151], v158 offset:0x1000
	ds_read_b64_tr_b16 v[152:153], v158 offset:0x1800
	s_waitcnt lgkmcnt(4)
	s_nop 0
	v_mfma_f32_32x32x16_bf16 v[64:79], v[128:131], v[154:157], v[64:79]
	ds_read_b64_tr_b16 v[154:155], v158 offset:0x2000
	ds_read_b64_tr_b16 v[156:157], v158 offset:0x2800
	v_mfma_f32_32x32x16_bf16 v[64:79], v[136:139], v[230:233], v[64:79]
	ds_read_b64_tr_b16 v[230:231], v158 offset:0x3000
	ds_read_b64_tr_b16 v[232:233], v158 offset:0x3800
	s_waitcnt lgkmcnt(4)
	s_nop 0
	v_mfma_f32_32x32x16_bf16 v[0:15], v[140:143], v[146:149], v[0:15]
	ds_read_b64_tr_b16 v[146:147], v158 offset:0x200
	ds_read_b64_tr_b16 v[148:149], v158 offset:0xa00
	v_mfma_f32_32x32x16_bf16 v[0:15], v[132:135], v[150:153], v[0:15]
	ds_read_b64_tr_b16 v[150:151], v158 offset:0x1200
	ds_read_b64_tr_b16 v[152:153], v158 offset:0x1a00
	s_waitcnt lgkmcnt(4)
	s_nop 0
	v_mfma_f32_32x32x16_bf16 v[0:15], v[128:131], v[154:157], v[0:15]
	ds_read_b64_tr_b16 v[154:155], v158 offset:0x2200
	ds_read_b64_tr_b16 v[156:157], v158 offset:0x2a00
	v_mfma_f32_32x32x16_bf16 v[0:15], v[136:139], v[230:233], v[0:15]
	ds_read_b64_tr_b16 v[230:231], v158 offset:0x3200
	ds_read_b64_tr_b16 v[232:233], v158 offset:0x3a00
	s_waitcnt lgkmcnt(4)
	s_nop 0
	v_mfma_f32_32x32x16_bf16 v[48:63], v[140:143], v[146:149], v[48:63]
	ds_read_b64_tr_b16 v[146:147], v158 offset:0x400
	ds_read_b64_tr_b16 v[148:149], v158 offset:0xc00
	v_mfma_f32_32x32x16_bf16 v[48:63], v[132:135], v[150:153], v[48:63]
	ds_read_b64_tr_b16 v[150:151], v158 offset:0x1400
	ds_read_b64_tr_b16 v[152:153], v158 offset:0x1c00
	s_waitcnt lgkmcnt(4)
	s_nop 0
	v_mfma_f32_32x32x16_bf16 v[48:63], v[128:131], v[154:157], v[48:63]
	ds_read_b64_tr_b16 v[154:155], v158 offset:0x2400
	ds_read_b64_tr_b16 v[156:157], v158 offset:0x2c00
	v_mfma_f32_32x32x16_bf16 v[48:63], v[136:139], v[230:233], v[48:63]
	ds_read_b64_tr_b16 v[230:231], v158 offset:0x3400
	ds_read_b64_tr_b16 v[232:233], v158 offset:0x3c00
	s_waitcnt lgkmcnt(4)
	s_nop 0
	v_mfma_f32_32x32x16_bf16 v[32:47], v[140:143], v[146:149], v[32:47]
	ds_read_b64_tr_b16 v[146:147], v158 offset:0x600
	ds_read_b64_tr_b16 v[148:149], v158 offset:0xe00
	v_mfma_f32_32x32x16_bf16 v[32:47], v[132:135], v[150:153], v[32:47]
	ds_read_b64_tr_b16 v[150:151], v158 offset:0x1600
	ds_read_b64_tr_b16 v[152:153], v158 offset:0x1e00
	s_waitcnt lgkmcnt(4)
	s_nop 0
	v_mfma_f32_32x32x16_bf16 v[32:47], v[128:131], v[154:157], v[32:47]
	ds_read_b64_tr_b16 v[154:155], v158 offset:0x2600
	ds_read_b64_tr_b16 v[156:157], v158 offset:0x2e00
	v_mfma_f32_32x32x16_bf16 v[32:47], v[136:139], v[230:233], v[32:47]
	ds_read_b64_tr_b16 v[230:231], v158 offset:0x3600
	ds_read_b64_tr_b16 v[232:233], v158 offset:0x3e00
	s_waitcnt lgkmcnt(4)
	s_nop 0
	s_waitcnt lgkmcnt(0)
	v_mfma_f32_32x32x16_bf16 v[16:31], v[140:143], v[146:149], v[16:31]
	v_mfma_f32_32x32x16_bf16 v[16:31], v[132:135], v[150:153], v[16:31]
	v_mfma_f32_32x32x16_bf16 v[16:31], v[128:131], v[154:157], v[16:31]
	v_mfma_f32_32x32x16_bf16 v[16:31], v[136:139], v[230:233], v[16:31]
	s_cbranch_scc1 .LBB0_307
	s_mov_b32 s12, s62
	s_mov_b32 s13, s95
	v_mov_b32_e32 v229, v144
	s_branch .LBB0_286

; #define ALAS __attribute__((address_space(3)))
; __device__ __forceinline__ void qkt(f32x16& p0, f32x16& p1, const ALAS char* Ks, const bf16x8* qr, int r32, int hi) {
;   p0 = f32x16{}; p1 = f32x16{};
; #pragma unroll
;   for (int d0 = 0; d0 < 8; ++d0) { int cb = (d0 * 16 + hi * 8) * 2;
;     bf16x8 b0 = *(const ALAS bf16x8*)(Ks + KSWZ(r32, cb));
;     bf16x8 b1 = *(const ALAS bf16x8*)(Ks + KSWZ(32 + r32, cb));
;     p0 = __builtin_amdgcn_mfma_f32_32x32x16_bf16(b0, qr[d0], p0, 0, 0, 0);
;     p1 = __builtin_amdgcn_mfma_f32_32x32x16_bf16(b1, qr[d0], p1, 0, 0, 0); }
; }
; template <int MODE> __device__ __forceinline__ void modify2(f32x16& p0, f32x16& p1, const Mod& M, int j, float& boff) {
;   const float dq = M.a0 - (float)(j * 64); const float nsl = -M.a1;
; #pragma unroll
;   for (int r = 0; r < 16; ++r) { const float cr = (float)((r & 3) + 8 * (r >> 2));
;     p0[r] = fmaf(fabsf(dq - cr), nsl, p0[r]); p1[r] = fmaf(fabsf(dq - (cr + 32.f)), nsl, p1[r]); }
;   boff = 0.f;
.LBB0_349:
	s_and_b32 s45, s12, 1
	v_mov_b32_e32 v128, v215
	v_mov_b32_e32 v129, v214
	s_lshl_b32 s4, s45, 14
	s_add_i32 s4, s4, 0
	s_add_i32 s4, s4, 0x10000
	v_lshlrev_b32_e32 v242, 4, v128
	v_lshlrev_b32_e32 v243, 4, v129
	v_and_b32_e32 v243, 0x70, v243
	v_lshl_add_u32 v241, v129, 8, s4
	v_xad_u32 v244, v242, v243, v241
	v_add_u32_e32 v240, 32, v242
	v_xad_u32 v245, v240, v243, v241
	v_add_u32_e32 v240, 64, v242
	v_xad_u32 v246, v240, v243, v241
	v_add_u32_e32 v240, 0x60, v242
	v_xad_u32 v247, v240, v243, v241
	s_lshl_b32 s4, s16, 6
	ds_read_b128 v[148:151], v244
	ds_read_b128 v[152:155], v245
	ds_read_b128 v[156:159], v246
	ds_read_b128 v[230:233], v247
	ds_read_b128 v[234:237], v244 offset:128
	ds_read_b128 v[238:241], v245 offset:128
	s_waitcnt lgkmcnt(5)
	v_mfma_f32_32x32x16_bf16 v[128:143], v[148:151], v[160:163], 0
	ds_read_b128 v[148:151], v246 offset:128
	s_waitcnt lgkmcnt(5)
	v_mfma_f32_32x32x16_bf16 v[128:143], v[152:155], v[164:167], v[128:143]
	ds_read_b128 v[152:155], v247 offset:128
	s_waitcnt lgkmcnt(5)
	v_mfma_f32_32x32x16_bf16 v[128:143], v[156:159], v[168:171], v[128:143]
	ds_read_b128 v[144:147], v244 offset:8192
	s_waitcnt lgkmcnt(5)
	v_mfma_f32_32x32x16_bf16 v[128:143], v[230:233], v[172:175], v[128:143]
	ds_read_b128 v[230:233], v245 offset:8192
	s_waitcnt lgkmcnt(5)
	v_mfma_f32_32x32x16_bf16 v[128:143], v[234:237], v[176:179], v[128:143]
	ds_read_b128 v[234:237], v246 offset:8192
	s_waitcnt lgkmcnt(5)
	v_mfma_f32_32x32x16_bf16 v[128:143], v[238:241], v[180:183], v[128:143]
	ds_read_b128 v[238:241], v247 offset:8192
	s_waitcnt lgkmcnt(5)
	v_mfma_f32_32x32x16_bf16 v[128:143], v[148:151], v[184:187], v[128:143]
	s_waitcnt lgkmcnt(4)
	v_mfma_f32_32x32x16_bf16 v[128:143], v[152:155], v[188:191], v[128:143]
	s_waitcnt lgkmcnt(3)
	v_mfma_f32_32x32x16_bf16 v[144:159], v[144:147], v[160:163], 0
	s_waitcnt lgkmcnt(2)
	v_mfma_f32_32x32x16_bf16 v[144:159], v[230:233], v[164:167], v[144:159]
	ds_read_b128 v[230:233], v244 offset:8320
	s_waitcnt lgkmcnt(2)
	v_mfma_f32_32x32x16_bf16 v[144:159], v[234:237], v[168:171], v[144:159]
	ds_read_b128 v[234:237], v245 offset:8320
	s_waitcnt lgkmcnt(2)
	v_mfma_f32_32x32x16_bf16 v[144:159], v[238:241], v[172:175], v[144:159]
	ds_read_b128 v[238:241], v246 offset:8320
	s_waitcnt lgkmcnt(2)
	v_mfma_f32_32x32x16_bf16 v[144:159], v[230:233], v[176:179], v[144:159]
	ds_read_b128 v[230:233], v247 offset:8320
	s_waitcnt lgkmcnt(2)
	v_mfma_f32_32x32x16_bf16 v[144:159], v[234:237], v[180:183], v[144:159]
	s_waitcnt lgkmcnt(1)
	v_mfma_f32_32x32x16_bf16 v[144:159], v[238:241], v[184:187], v[144:159]
	s_waitcnt lgkmcnt(0)
	v_mfma_f32_32x32x16_bf16 v[144:159], v[230:233], v[188:191], v[144:159]
	v_cvt_f32_i32_e32 v230, s4
	v_mov_b32_e32 v231, v212
	s_nop 0
	v_sub_f32_e32 v247, v231, v230
	v_fma_f32 v231, |v247|, v213, v128
	v_add_f32_e32 v128, -1.0, v247
	v_fma_f32 v232, |v128|, v213, v129
	v_add_f32_e32 v128, -2.0, v247
	v_fma_f32 v233, |v128|, v213, v130
	v_add_f32_e32 v128, 0xc0400000, v247
	v_fma_f32 v234, |v128|, v213, v131
	v_add_f32_e32 v128, 0xc1000000, v247
	v_fma_f32 v235, |v128|, v213, v132
	v_add_f32_e32 v128, 0xc1100000, v247
	v_fma_f32 v236, |v128|, v213, v133
	v_add_f32_e32 v128, 0xc1200000, v247
	v_fma_f32 v237, |v128|, v213, v134
	v_add_f32_e32 v128, 0xc1300000, v247
	v_fma_f32 v238, |v128|, v213, v135
	v_add_f32_e32 v128, 0xc1800000, v247
	v_fma_f32 v239, |v128|, v213, v136
	v_add_f32_e32 v128, 0xc1880000, v247
	v_fma_f32 v240, |v128|, v213, v137
	v_add_f32_e32 v128, 0xc1900000, v247
	v_fma_f32 v241, |v128|, v213, v138
	v_add_f32_e32 v128, 0xc1980000, v247
	v_fma_f32 v242, |v128|, v213, v139
	v_add_f32_e32 v128, 0xc1c00000, v247
	v_fma_f32 v243, |v128|, v213, v140
	v_add_f32_e32 v128, 0xc1c80000, v247
	v_fma_f32 v244, |v128|, v213, v141
	v_add_f32_e32 v128, 0xc1d00000, v247
	v_fma_f32 v245, |v128|, v213, v142
	v_add_f32_e32 v128, 0xc1d80000, v247
	v_fma_f32 v246, |v128|, v213, v143
	v_add_f32_e32 v128, 0xc2000000, v247
	v_fma_f32 v144, |v128|, v213, v144
	v_add_f32_e32 v128, 0xc2040000, v247
	v_fma_f32 v230, |v128|, v213, v145
	v_add_f32_e32 v128, 0xc2080000, v247
	v_fma_f32 v146, |v128|, v213, v146
	v_add_f32_e32 v128, 0xc20c0000, v247
	v_fma_f32 v147, |v128|, v213, v147
	v_add_f32_e32 v128, 0xc2200000, v247
	v_fma_f32 v148, |v128|, v213, v148
	v_add_f32_e32 v128, 0xc2240000, v247
	v_fma_f32 v149, |v128|, v213, v149
	v_add_f32_e32 v128, 0xc2280000, v247
	v_fma_f32 v150, |v128|, v213, v150
	v_add_f32_e32 v128, 0xc22c0000, v247
	v_fma_f32 v151, |v128|, v213, v151
	v_add_f32_e32 v128, 0xc2400000, v247
	v_fma_f32 v152, |v128|, v213, v152
	v_add_f32_e32 v128, 0xc2440000, v247
	v_fma_f32 v153, |v128|, v213, v153
	v_add_f32_e32 v128, 0xc2480000, v247
	v_fma_f32 v154, |v128|, v213, v154
	v_add_f32_e32 v128, 0xc24c0000, v247
	v_fma_f32 v155, |v128|, v213, v155
	v_add_f32_e32 v128, 0xc2600000, v247
	v_fma_f32 v156, |v128|, v213, v156
	v_add_f32_e32 v128, 0xc2640000, v247
	v_fma_f32 v157, |v128|, v213, v157
	v_add_f32_e32 v128, 0xc2680000, v247
	v_fma_f32 v158, |v128|, v213, v158
	v_add_f32_e32 v128, 0xc26c0000, v247
	v_fma_f32 v159, |v128|, v213, v159
	v_max_f32_e32 v128, v231, v232
	v_max3_f32 v128, v128, v233, v234
	v_max3_f32 v128, v128, v235, v236
	v_max3_f32 v128, v128, v237, v238
	v_max3_f32 v128, v128, v239, v240
	v_max3_f32 v128, v128, v241, v242
	v_max3_f32 v128, v128, v243, v244
	v_max3_f32 v128, v128, v245, v246
	v_max3_f32 v128, v128, v144, v230
	v_max3_f32 v128, v128, v146, v147
	v_max3_f32 v128, v128, v148, v149
	v_max3_f32 v128, v128, v150, v151
	v_max3_f32 v128, v128, v152, v153
	v_max3_f32 v128, v128, v154, v155
	v_max3_f32 v128, v128, v156, v157
	v_max3_f32 v128, v128, v158, v159
	v_mov_b32_e32 v129, v128
	s_nop 1
	v_permlane32_swap_b32_e32 v128, v129
	v_max_f32_e32 v129, v129, v129
	v_max_f32_e32 v128, v128, v128
	v_max_f32_e32 v128, v128, v129
	v_max_f32_e32 v130, v228, v228
	v_max_f32_e32 v247, v130, v128
	v_sub_f32_e32 v129, v128, v228
	v_sub_f32_e32 v128, v228, v247
	v_mul_f32_e32 v128, 0x3e0293ee, v128
	v_exp_f32_e32 v128, v128
	v_cmp_ge_f32_e32 vcc, s87, v129
	s_cmp_eq_u64 vcc, exec
	s_cselect_b64 s[4:5], -1, 0
	v_cndmask_b32_e64 v145, v128, 1.0, s[4:5]
	s_cbranch_scc1 .LBB0_353
; __device__ __forceinline__ int crow(int r, int hi) { return (r & 3) + 8 * (r >> 2) + 4 * hi; }
; template <bool OFF>
; __device__ __forceinline__ void partialSM(f32x16& p0, f32x16& p1, float& m_reg, float& mn, float& alpha, float boff) {
;     ...
;   const float mnC = (OFF ? boff - mn : -mn) * C;
; #pragma unroll
;   for (int r = 0; r < 16; ++r) p0[r] = fmaf(p0[r], C, mnC);
; #pragma unroll
;   for (int r = 0; r < 16; ++r) p1[r] = fmaf(p1[r], C, mnC);
; #pragma unroll
;   for (int r = 0; r < 16; ++r) p0[r] = __builtin_amdgcn_exp2f(p0[r]);
; }
; __device__ __forceinline__ void finishSM(f32x16& p0, f32x16& p1, float alpha, float& l_reg, bf16x8& pa0, bf16x8& pa1, bf16x8& pa2, bf16x8& pa3) {
; #pragma unroll
;   for (int r = 0; r < 16; ++r) p1[r] = __builtin_amdgcn_exp2f(p1[r]);
; __device__ __forceinline__ void b3_map(f32x16 (&o0)[4], f32x16 (&o1)[4], const AGAS bf16* __restrict__ Qb, const AGAS bf16* __restrict__ Kh, const AGAS bf16* __restrict__ V0h, const AGAS bf16* __restrict__ V1h, int NT, Mod M, ALAS char* lds) {
;     ...
;     if (__any(alpha < 1.f)) { if (hi == 0) al_l[r32] = alpha; asm volatile("s_waitcnt lgkmcnt(0)" ::: "memory");
; #pragma unroll
;       for (int r = 0; r < 16; ++r) { const float al = al_l[crow(r, hi)];
; #pragma unroll
;         for (int d = 0; d < 4; ++d) { o0[d][r] *= al; o1[d][r] *= al; } } }
	s_and_saveexec_b64 s[16:17], s[6:7]
	ds_write_b32 v218, v145 offset:128
	s_or_b64 exec, exec, s[16:17]
	s_waitcnt lgkmcnt(0)
	v_add_u32_e32 v128, s78, v196
	ds_read_b128 v[140:143], v128 offset:224
	ds_read_b128 v[136:139], v128 offset:192
	ds_read_b128 v[132:135], v128 offset:160
	ds_read_b128 v[128:131], v128 offset:128
	s_waitcnt lgkmcnt(0)
	v_pk_mul_f32 v[124:125], v[124:125], v[140:141]
	v_pk_mul_f32 v[120:121], v[120:121], v[136:137]
	v_pk_mul_f32 v[116:117], v[116:117], v[132:133]
	v_pk_mul_f32 v[126:127], v[126:127], v[142:143]
	v_pk_mul_f32 v[122:123], v[122:123], v[138:139]
	v_pk_mul_f32 v[118:119], v[118:119], v[134:135]
	v_pk_mul_f32 v[114:115], v[114:115], v[130:131]
	v_pk_mul_f32 v[112:113], v[112:113], v[128:129]
	v_pk_mul_f32 v[108:109], v[108:109], v[140:141]
	v_pk_mul_f32 v[104:105], v[104:105], v[136:137]
	v_pk_mul_f32 v[100:101], v[100:101], v[132:133]
	v_pk_mul_f32 v[110:111], v[110:111], v[142:143]
	v_pk_mul_f32 v[106:107], v[106:107], v[138:139]
	v_pk_mul_f32 v[102:103], v[102:103], v[134:135]
	v_pk_mul_f32 v[98:99], v[98:99], v[130:131]
	v_pk_mul_f32 v[96:97], v[96:97], v[128:129]
	v_pk_mul_f32 v[92:93], v[92:93], v[140:141]
	v_pk_mul_f32 v[88:89], v[88:89], v[136:137]
	v_pk_mul_f32 v[84:85], v[84:85], v[132:133]
	v_pk_mul_f32 v[94:95], v[94:95], v[142:143]
	v_pk_mul_f32 v[90:91], v[90:91], v[138:139]
	v_pk_mul_f32 v[86:87], v[86:87], v[134:135]
	v_pk_mul_f32 v[82:83], v[82:83], v[130:131]
	v_pk_mul_f32 v[80:81], v[80:81], v[128:129]
	v_pk_mul_f32 v[44:45], v[44:45], v[140:141]
	v_pk_mul_f32 v[40:41], v[40:41], v[136:137]
	v_pk_mul_f32 v[36:37], v[36:37], v[132:133]
	v_pk_mul_f32 v[46:47], v[46:47], v[142:143]
	v_pk_mul_f32 v[42:43], v[42:43], v[138:139]
	v_pk_mul_f32 v[38:39], v[38:39], v[134:135]
	v_pk_mul_f32 v[34:35], v[34:35], v[130:131]
	v_pk_mul_f32 v[32:33], v[32:33], v[128:129]
	v_pk_mul_f32 v[76:77], v[76:77], v[140:141]
	v_pk_mul_f32 v[72:73], v[72:73], v[136:137]
	v_pk_mul_f32 v[68:69], v[68:69], v[132:133]
	v_pk_mul_f32 v[78:79], v[78:79], v[142:143]
	v_pk_mul_f32 v[74:75], v[74:75], v[138:139]
	v_pk_mul_f32 v[70:71], v[70:71], v[134:135]
	v_pk_mul_f32 v[66:67], v[66:67], v[130:131]
	v_pk_mul_f32 v[64:65], v[64:65], v[128:129]
	v_pk_mul_f32 v[28:29], v[28:29], v[140:141]
	v_pk_mul_f32 v[24:25], v[24:25], v[136:137]
	v_pk_mul_f32 v[20:21], v[20:21], v[132:133]
	v_pk_mul_f32 v[30:31], v[30:31], v[142:143]
	v_pk_mul_f32 v[26:27], v[26:27], v[138:139]
	v_pk_mul_f32 v[22:23], v[22:23], v[134:135]
	v_pk_mul_f32 v[18:19], v[18:19], v[130:131]
	v_pk_mul_f32 v[16:17], v[16:17], v[128:129]
	v_pk_mul_f32 v[60:61], v[60:61], v[140:141]
	v_pk_mul_f32 v[56:57], v[56:57], v[136:137]
	v_pk_mul_f32 v[52:53], v[52:53], v[132:133]
	v_pk_mul_f32 v[62:63], v[62:63], v[142:143]
	v_pk_mul_f32 v[58:59], v[58:59], v[138:139]
	v_pk_mul_f32 v[54:55], v[54:55], v[134:135]
	v_pk_mul_f32 v[50:51], v[50:51], v[130:131]
	v_pk_mul_f32 v[48:49], v[48:49], v[128:129]
	v_pk_mul_f32 v[12:13], v[12:13], v[140:141]
	v_pk_mul_f32 v[8:9], v[8:9], v[136:137]
	v_pk_mul_f32 v[4:5], v[4:5], v[132:133]
	v_pk_mul_f32 v[14:15], v[14:15], v[142:143]
	v_pk_mul_f32 v[10:11], v[10:11], v[138:139]
	v_pk_mul_f32 v[6:7], v[6:7], v[134:135]
	v_pk_mul_f32 v[2:3], v[2:3], v[130:131]
	v_pk_mul_f32 v[0:1], v[0:1], v[128:129]
.LBB0_353:
	v_cndmask_b32_e64 v228, v247, v228, s[4:5]
	v_mul_f32_e32 v128, 0xbe0293ee, v228
	v_fmamk_f32 v129, v231, 0x3e0293ee, v128
	v_fmamk_f32 v130, v232, 0x3e0293ee, v128
	v_exp_f32_e32 v129, v129
	v_fmamk_f32 v131, v233, 0x3e0293ee, v128
	v_exp_f32_e32 v130, v130
	v_fmamk_f32 v132, v234, 0x3e0293ee, v128
	v_exp_f32_e32 v131, v131
	v_fmamk_f32 v133, v235, 0x3e0293ee, v128
	v_fmamk_f32 v134, v236, 0x3e0293ee, v128
	v_fmamk_f32 v135, v237, 0x3e0293ee, v128
	v_fmamk_f32 v136, v238, 0x3e0293ee, v128
	v_fmamk_f32 v137, v239, 0x3e0293ee, v128
	v_fmamk_f32 v138, v240, 0x3e0293ee, v128
	v_fmamk_f32 v139, v241, 0x3e0293ee, v128
	v_fmamk_f32 v140, v242, 0x3e0293ee, v128
	v_fmamk_f32 v141, v243, 0x3e0293ee, v128
	v_fmamk_f32 v142, v244, 0x3e0293ee, v128
	v_fmamk_f32 v143, v245, 0x3e0293ee, v128
	v_fmamk_f32 v231, v246, 0x3e0293ee, v128
	v_fmamk_f32 v144, v144, 0x3e0293ee, v128
	v_fmamk_f32 v230, v230, 0x3e0293ee, v128
	v_fmamk_f32 v146, v146, 0x3e0293ee, v128
	v_fmamk_f32 v147, v147, 0x3e0293ee, v128
	v_fmamk_f32 v148, v148, 0x3e0293ee, v128
	v_fmamk_f32 v149, v149, 0x3e0293ee, v128
	v_fmamk_f32 v150, v150, 0x3e0293ee, v128
	v_fmamk_f32 v151, v151, 0x3e0293ee, v128
	v_fmamk_f32 v152, v152, 0x3e0293ee, v128
	v_fmamk_f32 v153, v153, 0x3e0293ee, v128
	v_fmamk_f32 v154, v154, 0x3e0293ee, v128
	v_fmamk_f32 v155, v155, 0x3e0293ee, v128
	v_fmamk_f32 v156, v156, 0x3e0293ee, v128
	v_fmamk_f32 v157, v157, 0x3e0293ee, v128
	v_fmamk_f32 v158, v158, 0x3e0293ee, v128
	v_fmac_f32_e32 v128, 0x3e0293ee, v159
	v_exp_f32_e32 v132, v132
	v_exp_f32_e32 v133, v133
	v_exp_f32_e32 v236, v128
	v_add_f32_e32 v128, 0, v129
	v_exp_f32_e32 v134, v134
	v_add_f32_e32 v128, v130, v128
	v_exp_f32_e32 v135, v135
	v_add_f32_e32 v128, v131, v128
	v_exp_f32_e32 v136, v136
	v_add_f32_e32 v128, v132, v128
	v_exp_f32_e32 v137, v137
	v_add_f32_e32 v128, v133, v128
	v_exp_f32_e32 v138, v138
	v_add_f32_e32 v128, v134, v128
	v_exp_f32_e32 v139, v139
	v_add_f32_e32 v128, v135, v128
	v_exp_f32_e32 v159, v140
	v_add_f32_e32 v128, v136, v128
	v_exp_f32_e32 v232, v141
	v_add_f32_e32 v128, v137, v128
	v_exp_f32_e32 v233, v142
	v_add_f32_e32 v128, v138, v128
	v_exp_f32_e32 v234, v143
	v_add_f32_e32 v128, v139, v128
	v_exp_f32_e32 v231, v231
	v_add_f32_e32 v128, v159, v128
	v_exp_f32_e32 v235, v144
	v_add_f32_e32 v128, v232, v128
	v_exp_f32_e32 v230, v230
	v_add_f32_e32 v128, v233, v128
; __device__ __forceinline__ void finishSM(f32x16& p0, f32x16& p1, float alpha, float& l_reg, bf16x8& pa0, bf16x8& pa1, bf16x8& pa2, bf16x8& pa3) {
; #pragma unroll
;   for (int r = 0; r < 16; ++r) p1[r] = __builtin_amdgcn_exp2f(p1[r]);
;   float ps = 0;
; #pragma unroll
;   for (int r = 0; r < 16; ++r) ps += p0[r];
; #pragma unroll
;   for (int r = 0; r < 16; ++r) ps += p1[r];
;   { auto rr = __builtin_amdgcn_permlane32_swap(__float_as_uint(ps), __float_as_uint(ps), false, false);
;     ps = __uint_as_float(rr[0]) + __uint_as_float(rr[1]); }
;   l_reg = l_reg * alpha + ps;
;     ...
;   PK4(p0, 0, pa0); PK4(p0, 8, pa1); PK4(p1, 0, pa2); PK4(p1, 8, pa3);
	v_exp_f32_e32 v146, v146
	v_add_f32_e32 v128, v234, v128
	v_exp_f32_e32 v147, v147
	v_add_f32_e32 v128, v231, v128
	v_exp_f32_e32 v148, v148
	v_add_f32_e32 v128, v235, v128
	v_exp_f32_e32 v149, v149
	v_add_f32_e32 v128, v230, v128
	v_exp_f32_e32 v150, v150
	v_add_f32_e32 v128, v146, v128
	v_exp_f32_e32 v151, v151
	v_add_f32_e32 v128, v147, v128
	v_exp_f32_e32 v152, v152
	v_add_f32_e32 v128, v148, v128
	v_exp_f32_e32 v153, v153
	v_add_f32_e32 v128, v149, v128
	v_exp_f32_e32 v154, v154
	v_add_f32_e32 v128, v150, v128
	v_exp_f32_e32 v155, v155
	v_add_f32_e32 v128, v151, v128
	v_exp_f32_e32 v156, v156
	v_add_f32_e32 v128, v152, v128
	v_exp_f32_e32 v157, v157
	v_add_f32_e32 v128, v153, v128
	v_exp_f32_e32 v158, v158
	v_add_f32_e32 v128, v154, v128
	v_add_f32_e32 v128, v155, v128
	v_add_f32_e32 v128, v156, v128
	v_add_f32_e32 v128, v157, v128
	s_sub_i32 s94, s94, s46
	s_xor_b64 s[4:5], s[46:47], -1
	v_add_f32_e32 v128, v158, v128
	v_add_f32_e32 v128, v236, v128
	v_mov_b32_e32 v140, v128
	s_nop 1
	v_permlane32_swap_b32_e32 v128, v140
	v_add_f32_e32 v144, v128, v140
	v_cvt_pk_bf16_f32 v140, v129, v130
	v_cvt_pk_bf16_f32 v141, v131, v132
	v_cvt_pk_bf16_f32 v142, v133, v134
	v_cvt_pk_bf16_f32 v143, v135, v136
	v_cvt_pk_bf16_f32 v132, v137, v138
	v_cvt_pk_bf16_f32 v133, v139, v159
	v_cvt_pk_bf16_f32 v134, v232, v233
	v_cvt_pk_bf16_f32 v135, v234, v231
	v_cvt_pk_bf16_f32 v128, v235, v230
	v_cvt_pk_bf16_f32 v129, v146, v147
	v_cvt_pk_bf16_f32 v130, v148, v149
	v_cvt_pk_bf16_f32 v131, v150, v151
	v_cvt_pk_bf16_f32 v136, v152, v153
	v_cvt_pk_bf16_f32 v137, v154, v155
	v_cvt_pk_bf16_f32 v138, v156, v157
	v_cvt_pk_bf16_f32 v139, v158, v236
	s_waitcnt lgkmcnt(0)
	v_fmac_f32_e32 v144, v229, v145
	v_lshl_add_u32 v145, s45, 15, v227
	ds_read_b64_tr_b16 v[146:147], v145 offset:0
	ds_read_b64_tr_b16 v[148:149], v145 offset:0x800
	ds_read_b64_tr_b16 v[150:151], v145 offset:0x1000
	v_permlane32_swap_b32_e32 v140, v142
	v_permlane32_swap_b32_e32 v141, v143
	ds_read_b64_tr_b16 v[152:153], v145 offset:0x1800
	ds_read_b64_tr_b16 v[154:155], v145 offset:0x2000
	ds_read_b64_tr_b16 v[156:157], v145 offset:0x2800
	ds_read_b64_tr_b16 v[230:231], v145 offset:0x3000
	ds_read_b64_tr_b16 v[232:233], v145 offset:0x3800
	v_permlane32_swap_b32_e32 v132, v134
	s_waitcnt lgkmcnt(4)
	v_permlane32_swap_b32_e32 v133, v135
	v_mfma_f32_32x32x16_bf16 v[112:127], v[140:143], v[146:149], v[112:127]
	v_permlane32_swap_b32_e32 v128, v130
	v_permlane32_swap_b32_e32 v129, v131
	ds_read_b64_tr_b16 v[146:147], v145 offset:0x200
	ds_read_b64_tr_b16 v[148:149], v145 offset:0xa00
	v_permlane32_swap_b32_e32 v136, v138
	v_mfma_f32_32x32x16_bf16 v[112:127], v[132:135], v[150:153], v[112:127]
	ds_read_b64_tr_b16 v[150:151], v145 offset:0x1200
	ds_read_b64_tr_b16 v[152:153], v145 offset:0x1a00
	s_waitcnt lgkmcnt(4)
	v_permlane32_swap_b32_e32 v137, v139
	v_add_u32_e32 v158, 0x4000, v145
	s_add_i32 s11, s11, s4
	v_mfma_f32_32x32x16_bf16 v[112:127], v[128:131], v[154:157], v[112:127]
	ds_read_b64_tr_b16 v[154:155], v145 offset:0x2200
	ds_read_b64_tr_b16 v[156:157], v145 offset:0x2a00
	s_xor_b64 s[40:41], s[40:41], -1
	s_cmp_eq_u32 s42, 64
	v_mfma_f32_32x32x16_bf16 v[112:127], v[136:139], v[230:233], v[112:127]
	ds_read_b64_tr_b16 v[230:231], v145 offset:0x3200
	ds_read_b64_tr_b16 v[232:233], v145 offset:0x3a00
	s_waitcnt lgkmcnt(4)
	s_nop 0
	v_mfma_f32_32x32x16_bf16 v[80:95], v[140:143], v[146:149], v[80:95]
	ds_read_b64_tr_b16 v[146:147], v145 offset:0x400
	ds_read_b64_tr_b16 v[148:149], v145 offset:0xc00
	v_mfma_f32_32x32x16_bf16 v[80:95], v[132:135], v[150:153], v[80:95]
	ds_read_b64_tr_b16 v[150:151], v145 offset:0x1400
	ds_read_b64_tr_b16 v[152:153], v145 offset:0x1c00
	s_waitcnt lgkmcnt(4)
	s_nop 0
	v_mfma_f32_32x32x16_bf16 v[80:95], v[128:131], v[154:157], v[80:95]
	ds_read_b64_tr_b16 v[154:155], v145 offset:0x2400
	ds_read_b64_tr_b16 v[156:157], v145 offset:0x2c00
	v_mfma_f32_32x32x16_bf16 v[80:95], v[136:139], v[230:233], v[80:95]
	ds_read_b64_tr_b16 v[230:231], v145 offset:0x3400
	ds_read_b64_tr_b16 v[232:233], v145 offset:0x3c00
	s_waitcnt lgkmcnt(4)
; #define PVR(S, VB, D0, K0) do { S##l0 = tr_read<v_rd_off(D0, K0, 0)>(VB); S##h0 = tr_read<v_rd_off(D0, K0, 1)>(VB); S##l1 = tr_read<v_rd_off(D0, (K0) + 1, 0)>(VB); S##h1 = tr_read<v_rd_off(D0, (K0) + 1, 1)>(VB); } while (0)
; #define PVW(S, N) asm volatile("s_waitcnt lgkmcnt(" #N ")" : "+v"(S##l0), "+v"(S##h0), "+v"(S##l1), "+v"(S##h1) :: "memory")
; #define PVM(O, S, PA, PB) do { O = __builtin_amdgcn_mfma_f32_32x32x16_bf16(PA, PVK(S##l0, S##h0), O, 0, 0, 0); O = __builtin_amdgcn_mfma_f32_32x32x16_bf16(PB, PVK(S##l1, S##h1), O, 0, 0, 0); } while (0)
; __device__ __forceinline__ void pv_256(f32x16* o0, f32x16* o1, int v0, int v1, bf16x8 pa0, bf16x8 pa1, bf16x8 pa2, bf16x8 pa3) {
;   s16x4 Al0, Ah0, Al1, Ah1, Bl0, Bh0, Bl1, Bh1;
;   PVR(A, v0, 0, 0); PVR(B, v0, 0, 2);
;   PVW(A, 4); PVM(o0[0], A, pa0, pa1); PVR(A, v0, 1, 0);
;   PVW(B, 4); PVM(o0[0], B, pa2, pa3); PVR(B, v0, 1, 2);
;   PVW(A, 4); PVM(o0[1], A, pa0, pa1); PVR(A, v0, 2, 0);
;   PVW(B, 4); PVM(o0[1], B, pa2, pa3); PVR(B, v0, 2, 2);
;   PVW(A, 4); PVM(o0[2], A, pa0, pa1); PVR(A, v0, 3, 0);
;   PVW(B, 4); PVM(o0[2], B, pa2, pa3); PVR(B, v0, 3, 2);
;   PVW(A, 4); PVM(o0[3], A, pa0, pa1); PVR(A, v1, 0, 0);
;   PVW(B, 4); PVM(o0[3], B, pa2, pa3); PVR(B, v1, 0, 2);
;   PVW(A, 4); PVM(o1[0], A, pa0, pa1); PVR(A, v1, 1, 0);
;   PVW(B, 4); PVM(o1[0], B, pa2, pa3); PVR(B, v1, 1, 2);
;   PVW(A, 4); PVM(o1[1], A, pa0, pa1); PVR(A, v1, 2, 0);
;   PVW(B, 4); PVM(o1[1], B, pa2, pa3); PVR(B, v1, 2, 2);
;   PVW(A, 4); PVM(o1[2], A, pa0, pa1); PVR(A, v1, 3, 0);
;   PVW(B, 4); PVM(o1[2], B, pa2, pa3); PVR(B, v1, 3, 2);
;   PVW(A, 4); PVM(o1[3], A, pa0, pa1);
;   PVW(B, 0); PVM(o1[3], B, pa2, pa3);
; }
	s_nop 0
	v_mfma_f32_32x32x16_bf16 v[64:79], v[140:143], v[146:149], v[64:79]
	ds_read_b64_tr_b16 v[146:147], v145 offset:0x600
	ds_read_b64_tr_b16 v[148:149], v145 offset:0xe00
	v_mfma_f32_32x32x16_bf16 v[64:79], v[132:135], v[150:153], v[64:79]
	ds_read_b64_tr_b16 v[150:151], v145 offset:0x1600
	ds_read_b64_tr_b16 v[152:153], v145 offset:0x1e00
	s_waitcnt lgkmcnt(4)
	s_nop 0
	v_mfma_f32_32x32x16_bf16 v[64:79], v[128:131], v[154:157], v[64:79]
	ds_read_b64_tr_b16 v[154:155], v145 offset:0x2600
	ds_read_b64_tr_b16 v[156:157], v145 offset:0x2e00
	v_mfma_f32_32x32x16_bf16 v[64:79], v[136:139], v[230:233], v[64:79]
	ds_read_b64_tr_b16 v[230:231], v145 offset:0x3600
	ds_read_b64_tr_b16 v[232:233], v145 offset:0x3e00
	s_waitcnt lgkmcnt(4)
	s_nop 0
	v_mfma_f32_32x32x16_bf16 v[48:63], v[140:143], v[146:149], v[48:63]
	ds_read_b64_tr_b16 v[146:147], v158 offset:0
	ds_read_b64_tr_b16 v[148:149], v158 offset:0x800
	v_mfma_f32_32x32x16_bf16 v[48:63], v[132:135], v[150:153], v[48:63]
	ds_read_b64_tr_b16 v[150:151], v158 offset:0x1000
	ds_read_b64_tr_b16 v[152:153], v158 offset:0x1800
	s_waitcnt lgkmcnt(4)
	s_nop 0
	v_mfma_f32_32x32x16_bf16 v[48:63], v[128:131], v[154:157], v[48:63]
	ds_read_b64_tr_b16 v[154:155], v158 offset:0x2000
	ds_read_b64_tr_b16 v[156:157], v158 offset:0x2800
	v_mfma_f32_32x32x16_bf16 v[48:63], v[136:139], v[230:233], v[48:63]
	ds_read_b64_tr_b16 v[230:231], v158 offset:0x3000
	ds_read_b64_tr_b16 v[232:233], v158 offset:0x3800
	s_waitcnt lgkmcnt(4)
	s_nop 0
	v_mfma_f32_32x32x16_bf16 v[96:111], v[140:143], v[146:149], v[96:111]
	ds_read_b64_tr_b16 v[146:147], v158 offset:0x200
	ds_read_b64_tr_b16 v[148:149], v158 offset:0xa00
	v_mfma_f32_32x32x16_bf16 v[96:111], v[132:135], v[150:153], v[96:111]
	ds_read_b64_tr_b16 v[150:151], v158 offset:0x1200
	ds_read_b64_tr_b16 v[152:153], v158 offset:0x1a00
	s_waitcnt lgkmcnt(4)
	s_nop 0
	v_mfma_f32_32x32x16_bf16 v[96:111], v[128:131], v[154:157], v[96:111]
	ds_read_b64_tr_b16 v[154:155], v158 offset:0x2200
	ds_read_b64_tr_b16 v[156:157], v158 offset:0x2a00
	v_mfma_f32_32x32x16_bf16 v[96:111], v[136:139], v[230:233], v[96:111]
	ds_read_b64_tr_b16 v[230:231], v158 offset:0x3200
	ds_read_b64_tr_b16 v[232:233], v158 offset:0x3a00
	s_waitcnt lgkmcnt(4)
	s_nop 0
	v_mfma_f32_32x32x16_bf16 v[32:47], v[140:143], v[146:149], v[32:47]
	ds_read_b64_tr_b16 v[146:147], v158 offset:0x400
	ds_read_b64_tr_b16 v[148:149], v158 offset:0xc00
	v_mfma_f32_32x32x16_bf16 v[32:47], v[132:135], v[150:153], v[32:47]
	ds_read_b64_tr_b16 v[150:151], v158 offset:0x1400
	ds_read_b64_tr_b16 v[152:153], v158 offset:0x1c00
	s_waitcnt lgkmcnt(4)
	s_nop 0
	v_mfma_f32_32x32x16_bf16 v[32:47], v[128:131], v[154:157], v[32:47]
	ds_read_b64_tr_b16 v[154:155], v158 offset:0x2400
	ds_read_b64_tr_b16 v[156:157], v158 offset:0x2c00
	v_mfma_f32_32x32x16_bf16 v[32:47], v[136:139], v[230:233], v[32:47]
	ds_read_b64_tr_b16 v[230:231], v158 offset:0x3400
	ds_read_b64_tr_b16 v[232:233], v158 offset:0x3c00
	s_waitcnt lgkmcnt(4)
	s_nop 0
	v_mfma_f32_32x32x16_bf16 v[16:31], v[140:143], v[146:149], v[16:31]
	ds_read_b64_tr_b16 v[146:147], v158 offset:0x600
	ds_read_b64_tr_b16 v[148:149], v158 offset:0xe00
	v_mfma_f32_32x32x16_bf16 v[16:31], v[132:135], v[150:153], v[16:31]
	ds_read_b64_tr_b16 v[150:151], v158 offset:0x1600
	ds_read_b64_tr_b16 v[152:153], v158 offset:0x1e00
	s_waitcnt lgkmcnt(4)
	s_nop 0
	v_mfma_f32_32x32x16_bf16 v[16:31], v[128:131], v[154:157], v[16:31]
	ds_read_b64_tr_b16 v[154:155], v158 offset:0x2600
	ds_read_b64_tr_b16 v[156:157], v158 offset:0x2e00
	v_mfma_f32_32x32x16_bf16 v[16:31], v[136:139], v[230:233], v[16:31]
	ds_read_b64_tr_b16 v[230:231], v158 offset:0x3600
	ds_read_b64_tr_b16 v[232:233], v158 offset:0x3e00
	s_waitcnt lgkmcnt(4)
	s_nop 0
	s_waitcnt lgkmcnt(0)
	v_mfma_f32_32x32x16_bf16 v[0:15], v[140:143], v[146:149], v[0:15]
	v_mfma_f32_32x32x16_bf16 v[0:15], v[132:135], v[150:153], v[0:15]
	v_mfma_f32_32x32x16_bf16 v[0:15], v[128:131], v[154:157], v[0:15]
	v_mfma_f32_32x32x16_bf16 v[0:15], v[136:139], v[230:233], v[0:15]
	s_cbranch_scc1 .LBB0_355
	s_mov_b32 s16, s44
	s_mov_b32 s12, s42
	v_mov_b32_e32 v229, v144
	s_branch .LBB0_334

; #define ALAS __attribute__((address_space(3)))
; __device__ __forceinline__ void qkt(f32x16& p0, f32x16& p1, const ALAS char* Ks, const bf16x8* qr, int r32, int hi) {
;   p0 = f32x16{}; p1 = f32x16{};
; #pragma unroll
;   for (int d0 = 0; d0 < 8; ++d0) { int cb = (d0 * 16 + hi * 8) * 2;
;     bf16x8 b0 = *(const ALAS bf16x8*)(Ks + KSWZ(r32, cb));
;     bf16x8 b1 = *(const ALAS bf16x8*)(Ks + KSWZ(32 + r32, cb));
;     p0 = __builtin_amdgcn_mfma_f32_32x32x16_bf16(b0, qr[d0], p0, 0, 0, 0);
;     p1 = __builtin_amdgcn_mfma_f32_32x32x16_bf16(b1, qr[d0], p1, 0, 0, 0); }
; }
; template <int MODE> __device__ __forceinline__ void modify2(f32x16& p0, f32x16& p1, const Mod& M, int j, float& boff) {
;   const float dq = M.a0 - (float)(j * 64); const float nsl = -M.a1;
; #pragma unroll
;   for (int r = 0; r < 16; ++r) { const float cr = (float)((r & 3) + 8 * (r >> 2));
;     p0[r] = fmaf(fabsf(dq - cr), nsl, p0[r]); p1[r] = fmaf(fabsf(dq - (cr + 32.f)), nsl, p1[r]); }
;   boff = 0.f;
.LBB0_957:
	s_and_b32 s77, s94, 1
	v_mov_b32_e32 v128, v214
	v_mov_b32_e32 v129, v215
	s_lshl_b32 s8, s77, 14
	s_add_i32 s8, s8, 0
	s_add_i32 s8, s8, 0x10000
	v_lshlrev_b32_e32 v242, 4, v129
	v_lshlrev_b32_e32 v243, 4, v128
	v_and_b32_e32 v243, 0x70, v243
	v_lshl_add_u32 v241, v128, 8, s8
	v_xad_u32 v244, v242, v243, v241
	v_add_u32_e32 v240, 32, v242
	v_xad_u32 v245, v240, v243, v241
	v_add_u32_e32 v240, 64, v242
	v_xad_u32 v246, v240, v243, v241
	v_add_u32_e32 v240, 0x60, v242
	v_xad_u32 v247, v240, v243, v241
	s_lshl_b32 s8, s95, 6
	ds_read_b128 v[148:151], v244
	ds_read_b128 v[152:155], v245
	ds_read_b128 v[156:159], v246
	ds_read_b128 v[230:233], v247
	ds_read_b128 v[234:237], v244 offset:128
	ds_read_b128 v[238:241], v245 offset:128
	s_waitcnt lgkmcnt(5)
	v_mfma_f32_32x32x16_bf16 v[128:143], v[148:151], v[160:163], 0
	ds_read_b128 v[148:151], v246 offset:128
	s_waitcnt lgkmcnt(5)
	v_mfma_f32_32x32x16_bf16 v[128:143], v[152:155], v[164:167], v[128:143]
	ds_read_b128 v[152:155], v247 offset:128
	s_waitcnt lgkmcnt(5)
	v_mfma_f32_32x32x16_bf16 v[128:143], v[156:159], v[168:171], v[128:143]
	ds_read_b128 v[144:147], v244 offset:8192
	s_waitcnt lgkmcnt(5)
	v_mfma_f32_32x32x16_bf16 v[128:143], v[230:233], v[172:175], v[128:143]
	ds_read_b128 v[230:233], v245 offset:8192
	s_waitcnt lgkmcnt(5)
	v_mfma_f32_32x32x16_bf16 v[128:143], v[234:237], v[176:179], v[128:143]
	ds_read_b128 v[234:237], v246 offset:8192
	s_waitcnt lgkmcnt(5)
	v_mfma_f32_32x32x16_bf16 v[128:143], v[238:241], v[180:183], v[128:143]
	ds_read_b128 v[238:241], v247 offset:8192
	s_waitcnt lgkmcnt(5)
	v_mfma_f32_32x32x16_bf16 v[128:143], v[148:151], v[184:187], v[128:143]
	s_waitcnt lgkmcnt(4)
	v_mfma_f32_32x32x16_bf16 v[128:143], v[152:155], v[188:191], v[128:143]
	s_waitcnt lgkmcnt(3)
	v_mfma_f32_32x32x16_bf16 v[144:159], v[144:147], v[160:163], 0
	s_waitcnt lgkmcnt(2)
	v_mfma_f32_32x32x16_bf16 v[144:159], v[230:233], v[164:167], v[144:159]
	ds_read_b128 v[230:233], v244 offset:8320
	s_waitcnt lgkmcnt(2)
	v_mfma_f32_32x32x16_bf16 v[144:159], v[234:237], v[168:171], v[144:159]
	ds_read_b128 v[234:237], v245 offset:8320
	s_waitcnt lgkmcnt(2)
	v_mfma_f32_32x32x16_bf16 v[144:159], v[238:241], v[172:175], v[144:159]
	ds_read_b128 v[238:241], v246 offset:8320
	s_waitcnt lgkmcnt(2)
	v_mfma_f32_32x32x16_bf16 v[144:159], v[230:233], v[176:179], v[144:159]
	ds_read_b128 v[230:233], v247 offset:8320
	s_waitcnt lgkmcnt(2)
	v_mfma_f32_32x32x16_bf16 v[144:159], v[234:237], v[180:183], v[144:159]
	s_waitcnt lgkmcnt(1)
	v_mfma_f32_32x32x16_bf16 v[144:159], v[238:241], v[184:187], v[144:159]
	s_waitcnt lgkmcnt(0)
	v_mfma_f32_32x32x16_bf16 v[144:159], v[230:233], v[188:191], v[144:159]
	v_cvt_f32_i32_e32 v230, s8
	v_mov_b32_e32 v231, v212
	s_nop 0
	v_sub_f32_e32 v247, v231, v230
	v_fma_f32 v231, |v247|, v213, v128
	v_add_f32_e32 v128, -1.0, v247
	v_fma_f32 v232, |v128|, v213, v129
	v_add_f32_e32 v128, -2.0, v247
	v_fma_f32 v233, |v128|, v213, v130
	v_add_f32_e32 v128, 0xc0400000, v247
	v_fma_f32 v234, |v128|, v213, v131
	v_add_f32_e32 v128, 0xc1000000, v247
	v_fma_f32 v235, |v128|, v213, v132
	v_add_f32_e32 v128, 0xc1100000, v247
	v_fma_f32 v236, |v128|, v213, v133
	v_add_f32_e32 v128, 0xc1200000, v247
	v_fma_f32 v237, |v128|, v213, v134
	v_add_f32_e32 v128, 0xc1300000, v247
	v_fma_f32 v238, |v128|, v213, v135
	v_add_f32_e32 v128, 0xc1800000, v247
	v_fma_f32 v239, |v128|, v213, v136
	v_add_f32_e32 v128, 0xc1880000, v247
	v_fma_f32 v240, |v128|, v213, v137
	v_add_f32_e32 v128, 0xc1900000, v247
	v_fma_f32 v241, |v128|, v213, v138
	v_add_f32_e32 v128, 0xc1980000, v247
	v_fma_f32 v242, |v128|, v213, v139
	v_add_f32_e32 v128, 0xc1c00000, v247
	v_fma_f32 v243, |v128|, v213, v140
	v_add_f32_e32 v128, 0xc1c80000, v247
	v_fma_f32 v244, |v128|, v213, v141
	v_add_f32_e32 v128, 0xc1d00000, v247
	v_fma_f32 v245, |v128|, v213, v142
	v_add_f32_e32 v128, 0xc1d80000, v247
	v_fma_f32 v246, |v128|, v213, v143
	v_add_f32_e32 v128, 0xc2000000, v247
	v_fma_f32 v144, |v128|, v213, v144
	v_add_f32_e32 v128, 0xc2040000, v247
	v_fma_f32 v230, |v128|, v213, v145
	v_add_f32_e32 v128, 0xc2080000, v247
	v_fma_f32 v146, |v128|, v213, v146
	v_add_f32_e32 v128, 0xc20c0000, v247
	v_fma_f32 v147, |v128|, v213, v147
	v_add_f32_e32 v128, 0xc2200000, v247
	v_fma_f32 v148, |v128|, v213, v148
	v_add_f32_e32 v128, 0xc2240000, v247
	v_fma_f32 v149, |v128|, v213, v149
	v_add_f32_e32 v128, 0xc2280000, v247
	v_fma_f32 v150, |v128|, v213, v150
	v_add_f32_e32 v128, 0xc22c0000, v247
	v_fma_f32 v151, |v128|, v213, v151
	v_add_f32_e32 v128, 0xc2400000, v247
	v_fma_f32 v152, |v128|, v213, v152
	v_add_f32_e32 v128, 0xc2440000, v247
	v_fma_f32 v153, |v128|, v213, v153
	v_add_f32_e32 v128, 0xc2480000, v247
	v_fma_f32 v154, |v128|, v213, v154
	v_add_f32_e32 v128, 0xc24c0000, v247
	v_fma_f32 v155, |v128|, v213, v155
	v_add_f32_e32 v128, 0xc2600000, v247
	v_fma_f32 v156, |v128|, v213, v156
	v_add_f32_e32 v128, 0xc2640000, v247
	v_fma_f32 v157, |v128|, v213, v157
	v_add_f32_e32 v128, 0xc2680000, v247
	v_fma_f32 v158, |v128|, v213, v158
	v_add_f32_e32 v128, 0xc26c0000, v247
	v_fma_f32 v159, |v128|, v213, v159
	v_max_f32_e32 v128, v231, v232
	v_max3_f32 v128, v128, v233, v234
	v_max3_f32 v128, v128, v235, v236
	v_max3_f32 v128, v128, v237, v238
	v_max3_f32 v128, v128, v239, v240
	v_max3_f32 v128, v128, v241, v242
	v_max3_f32 v128, v128, v243, v244
	v_max3_f32 v128, v128, v245, v246
	v_max3_f32 v128, v128, v144, v230
	v_max3_f32 v128, v128, v146, v147
	v_max3_f32 v128, v128, v148, v149
	v_max3_f32 v128, v128, v150, v151
	v_max3_f32 v128, v128, v152, v153
	v_max3_f32 v128, v128, v154, v155
	v_max3_f32 v128, v128, v156, v157
	v_max3_f32 v128, v128, v158, v159
	v_mov_b32_e32 v129, v128
	s_nop 1
	v_permlane32_swap_b32_e32 v128, v129
	v_max_f32_e32 v129, v129, v129
	v_max_f32_e32 v128, v128, v128
	v_max_f32_e32 v128, v128, v129
	v_max_f32_e32 v130, v228, v228
	v_max_f32_e32 v247, v130, v128
	v_sub_f32_e32 v129, v128, v228
	v_sub_f32_e32 v128, v228, v247
	v_mul_f32_e32 v128, 0x3e0293ee, v128
	v_exp_f32_e32 v128, v128
	v_cmp_ge_f32_e32 vcc, s5, v129
	s_cmp_eq_u64 vcc, exec
	s_cselect_b64 s[8:9], -1, 0
	v_cndmask_b32_e64 v145, v128, 1.0, s[8:9]
	s_cbranch_scc1 .LBB0_961
; __device__ __forceinline__ int crow(int r, int hi) { return (r & 3) + 8 * (r >> 2) + 4 * hi; }
; template <bool OFF>
; __device__ __forceinline__ void partialSM(f32x16& p0, f32x16& p1, float& m_reg, float& mn, float& alpha, float boff) {
;     ...
;   const float mnC = (OFF ? boff - mn : -mn) * C;
; #pragma unroll
;   for (int r = 0; r < 16; ++r) p0[r] = fmaf(p0[r], C, mnC);
; #pragma unroll
;   for (int r = 0; r < 16; ++r) p1[r] = fmaf(p1[r], C, mnC);
; #pragma unroll
;   for (int r = 0; r < 16; ++r) p0[r] = __builtin_amdgcn_exp2f(p0[r]);
; }
; __device__ __forceinline__ void finishSM(f32x16& p0, f32x16& p1, float alpha, float& l_reg, bf16x8& pa0, bf16x8& pa1, bf16x8& pa2, bf16x8& pa3) {
; #pragma unroll
;   for (int r = 0; r < 16; ++r) p1[r] = __builtin_amdgcn_exp2f(p1[r]);
; __device__ __forceinline__ void b3_map(f32x16 (&o0)[4], f32x16 (&o1)[4], const AGAS bf16* __restrict__ Qb, const AGAS bf16* __restrict__ Kh, const AGAS bf16* __restrict__ V0h, const AGAS bf16* __restrict__ V1h, int NT, Mod M, ALAS char* lds) {
;     ...
;     if (__any(alpha < 1.f)) { if (hi == 0) al_l[r32] = alpha; asm volatile("s_waitcnt lgkmcnt(0)" ::: "memory");
; #pragma unroll
;       for (int r = 0; r < 16; ++r) { const float al = al_l[crow(r, hi)];
; #pragma unroll
;         for (int d = 0; d < 4; ++d) { o0[d][r] *= al; o1[d][r] *= al; } } }
	s_and_saveexec_b64 s[80:81], s[6:7]
	ds_write_b32 v218, v145 offset:128
	s_or_b64 exec, exec, s[80:81]
	s_waitcnt lgkmcnt(0)
	v_add_u32_e32 v128, s90, v196
	ds_read_b128 v[140:143], v128 offset:224
	ds_read_b128 v[136:139], v128 offset:192
	ds_read_b128 v[132:135], v128 offset:160
	ds_read_b128 v[128:131], v128 offset:128
	s_waitcnt lgkmcnt(0)
	v_pk_mul_f32 v[124:125], v[124:125], v[140:141]
	v_pk_mul_f32 v[120:121], v[120:121], v[136:137]
	v_pk_mul_f32 v[116:117], v[116:117], v[132:133]
	v_pk_mul_f32 v[126:127], v[126:127], v[142:143]
	v_pk_mul_f32 v[122:123], v[122:123], v[138:139]
	v_pk_mul_f32 v[118:119], v[118:119], v[134:135]
	v_pk_mul_f32 v[114:115], v[114:115], v[130:131]
	v_pk_mul_f32 v[112:113], v[112:113], v[128:129]
	v_pk_mul_f32 v[12:13], v[12:13], v[140:141]
	v_pk_mul_f32 v[8:9], v[8:9], v[136:137]
	v_pk_mul_f32 v[4:5], v[4:5], v[132:133]
	v_pk_mul_f32 v[14:15], v[14:15], v[142:143]
	v_pk_mul_f32 v[10:11], v[10:11], v[138:139]
	v_pk_mul_f32 v[6:7], v[6:7], v[134:135]
	v_pk_mul_f32 v[2:3], v[2:3], v[130:131]
	v_pk_mul_f32 v[0:1], v[0:1], v[128:129]
	v_pk_mul_f32 v[108:109], v[108:109], v[140:141]
	v_pk_mul_f32 v[104:105], v[104:105], v[136:137]
	v_pk_mul_f32 v[100:101], v[100:101], v[132:133]
	v_pk_mul_f32 v[110:111], v[110:111], v[142:143]
	v_pk_mul_f32 v[106:107], v[106:107], v[138:139]
	v_pk_mul_f32 v[102:103], v[102:103], v[134:135]
	v_pk_mul_f32 v[98:99], v[98:99], v[130:131]
	v_pk_mul_f32 v[96:97], v[96:97], v[128:129]
	v_pk_mul_f32 v[60:61], v[60:61], v[140:141]
	v_pk_mul_f32 v[56:57], v[56:57], v[136:137]
	v_pk_mul_f32 v[52:53], v[52:53], v[132:133]
	v_pk_mul_f32 v[62:63], v[62:63], v[142:143]
	v_pk_mul_f32 v[58:59], v[58:59], v[138:139]
	v_pk_mul_f32 v[54:55], v[54:55], v[134:135]
	v_pk_mul_f32 v[50:51], v[50:51], v[130:131]
	v_pk_mul_f32 v[48:49], v[48:49], v[128:129]
	v_pk_mul_f32 v[92:93], v[92:93], v[140:141]
	v_pk_mul_f32 v[88:89], v[88:89], v[136:137]
	v_pk_mul_f32 v[84:85], v[84:85], v[132:133]
	v_pk_mul_f32 v[94:95], v[94:95], v[142:143]
	v_pk_mul_f32 v[90:91], v[90:91], v[138:139]
	v_pk_mul_f32 v[86:87], v[86:87], v[134:135]
	v_pk_mul_f32 v[82:83], v[82:83], v[130:131]
	v_pk_mul_f32 v[80:81], v[80:81], v[128:129]
	v_pk_mul_f32 v[44:45], v[44:45], v[140:141]
	v_pk_mul_f32 v[40:41], v[40:41], v[136:137]
	v_pk_mul_f32 v[36:37], v[36:37], v[132:133]
	v_pk_mul_f32 v[46:47], v[46:47], v[142:143]
	v_pk_mul_f32 v[42:43], v[42:43], v[138:139]
	v_pk_mul_f32 v[38:39], v[38:39], v[134:135]
	v_pk_mul_f32 v[34:35], v[34:35], v[130:131]
	v_pk_mul_f32 v[32:33], v[32:33], v[128:129]
	v_pk_mul_f32 v[76:77], v[76:77], v[140:141]
	v_pk_mul_f32 v[72:73], v[72:73], v[136:137]
	v_pk_mul_f32 v[68:69], v[68:69], v[132:133]
	v_pk_mul_f32 v[78:79], v[78:79], v[142:143]
	v_pk_mul_f32 v[74:75], v[74:75], v[138:139]
	v_pk_mul_f32 v[70:71], v[70:71], v[134:135]
	v_pk_mul_f32 v[66:67], v[66:67], v[130:131]
	v_pk_mul_f32 v[64:65], v[64:65], v[128:129]
	v_pk_mul_f32 v[28:29], v[28:29], v[140:141]
	v_pk_mul_f32 v[24:25], v[24:25], v[136:137]
	v_pk_mul_f32 v[20:21], v[20:21], v[132:133]
	v_pk_mul_f32 v[30:31], v[30:31], v[142:143]
	v_pk_mul_f32 v[26:27], v[26:27], v[138:139]
	v_pk_mul_f32 v[22:23], v[22:23], v[134:135]
	v_pk_mul_f32 v[18:19], v[18:19], v[130:131]
	v_pk_mul_f32 v[16:17], v[16:17], v[128:129]
.LBB0_961:
	v_cndmask_b32_e64 v228, v247, v228, s[8:9]
	v_mul_f32_e32 v128, 0xbe0293ee, v228
	v_fmamk_f32 v129, v231, 0x3e0293ee, v128
	v_fmamk_f32 v130, v232, 0x3e0293ee, v128
	v_exp_f32_e32 v129, v129
	v_fmamk_f32 v131, v233, 0x3e0293ee, v128
	v_exp_f32_e32 v130, v130
	v_fmamk_f32 v132, v234, 0x3e0293ee, v128
	v_exp_f32_e32 v131, v131
	v_fmamk_f32 v133, v235, 0x3e0293ee, v128
	v_fmamk_f32 v134, v236, 0x3e0293ee, v128
	v_fmamk_f32 v135, v237, 0x3e0293ee, v128
	v_fmamk_f32 v136, v238, 0x3e0293ee, v128
	v_fmamk_f32 v137, v239, 0x3e0293ee, v128
	v_fmamk_f32 v138, v240, 0x3e0293ee, v128
	v_fmamk_f32 v139, v241, 0x3e0293ee, v128
	v_fmamk_f32 v140, v242, 0x3e0293ee, v128
	v_fmamk_f32 v141, v243, 0x3e0293ee, v128
	v_fmamk_f32 v142, v244, 0x3e0293ee, v128
	v_fmamk_f32 v143, v245, 0x3e0293ee, v128
	v_fmamk_f32 v231, v246, 0x3e0293ee, v128
	v_fmamk_f32 v144, v144, 0x3e0293ee, v128
	v_fmamk_f32 v230, v230, 0x3e0293ee, v128
	v_fmamk_f32 v146, v146, 0x3e0293ee, v128
	v_fmamk_f32 v147, v147, 0x3e0293ee, v128
	v_fmamk_f32 v148, v148, 0x3e0293ee, v128
	v_fmamk_f32 v149, v149, 0x3e0293ee, v128
	v_fmamk_f32 v150, v150, 0x3e0293ee, v128
	v_fmamk_f32 v151, v151, 0x3e0293ee, v128
	v_fmamk_f32 v152, v152, 0x3e0293ee, v128
	v_fmamk_f32 v153, v153, 0x3e0293ee, v128
	v_fmamk_f32 v154, v154, 0x3e0293ee, v128
	v_fmamk_f32 v155, v155, 0x3e0293ee, v128
	v_fmamk_f32 v156, v156, 0x3e0293ee, v128
	v_fmamk_f32 v157, v157, 0x3e0293ee, v128
	v_fmamk_f32 v158, v158, 0x3e0293ee, v128
	v_fmac_f32_e32 v128, 0x3e0293ee, v159
	v_exp_f32_e32 v132, v132
	v_exp_f32_e32 v133, v133
	v_exp_f32_e32 v236, v128
	v_add_f32_e32 v128, 0, v129
	v_exp_f32_e32 v134, v134
	v_add_f32_e32 v128, v130, v128
	v_exp_f32_e32 v135, v135
	v_add_f32_e32 v128, v131, v128
	v_exp_f32_e32 v136, v136
	v_add_f32_e32 v128, v132, v128
	v_exp_f32_e32 v137, v137
	v_add_f32_e32 v128, v133, v128
	v_exp_f32_e32 v138, v138
	v_add_f32_e32 v128, v134, v128
	v_exp_f32_e32 v139, v139
	v_add_f32_e32 v128, v135, v128
	v_exp_f32_e32 v159, v140
	v_add_f32_e32 v128, v136, v128
	v_exp_f32_e32 v232, v141
	v_add_f32_e32 v128, v137, v128
	v_exp_f32_e32 v233, v142
	v_add_f32_e32 v128, v138, v128
	v_exp_f32_e32 v234, v143
	v_add_f32_e32 v128, v139, v128
	v_exp_f32_e32 v231, v231
	v_add_f32_e32 v128, v159, v128
	v_exp_f32_e32 v235, v144
	v_add_f32_e32 v128, v232, v128
	v_exp_f32_e32 v230, v230
	v_add_f32_e32 v128, v233, v128
; __device__ __forceinline__ void finishSM(f32x16& p0, f32x16& p1, float alpha, float& l_reg, bf16x8& pa0, bf16x8& pa1, bf16x8& pa2, bf16x8& pa3) {
; #pragma unroll
;   for (int r = 0; r < 16; ++r) p1[r] = __builtin_amdgcn_exp2f(p1[r]);
;   float ps = 0;
; #pragma unroll
;   for (int r = 0; r < 16; ++r) ps += p0[r];
; #pragma unroll
;   for (int r = 0; r < 16; ++r) ps += p1[r];
;   { auto rr = __builtin_amdgcn_permlane32_swap(__float_as_uint(ps), __float_as_uint(ps), false, false);
;     ps = __uint_as_float(rr[0]) + __uint_as_float(rr[1]); }
;   l_reg = l_reg * alpha + ps;
;     ...
;   PK4(p0, 0, pa0); PK4(p0, 8, pa1); PK4(p1, 0, pa2); PK4(p1, 8, pa3);
	v_exp_f32_e32 v146, v146
	v_add_f32_e32 v128, v234, v128
	v_exp_f32_e32 v147, v147
	v_add_f32_e32 v128, v231, v128
	v_exp_f32_e32 v148, v148
	v_add_f32_e32 v128, v235, v128
	v_exp_f32_e32 v149, v149
	v_add_f32_e32 v128, v230, v128
	v_exp_f32_e32 v150, v150
	v_add_f32_e32 v128, v146, v128
	v_exp_f32_e32 v151, v151
	v_add_f32_e32 v128, v147, v128
	v_exp_f32_e32 v152, v152
	v_add_f32_e32 v128, v148, v128
	v_exp_f32_e32 v153, v153
	v_add_f32_e32 v128, v149, v128
	v_exp_f32_e32 v154, v154
	v_add_f32_e32 v128, v150, v128
	v_exp_f32_e32 v155, v155
	v_add_f32_e32 v128, v151, v128
	v_exp_f32_e32 v156, v156
	v_add_f32_e32 v128, v152, v128
	v_exp_f32_e32 v157, v157
	v_add_f32_e32 v128, v153, v128
	v_exp_f32_e32 v158, v158
	v_add_f32_e32 v128, v154, v128
	v_add_f32_e32 v128, v155, v128
	v_add_f32_e32 v128, v156, v128
	v_add_f32_e32 v128, v157, v128
	s_sub_i32 s92, s92, s78
	s_xor_b64 s[8:9], s[78:79], -1
	v_add_f32_e32 v128, v158, v128
	v_add_f32_e32 v128, v236, v128
	v_mov_b32_e32 v140, v128
	s_nop 1
	v_permlane32_swap_b32_e32 v128, v140
	v_add_f32_e32 v144, v128, v140
	v_cvt_pk_bf16_f32 v140, v129, v130
	v_cvt_pk_bf16_f32 v141, v131, v132
	v_cvt_pk_bf16_f32 v142, v133, v134
	v_cvt_pk_bf16_f32 v143, v135, v136
	v_cvt_pk_bf16_f32 v132, v137, v138
	v_cvt_pk_bf16_f32 v133, v139, v159
	v_cvt_pk_bf16_f32 v134, v232, v233
	v_cvt_pk_bf16_f32 v135, v234, v231
	v_cvt_pk_bf16_f32 v128, v235, v230
	v_cvt_pk_bf16_f32 v129, v146, v147
	v_cvt_pk_bf16_f32 v130, v148, v149
	v_cvt_pk_bf16_f32 v131, v150, v151
	v_cvt_pk_bf16_f32 v136, v152, v153
	v_cvt_pk_bf16_f32 v137, v154, v155
	v_cvt_pk_bf16_f32 v138, v156, v157
	v_cvt_pk_bf16_f32 v139, v158, v236
	s_waitcnt lgkmcnt(0)
	v_fmac_f32_e32 v144, v229, v145
	v_lshl_add_u32 v145, s77, 15, v227
	ds_read_b64_tr_b16 v[146:147], v145 offset:0
	ds_read_b64_tr_b16 v[148:149], v145 offset:0x800
	ds_read_b64_tr_b16 v[150:151], v145 offset:0x1000
	v_permlane32_swap_b32_e32 v140, v142
	v_permlane32_swap_b32_e32 v141, v143
	ds_read_b64_tr_b16 v[152:153], v145 offset:0x1800
	ds_read_b64_tr_b16 v[154:155], v145 offset:0x2000
	ds_read_b64_tr_b16 v[156:157], v145 offset:0x2800
	ds_read_b64_tr_b16 v[230:231], v145 offset:0x3000
	ds_read_b64_tr_b16 v[232:233], v145 offset:0x3800
	v_permlane32_swap_b32_e32 v132, v134
	s_waitcnt lgkmcnt(4)
	v_permlane32_swap_b32_e32 v133, v135
	v_mfma_f32_32x32x16_bf16 v[112:127], v[140:143], v[146:149], v[112:127]
	v_permlane32_swap_b32_e32 v128, v130
	v_permlane32_swap_b32_e32 v129, v131
	ds_read_b64_tr_b16 v[146:147], v145 offset:0x200
	ds_read_b64_tr_b16 v[148:149], v145 offset:0xa00
	v_permlane32_swap_b32_e32 v136, v138
	v_mfma_f32_32x32x16_bf16 v[112:127], v[132:135], v[150:153], v[112:127]
	ds_read_b64_tr_b16 v[150:151], v145 offset:0x1200
	ds_read_b64_tr_b16 v[152:153], v145 offset:0x1a00
	s_waitcnt lgkmcnt(4)
	v_permlane32_swap_b32_e32 v137, v139
	v_add_u32_e32 v158, 0x4000, v145
	s_add_i32 s54, s54, s8
	v_mfma_f32_32x32x16_bf16 v[112:127], v[128:131], v[154:157], v[112:127]
	ds_read_b64_tr_b16 v[154:155], v145 offset:0x2200
	ds_read_b64_tr_b16 v[156:157], v145 offset:0x2a00
	s_xor_b64 s[62:63], s[62:63], -1
	s_cmp_eq_u32 s82, 32
	v_mfma_f32_32x32x16_bf16 v[112:127], v[136:139], v[230:233], v[112:127]
	ds_read_b64_tr_b16 v[230:231], v145 offset:0x3200
	ds_read_b64_tr_b16 v[232:233], v145 offset:0x3a00
	s_waitcnt lgkmcnt(4)
	s_nop 0
	v_mfma_f32_32x32x16_bf16 v[96:111], v[140:143], v[146:149], v[96:111]
	ds_read_b64_tr_b16 v[146:147], v145 offset:0x400
	ds_read_b64_tr_b16 v[148:149], v145 offset:0xc00
	v_mfma_f32_32x32x16_bf16 v[96:111], v[132:135], v[150:153], v[96:111]
	ds_read_b64_tr_b16 v[150:151], v145 offset:0x1400
	ds_read_b64_tr_b16 v[152:153], v145 offset:0x1c00
	s_waitcnt lgkmcnt(4)
	s_nop 0
	v_mfma_f32_32x32x16_bf16 v[96:111], v[128:131], v[154:157], v[96:111]
	ds_read_b64_tr_b16 v[154:155], v145 offset:0x2400
	ds_read_b64_tr_b16 v[156:157], v145 offset:0x2c00
	v_mfma_f32_32x32x16_bf16 v[96:111], v[136:139], v[230:233], v[96:111]
	ds_read_b64_tr_b16 v[230:231], v145 offset:0x3400
	ds_read_b64_tr_b16 v[232:233], v145 offset:0x3c00
	s_waitcnt lgkmcnt(4)
; #define PVR(S, VB, D0, K0) do { S##l0 = tr_read<v_rd_off(D0, K0, 0)>(VB); S##h0 = tr_read<v_rd_off(D0, K0, 1)>(VB); S##l1 = tr_read<v_rd_off(D0, (K0) + 1, 0)>(VB); S##h1 = tr_read<v_rd_off(D0, (K0) + 1, 1)>(VB); } while (0)
; #define PVW(S, N) asm volatile("s_waitcnt lgkmcnt(" #N ")" : "+v"(S##l0), "+v"(S##h0), "+v"(S##l1), "+v"(S##h1) :: "memory")
; #define PVM(O, S, PA, PB) do { O = __builtin_amdgcn_mfma_f32_32x32x16_bf16(PA, PVK(S##l0, S##h0), O, 0, 0, 0); O = __builtin_amdgcn_mfma_f32_32x32x16_bf16(PB, PVK(S##l1, S##h1), O, 0, 0, 0); } while (0)
; __device__ __forceinline__ void pv_256(f32x16* o0, f32x16* o1, int v0, int v1, bf16x8 pa0, bf16x8 pa1, bf16x8 pa2, bf16x8 pa3) {
;   s16x4 Al0, Ah0, Al1, Ah1, Bl0, Bh0, Bl1, Bh1;
;   PVR(A, v0, 0, 0); PVR(B, v0, 0, 2);
;   PVW(A, 4); PVM(o0[0], A, pa0, pa1); PVR(A, v0, 1, 0);
;   PVW(B, 4); PVM(o0[0], B, pa2, pa3); PVR(B, v0, 1, 2);
;   PVW(A, 4); PVM(o0[1], A, pa0, pa1); PVR(A, v0, 2, 0);
;   PVW(B, 4); PVM(o0[1], B, pa2, pa3); PVR(B, v0, 2, 2);
;   PVW(A, 4); PVM(o0[2], A, pa0, pa1); PVR(A, v0, 3, 0);
;   PVW(B, 4); PVM(o0[2], B, pa2, pa3); PVR(B, v0, 3, 2);
;   PVW(A, 4); PVM(o0[3], A, pa0, pa1); PVR(A, v1, 0, 0);
;   PVW(B, 4); PVM(o0[3], B, pa2, pa3); PVR(B, v1, 0, 2);
;   PVW(A, 4); PVM(o1[0], A, pa0, pa1); PVR(A, v1, 1, 0);
;   PVW(B, 4); PVM(o1[0], B, pa2, pa3); PVR(B, v1, 1, 2);
;   PVW(A, 4); PVM(o1[1], A, pa0, pa1); PVR(A, v1, 2, 0);
;   PVW(B, 4); PVM(o1[1], B, pa2, pa3); PVR(B, v1, 2, 2);
;   PVW(A, 4); PVM(o1[2], A, pa0, pa1); PVR(A, v1, 3, 0);
;   PVW(B, 4); PVM(o1[2], B, pa2, pa3); PVR(B, v1, 3, 2);
;   PVW(A, 4); PVM(o1[3], A, pa0, pa1);
;   PVW(B, 0); PVM(o1[3], B, pa2, pa3);
; }
	s_nop 0
	v_mfma_f32_32x32x16_bf16 v[80:95], v[140:143], v[146:149], v[80:95]
	ds_read_b64_tr_b16 v[146:147], v145 offset:0x600
	ds_read_b64_tr_b16 v[148:149], v145 offset:0xe00
	v_mfma_f32_32x32x16_bf16 v[80:95], v[132:135], v[150:153], v[80:95]
	ds_read_b64_tr_b16 v[150:151], v145 offset:0x1600
	ds_read_b64_tr_b16 v[152:153], v145 offset:0x1e00
	s_waitcnt lgkmcnt(4)
	s_nop 0
	v_mfma_f32_32x32x16_bf16 v[80:95], v[128:131], v[154:157], v[80:95]
	ds_read_b64_tr_b16 v[154:155], v145 offset:0x2600
	ds_read_b64_tr_b16 v[156:157], v145 offset:0x2e00
	v_mfma_f32_32x32x16_bf16 v[80:95], v[136:139], v[230:233], v[80:95]
	ds_read_b64_tr_b16 v[230:231], v145 offset:0x3600
	ds_read_b64_tr_b16 v[232:233], v145 offset:0x3e00
	s_waitcnt lgkmcnt(4)
	s_nop 0
	v_mfma_f32_32x32x16_bf16 v[64:79], v[140:143], v[146:149], v[64:79]
	ds_read_b64_tr_b16 v[146:147], v158 offset:0
	ds_read_b64_tr_b16 v[148:149], v158 offset:0x800
	v_mfma_f32_32x32x16_bf16 v[64:79], v[132:135], v[150:153], v[64:79]
	ds_read_b64_tr_b16 v[150:151], v158 offset:0x1000
	ds_read_b64_tr_b16 v[152:153], v158 offset:0x1800
	s_waitcnt lgkmcnt(4)
	s_nop 0
	v_mfma_f32_32x32x16_bf16 v[64:79], v[128:131], v[154:157], v[64:79]
	ds_read_b64_tr_b16 v[154:155], v158 offset:0x2000
	ds_read_b64_tr_b16 v[156:157], v158 offset:0x2800
	v_mfma_f32_32x32x16_bf16 v[64:79], v[136:139], v[230:233], v[64:79]
	ds_read_b64_tr_b16 v[230:231], v158 offset:0x3000
	ds_read_b64_tr_b16 v[232:233], v158 offset:0x3800
	s_waitcnt lgkmcnt(4)
	s_nop 0
	v_mfma_f32_32x32x16_bf16 v[0:15], v[140:143], v[146:149], v[0:15]
	ds_read_b64_tr_b16 v[146:147], v158 offset:0x200
	ds_read_b64_tr_b16 v[148:149], v158 offset:0xa00
	v_mfma_f32_32x32x16_bf16 v[0:15], v[132:135], v[150:153], v[0:15]
	ds_read_b64_tr_b16 v[150:151], v158 offset:0x1200
	ds_read_b64_tr_b16 v[152:153], v158 offset:0x1a00
	s_waitcnt lgkmcnt(4)
	s_nop 0
	v_mfma_f32_32x32x16_bf16 v[0:15], v[128:131], v[154:157], v[0:15]
	ds_read_b64_tr_b16 v[154:155], v158 offset:0x2200
	ds_read_b64_tr_b16 v[156:157], v158 offset:0x2a00
	v_mfma_f32_32x32x16_bf16 v[0:15], v[136:139], v[230:233], v[0:15]
	ds_read_b64_tr_b16 v[230:231], v158 offset:0x3200
	ds_read_b64_tr_b16 v[232:233], v158 offset:0x3a00
	s_waitcnt lgkmcnt(4)
	s_nop 0
	v_mfma_f32_32x32x16_bf16 v[48:63], v[140:143], v[146:149], v[48:63]
	ds_read_b64_tr_b16 v[146:147], v158 offset:0x400
	ds_read_b64_tr_b16 v[148:149], v158 offset:0xc00
	v_mfma_f32_32x32x16_bf16 v[48:63], v[132:135], v[150:153], v[48:63]
	ds_read_b64_tr_b16 v[150:151], v158 offset:0x1400
	ds_read_b64_tr_b16 v[152:153], v158 offset:0x1c00
	s_waitcnt lgkmcnt(4)
	s_nop 0
	v_mfma_f32_32x32x16_bf16 v[48:63], v[128:131], v[154:157], v[48:63]
	ds_read_b64_tr_b16 v[154:155], v158 offset:0x2400
	ds_read_b64_tr_b16 v[156:157], v158 offset:0x2c00
	v_mfma_f32_32x32x16_bf16 v[48:63], v[136:139], v[230:233], v[48:63]
	ds_read_b64_tr_b16 v[230:231], v158 offset:0x3400
	ds_read_b64_tr_b16 v[232:233], v158 offset:0x3c00
	s_waitcnt lgkmcnt(4)
	s_nop 0
	v_mfma_f32_32x32x16_bf16 v[32:47], v[140:143], v[146:149], v[32:47]
	ds_read_b64_tr_b16 v[146:147], v158 offset:0x600
	ds_read_b64_tr_b16 v[148:149], v158 offset:0xe00
	v_mfma_f32_32x32x16_bf16 v[32:47], v[132:135], v[150:153], v[32:47]
	ds_read_b64_tr_b16 v[150:151], v158 offset:0x1600
	ds_read_b64_tr_b16 v[152:153], v158 offset:0x1e00
	s_waitcnt lgkmcnt(4)
	s_nop 0
	v_mfma_f32_32x32x16_bf16 v[32:47], v[128:131], v[154:157], v[32:47]
	ds_read_b64_tr_b16 v[154:155], v158 offset:0x2600
	ds_read_b64_tr_b16 v[156:157], v158 offset:0x2e00
	v_mfma_f32_32x32x16_bf16 v[32:47], v[136:139], v[230:233], v[32:47]
	ds_read_b64_tr_b16 v[230:231], v158 offset:0x3600
	ds_read_b64_tr_b16 v[232:233], v158 offset:0x3e00
	s_waitcnt lgkmcnt(4)
	s_nop 0
	s_waitcnt lgkmcnt(0)
	v_mfma_f32_32x32x16_bf16 v[16:31], v[140:143], v[146:149], v[16:31]
	v_mfma_f32_32x32x16_bf16 v[16:31], v[132:135], v[150:153], v[16:31]
	v_mfma_f32_32x32x16_bf16 v[16:31], v[128:131], v[154:157], v[16:31]
	v_mfma_f32_32x32x16_bf16 v[16:31], v[136:139], v[230:233], v[16:31]
	s_cbranch_scc1 .LBB0_963
	s_mov_b32 s95, s76
	s_mov_b32 s94, s82
	v_mov_b32_e32 v229, v144
	s_branch .LBB0_942

; #define ALAS __attribute__((address_space(3)))
; __device__ __forceinline__ void qkt(f32x16& p0, f32x16& p1, const ALAS char* Ks, const bf16x8* qr, int r32, int hi) {
;   p0 = f32x16{}; p1 = f32x16{};
; #pragma unroll
;   for (int d0 = 0; d0 < 8; ++d0) { int cb = (d0 * 16 + hi * 8) * 2;
;     bf16x8 b0 = *(const ALAS bf16x8*)(Ks + KSWZ(r32, cb));
;     bf16x8 b1 = *(const ALAS bf16x8*)(Ks + KSWZ(32 + r32, cb));
;     p0 = __builtin_amdgcn_mfma_f32_32x32x16_bf16(b0, qr[d0], p0, 0, 0, 0);
;     p1 = __builtin_amdgcn_mfma_f32_32x32x16_bf16(b1, qr[d0], p1, 0, 0, 0); }
; }
; template <int MODE> __device__ __forceinline__ void modify2(f32x16& p0, f32x16& p1, const Mod& M, int j, float& boff) {
;   const float dq = M.a0 - (float)(j * 64); const float nsl = -M.a1;
; #pragma unroll
;   for (int r = 0; r < 16; ++r) { const float cr = (float)((r & 3) + 8 * (r >> 2));
;     p0[r] = fmaf(fabsf(dq - cr), nsl, p0[r]); p1[r] = fmaf(fabsf(dq - (cr + 32.f)), nsl, p1[r]); }
;   boff = 0.f;
.LBB0_1005:
	s_and_b32 s49, s19, 1
	v_mov_b32_e32 v128, v214
	v_mov_b32_e32 v129, v215
	s_lshl_b32 s8, s49, 14
	s_add_i32 s8, s8, 0
	s_add_i32 s8, s8, 0x10000
	v_lshlrev_b32_e32 v242, 4, v129
	v_lshlrev_b32_e32 v243, 4, v128
	v_and_b32_e32 v243, 0x70, v243
	v_lshl_add_u32 v241, v128, 8, s8
	v_xad_u32 v244, v242, v243, v241
	v_add_u32_e32 v240, 32, v242
	v_xad_u32 v245, v240, v243, v241
	v_add_u32_e32 v240, 64, v242
	v_xad_u32 v246, v240, v243, v241
	v_add_u32_e32 v240, 0x60, v242
	v_xad_u32 v247, v240, v243, v241
	s_lshl_b32 s8, s18, 6
	ds_read_b128 v[148:151], v244
	ds_read_b128 v[152:155], v245
	ds_read_b128 v[156:159], v246
	ds_read_b128 v[230:233], v247
	ds_read_b128 v[234:237], v244 offset:128
	ds_read_b128 v[238:241], v245 offset:128
	s_waitcnt lgkmcnt(5)
	v_mfma_f32_32x32x16_bf16 v[128:143], v[148:151], v[160:163], 0
	ds_read_b128 v[148:151], v246 offset:128
	s_waitcnt lgkmcnt(5)
	v_mfma_f32_32x32x16_bf16 v[128:143], v[152:155], v[164:167], v[128:143]
	ds_read_b128 v[152:155], v247 offset:128
	s_waitcnt lgkmcnt(5)
	v_mfma_f32_32x32x16_bf16 v[128:143], v[156:159], v[168:171], v[128:143]
	ds_read_b128 v[144:147], v244 offset:8192
	s_waitcnt lgkmcnt(5)
	v_mfma_f32_32x32x16_bf16 v[128:143], v[230:233], v[172:175], v[128:143]
	ds_read_b128 v[230:233], v245 offset:8192
	s_waitcnt lgkmcnt(5)
	v_mfma_f32_32x32x16_bf16 v[128:143], v[234:237], v[176:179], v[128:143]
	ds_read_b128 v[234:237], v246 offset:8192
	s_waitcnt lgkmcnt(5)
	v_mfma_f32_32x32x16_bf16 v[128:143], v[238:241], v[180:183], v[128:143]
	ds_read_b128 v[238:241], v247 offset:8192
	s_waitcnt lgkmcnt(5)
	v_mfma_f32_32x32x16_bf16 v[128:143], v[148:151], v[184:187], v[128:143]
	s_waitcnt lgkmcnt(4)
	v_mfma_f32_32x32x16_bf16 v[128:143], v[152:155], v[188:191], v[128:143]
	s_waitcnt lgkmcnt(3)
	v_mfma_f32_32x32x16_bf16 v[144:159], v[144:147], v[160:163], 0
	s_waitcnt lgkmcnt(2)
	v_mfma_f32_32x32x16_bf16 v[144:159], v[230:233], v[164:167], v[144:159]
	ds_read_b128 v[230:233], v244 offset:8320
	s_waitcnt lgkmcnt(2)
	v_mfma_f32_32x32x16_bf16 v[144:159], v[234:237], v[168:171], v[144:159]
	ds_read_b128 v[234:237], v245 offset:8320
	s_waitcnt lgkmcnt(2)
	v_mfma_f32_32x32x16_bf16 v[144:159], v[238:241], v[172:175], v[144:159]
	ds_read_b128 v[238:241], v246 offset:8320
	s_waitcnt lgkmcnt(2)
	v_mfma_f32_32x32x16_bf16 v[144:159], v[230:233], v[176:179], v[144:159]
	ds_read_b128 v[230:233], v247 offset:8320
	s_waitcnt lgkmcnt(2)
	v_mfma_f32_32x32x16_bf16 v[144:159], v[234:237], v[180:183], v[144:159]
	s_waitcnt lgkmcnt(1)
	v_mfma_f32_32x32x16_bf16 v[144:159], v[238:241], v[184:187], v[144:159]
	s_waitcnt lgkmcnt(0)
	v_mfma_f32_32x32x16_bf16 v[144:159], v[230:233], v[188:191], v[144:159]
	v_cvt_f32_i32_e32 v230, s8
	v_mov_b32_e32 v231, v212
	s_nop 0
	v_sub_f32_e32 v247, v231, v230
	v_fma_f32 v231, |v247|, v213, v128
	v_add_f32_e32 v128, -1.0, v247
	v_fma_f32 v232, |v128|, v213, v129
	v_add_f32_e32 v128, -2.0, v247
	v_fma_f32 v233, |v128|, v213, v130
	v_add_f32_e32 v128, 0xc0400000, v247
	v_fma_f32 v234, |v128|, v213, v131
	v_add_f32_e32 v128, 0xc1000000, v247
	v_fma_f32 v235, |v128|, v213, v132
	v_add_f32_e32 v128, 0xc1100000, v247
	v_fma_f32 v236, |v128|, v213, v133
	v_add_f32_e32 v128, 0xc1200000, v247
	v_fma_f32 v237, |v128|, v213, v134
	v_add_f32_e32 v128, 0xc1300000, v247
	v_fma_f32 v238, |v128|, v213, v135
	v_add_f32_e32 v128, 0xc1800000, v247
	v_fma_f32 v239, |v128|, v213, v136
	v_add_f32_e32 v128, 0xc1880000, v247
	v_fma_f32 v240, |v128|, v213, v137
	v_add_f32_e32 v128, 0xc1900000, v247
	v_fma_f32 v241, |v128|, v213, v138
	v_add_f32_e32 v128, 0xc1980000, v247
	v_fma_f32 v242, |v128|, v213, v139
	v_add_f32_e32 v128, 0xc1c00000, v247
	v_fma_f32 v243, |v128|, v213, v140
	v_add_f32_e32 v128, 0xc1c80000, v247
	v_fma_f32 v244, |v128|, v213, v141
	v_add_f32_e32 v128, 0xc1d00000, v247
	v_fma_f32 v245, |v128|, v213, v142
	v_add_f32_e32 v128, 0xc1d80000, v247
	v_fma_f32 v246, |v128|, v213, v143
	v_add_f32_e32 v128, 0xc2000000, v247
	v_fma_f32 v144, |v128|, v213, v144
	v_add_f32_e32 v128, 0xc2040000, v247
	v_fma_f32 v230, |v128|, v213, v145
	v_add_f32_e32 v128, 0xc2080000, v247
	v_fma_f32 v146, |v128|, v213, v146
	v_add_f32_e32 v128, 0xc20c0000, v247
	v_fma_f32 v147, |v128|, v213, v147
	v_add_f32_e32 v128, 0xc2200000, v247
	v_fma_f32 v148, |v128|, v213, v148
	v_add_f32_e32 v128, 0xc2240000, v247
	v_fma_f32 v149, |v128|, v213, v149
	v_add_f32_e32 v128, 0xc2280000, v247
	v_fma_f32 v150, |v128|, v213, v150
	v_add_f32_e32 v128, 0xc22c0000, v247
	v_fma_f32 v151, |v128|, v213, v151
	v_add_f32_e32 v128, 0xc2400000, v247
	v_fma_f32 v152, |v128|, v213, v152
	v_add_f32_e32 v128, 0xc2440000, v247
	v_fma_f32 v153, |v128|, v213, v153
	v_add_f32_e32 v128, 0xc2480000, v247
	v_fma_f32 v154, |v128|, v213, v154
	v_add_f32_e32 v128, 0xc24c0000, v247
	v_fma_f32 v155, |v128|, v213, v155
	v_add_f32_e32 v128, 0xc2600000, v247
	v_fma_f32 v156, |v128|, v213, v156
	v_add_f32_e32 v128, 0xc2640000, v247
	v_fma_f32 v157, |v128|, v213, v157
	v_add_f32_e32 v128, 0xc2680000, v247
	v_fma_f32 v158, |v128|, v213, v158
	v_add_f32_e32 v128, 0xc26c0000, v247
	v_fma_f32 v159, |v128|, v213, v159
	v_max_f32_e32 v128, v231, v232
	v_max3_f32 v128, v128, v233, v234
	v_max3_f32 v128, v128, v235, v236
	v_max3_f32 v128, v128, v237, v238
	v_max3_f32 v128, v128, v239, v240
	v_max3_f32 v128, v128, v241, v242
	v_max3_f32 v128, v128, v243, v244
	v_max3_f32 v128, v128, v245, v246
	v_max3_f32 v128, v128, v144, v230
	v_max3_f32 v128, v128, v146, v147
	v_max3_f32 v128, v128, v148, v149
	v_max3_f32 v128, v128, v150, v151
	v_max3_f32 v128, v128, v152, v153
	v_max3_f32 v128, v128, v154, v155
	v_max3_f32 v128, v128, v156, v157
	v_max3_f32 v128, v128, v158, v159
	v_mov_b32_e32 v129, v128
	s_nop 1
	v_permlane32_swap_b32_e32 v128, v129
	v_max_f32_e32 v129, v129, v129
	v_max_f32_e32 v128, v128, v128
	v_max_f32_e32 v128, v128, v129
	v_max_f32_e32 v130, v228, v228
	v_max_f32_e32 v247, v130, v128
	v_sub_f32_e32 v129, v128, v228
	v_sub_f32_e32 v128, v228, v247
	v_mul_f32_e32 v128, 0x3e0293ee, v128
	v_exp_f32_e32 v128, v128
	v_cmp_ge_f32_e32 vcc, s5, v129
	s_cmp_eq_u64 vcc, exec
	s_cselect_b64 s[8:9], -1, 0
	v_cndmask_b32_e64 v145, v128, 1.0, s[8:9]
	s_cbranch_scc1 .LBB0_1009
; __device__ __forceinline__ int crow(int r, int hi) { return (r & 3) + 8 * (r >> 2) + 4 * hi; }
; template <bool OFF>
; __device__ __forceinline__ void partialSM(f32x16& p0, f32x16& p1, float& m_reg, float& mn, float& alpha, float boff) {
;     ...
;   const float mnC = (OFF ? boff - mn : -mn) * C;
; #pragma unroll
;   for (int r = 0; r < 16; ++r) p0[r] = fmaf(p0[r], C, mnC);
; #pragma unroll
;   for (int r = 0; r < 16; ++r) p1[r] = fmaf(p1[r], C, mnC);
; #pragma unroll
;   for (int r = 0; r < 16; ++r) p0[r] = __builtin_amdgcn_exp2f(p0[r]);
; }
; __device__ __forceinline__ void finishSM(f32x16& p0, f32x16& p1, float alpha, float& l_reg, bf16x8& pa0, bf16x8& pa1, bf16x8& pa2, bf16x8& pa3) {
; #pragma unroll
;   for (int r = 0; r < 16; ++r) p1[r] = __builtin_amdgcn_exp2f(p1[r]);
; __device__ __forceinline__ void b3_map(f32x16 (&o0)[4], f32x16 (&o1)[4], const AGAS bf16* __restrict__ Qb, const AGAS bf16* __restrict__ Kh, const AGAS bf16* __restrict__ V0h, const AGAS bf16* __restrict__ V1h, int NT, Mod M, ALAS char* lds) {
;     ...
;     if (__any(alpha < 1.f)) { if (hi == 0) al_l[r32] = alpha; asm volatile("s_waitcnt lgkmcnt(0)" ::: "memory");
; #pragma unroll
;       for (int r = 0; r < 16; ++r) { const float al = al_l[crow(r, hi)];
; #pragma unroll
;         for (int d = 0; d < 4; ++d) { o0[d][r] *= al; o1[d][r] *= al; } } }
	s_and_saveexec_b64 s[18:19], s[6:7]
	ds_write_b32 v218, v145 offset:128
	s_or_b64 exec, exec, s[18:19]
	s_waitcnt lgkmcnt(0)
	v_add_u32_e32 v128, s81, v196
	ds_read_b128 v[140:143], v128 offset:224
	ds_read_b128 v[136:139], v128 offset:192
	ds_read_b128 v[132:135], v128 offset:160
	ds_read_b128 v[128:131], v128 offset:128
	s_waitcnt lgkmcnt(0)
	v_pk_mul_f32 v[124:125], v[124:125], v[140:141]
	v_pk_mul_f32 v[120:121], v[120:121], v[136:137]
	v_pk_mul_f32 v[116:117], v[116:117], v[132:133]
	v_pk_mul_f32 v[126:127], v[126:127], v[142:143]
	v_pk_mul_f32 v[122:123], v[122:123], v[138:139]
	v_pk_mul_f32 v[118:119], v[118:119], v[134:135]
	v_pk_mul_f32 v[114:115], v[114:115], v[130:131]
	v_pk_mul_f32 v[112:113], v[112:113], v[128:129]
	v_pk_mul_f32 v[108:109], v[108:109], v[140:141]
	v_pk_mul_f32 v[104:105], v[104:105], v[136:137]
	v_pk_mul_f32 v[100:101], v[100:101], v[132:133]
	v_pk_mul_f32 v[110:111], v[110:111], v[142:143]
	v_pk_mul_f32 v[106:107], v[106:107], v[138:139]
	v_pk_mul_f32 v[102:103], v[102:103], v[134:135]
	v_pk_mul_f32 v[98:99], v[98:99], v[130:131]
	v_pk_mul_f32 v[96:97], v[96:97], v[128:129]
	v_pk_mul_f32 v[92:93], v[92:93], v[140:141]
	v_pk_mul_f32 v[88:89], v[88:89], v[136:137]
	v_pk_mul_f32 v[84:85], v[84:85], v[132:133]
	v_pk_mul_f32 v[94:95], v[94:95], v[142:143]
	v_pk_mul_f32 v[90:91], v[90:91], v[138:139]
	v_pk_mul_f32 v[86:87], v[86:87], v[134:135]
	v_pk_mul_f32 v[82:83], v[82:83], v[130:131]
	v_pk_mul_f32 v[80:81], v[80:81], v[128:129]
	v_pk_mul_f32 v[44:45], v[44:45], v[140:141]
	v_pk_mul_f32 v[40:41], v[40:41], v[136:137]
	v_pk_mul_f32 v[36:37], v[36:37], v[132:133]
	v_pk_mul_f32 v[46:47], v[46:47], v[142:143]
	v_pk_mul_f32 v[42:43], v[42:43], v[138:139]
	v_pk_mul_f32 v[38:39], v[38:39], v[134:135]
	v_pk_mul_f32 v[34:35], v[34:35], v[130:131]
	v_pk_mul_f32 v[32:33], v[32:33], v[128:129]
	v_pk_mul_f32 v[76:77], v[76:77], v[140:141]
	v_pk_mul_f32 v[72:73], v[72:73], v[136:137]
	v_pk_mul_f32 v[68:69], v[68:69], v[132:133]
	v_pk_mul_f32 v[78:79], v[78:79], v[142:143]
	v_pk_mul_f32 v[74:75], v[74:75], v[138:139]
	v_pk_mul_f32 v[70:71], v[70:71], v[134:135]
	v_pk_mul_f32 v[66:67], v[66:67], v[130:131]
	v_pk_mul_f32 v[64:65], v[64:65], v[128:129]
	v_pk_mul_f32 v[28:29], v[28:29], v[140:141]
	v_pk_mul_f32 v[24:25], v[24:25], v[136:137]
	v_pk_mul_f32 v[20:21], v[20:21], v[132:133]
	v_pk_mul_f32 v[30:31], v[30:31], v[142:143]
	v_pk_mul_f32 v[26:27], v[26:27], v[138:139]
	v_pk_mul_f32 v[22:23], v[22:23], v[134:135]
	v_pk_mul_f32 v[18:19], v[18:19], v[130:131]
	v_pk_mul_f32 v[16:17], v[16:17], v[128:129]
	v_pk_mul_f32 v[60:61], v[60:61], v[140:141]
	v_pk_mul_f32 v[56:57], v[56:57], v[136:137]
	v_pk_mul_f32 v[52:53], v[52:53], v[132:133]
	v_pk_mul_f32 v[62:63], v[62:63], v[142:143]
	v_pk_mul_f32 v[58:59], v[58:59], v[138:139]
	v_pk_mul_f32 v[54:55], v[54:55], v[134:135]
	v_pk_mul_f32 v[50:51], v[50:51], v[130:131]
	v_pk_mul_f32 v[48:49], v[48:49], v[128:129]
	v_pk_mul_f32 v[12:13], v[12:13], v[140:141]
	v_pk_mul_f32 v[8:9], v[8:9], v[136:137]
	v_pk_mul_f32 v[4:5], v[4:5], v[132:133]
	v_pk_mul_f32 v[14:15], v[14:15], v[142:143]
	v_pk_mul_f32 v[10:11], v[10:11], v[138:139]
	v_pk_mul_f32 v[6:7], v[6:7], v[134:135]
	v_pk_mul_f32 v[2:3], v[2:3], v[130:131]
	v_pk_mul_f32 v[0:1], v[0:1], v[128:129]
.LBB0_1009:
	v_cndmask_b32_e64 v228, v247, v228, s[8:9]
	v_mul_f32_e32 v128, 0xbe0293ee, v228
	v_fmamk_f32 v129, v231, 0x3e0293ee, v128
	v_fmamk_f32 v130, v232, 0x3e0293ee, v128
	v_exp_f32_e32 v129, v129
	v_fmamk_f32 v131, v233, 0x3e0293ee, v128
	v_exp_f32_e32 v130, v130
	v_fmamk_f32 v132, v234, 0x3e0293ee, v128
	v_exp_f32_e32 v131, v131
	v_fmamk_f32 v133, v235, 0x3e0293ee, v128
	v_fmamk_f32 v134, v236, 0x3e0293ee, v128
	v_fmamk_f32 v135, v237, 0x3e0293ee, v128
	v_fmamk_f32 v136, v238, 0x3e0293ee, v128
	v_fmamk_f32 v137, v239, 0x3e0293ee, v128
	v_fmamk_f32 v138, v240, 0x3e0293ee, v128
	v_fmamk_f32 v139, v241, 0x3e0293ee, v128
	v_fmamk_f32 v140, v242, 0x3e0293ee, v128
	v_fmamk_f32 v141, v243, 0x3e0293ee, v128
	v_fmamk_f32 v142, v244, 0x3e0293ee, v128
	v_fmamk_f32 v143, v245, 0x3e0293ee, v128
	v_fmamk_f32 v231, v246, 0x3e0293ee, v128
	v_fmamk_f32 v144, v144, 0x3e0293ee, v128
	v_fmamk_f32 v230, v230, 0x3e0293ee, v128
	v_fmamk_f32 v146, v146, 0x3e0293ee, v128
	v_fmamk_f32 v147, v147, 0x3e0293ee, v128
	v_fmamk_f32 v148, v148, 0x3e0293ee, v128
	v_fmamk_f32 v149, v149, 0x3e0293ee, v128
	v_fmamk_f32 v150, v150, 0x3e0293ee, v128
	v_fmamk_f32 v151, v151, 0x3e0293ee, v128
	v_fmamk_f32 v152, v152, 0x3e0293ee, v128
	v_fmamk_f32 v153, v153, 0x3e0293ee, v128
	v_fmamk_f32 v154, v154, 0x3e0293ee, v128
	v_fmamk_f32 v155, v155, 0x3e0293ee, v128
	v_fmamk_f32 v156, v156, 0x3e0293ee, v128
	v_fmamk_f32 v157, v157, 0x3e0293ee, v128
	v_fmamk_f32 v158, v158, 0x3e0293ee, v128
	v_fmac_f32_e32 v128, 0x3e0293ee, v159
	v_exp_f32_e32 v132, v132
	v_exp_f32_e32 v133, v133
	v_exp_f32_e32 v236, v128
	v_add_f32_e32 v128, 0, v129
	v_exp_f32_e32 v134, v134
	v_add_f32_e32 v128, v130, v128
	v_exp_f32_e32 v135, v135
	v_add_f32_e32 v128, v131, v128
	v_exp_f32_e32 v136, v136
	v_add_f32_e32 v128, v132, v128
	v_exp_f32_e32 v137, v137
	v_add_f32_e32 v128, v133, v128
	v_exp_f32_e32 v138, v138
	v_add_f32_e32 v128, v134, v128
	v_exp_f32_e32 v139, v139
	v_add_f32_e32 v128, v135, v128
	v_exp_f32_e32 v159, v140
	v_add_f32_e32 v128, v136, v128
	v_exp_f32_e32 v232, v141
	v_add_f32_e32 v128, v137, v128
	v_exp_f32_e32 v233, v142
	v_add_f32_e32 v128, v138, v128
	v_exp_f32_e32 v234, v143
	v_add_f32_e32 v128, v139, v128
	v_exp_f32_e32 v231, v231
	v_add_f32_e32 v128, v159, v128
	v_exp_f32_e32 v235, v144
	v_add_f32_e32 v128, v232, v128
	v_exp_f32_e32 v230, v230
	v_add_f32_e32 v128, v233, v128
; __device__ __forceinline__ void finishSM(f32x16& p0, f32x16& p1, float alpha, float& l_reg, bf16x8& pa0, bf16x8& pa1, bf16x8& pa2, bf16x8& pa3) {
; #pragma unroll
;   for (int r = 0; r < 16; ++r) p1[r] = __builtin_amdgcn_exp2f(p1[r]);
;   float ps = 0;
; #pragma unroll
;   for (int r = 0; r < 16; ++r) ps += p0[r];
; #pragma unroll
;   for (int r = 0; r < 16; ++r) ps += p1[r];
;   { auto rr = __builtin_amdgcn_permlane32_swap(__float_as_uint(ps), __float_as_uint(ps), false, false);
;     ps = __uint_as_float(rr[0]) + __uint_as_float(rr[1]); }
;   l_reg = l_reg * alpha + ps;
;     ...
;   PK4(p0, 0, pa0); PK4(p0, 8, pa1); PK4(p1, 0, pa2); PK4(p1, 8, pa3);
	v_exp_f32_e32 v146, v146
	v_add_f32_e32 v128, v234, v128
	v_exp_f32_e32 v147, v147
	v_add_f32_e32 v128, v231, v128
	v_exp_f32_e32 v148, v148
	v_add_f32_e32 v128, v235, v128
	v_exp_f32_e32 v149, v149
	v_add_f32_e32 v128, v230, v128
	v_exp_f32_e32 v150, v150
	v_add_f32_e32 v128, v146, v128
	v_exp_f32_e32 v151, v151
	v_add_f32_e32 v128, v147, v128
	v_exp_f32_e32 v152, v152
	v_add_f32_e32 v128, v148, v128
	v_exp_f32_e32 v153, v153
	v_add_f32_e32 v128, v149, v128
	v_exp_f32_e32 v154, v154
	v_add_f32_e32 v128, v150, v128
	v_exp_f32_e32 v155, v155
	v_add_f32_e32 v128, v151, v128
	v_exp_f32_e32 v156, v156
	v_add_f32_e32 v128, v152, v128
	v_exp_f32_e32 v157, v157
	v_add_f32_e32 v128, v153, v128
	v_exp_f32_e32 v158, v158
	v_add_f32_e32 v128, v154, v128
	v_add_f32_e32 v128, v155, v128
	v_add_f32_e32 v128, v156, v128
	v_add_f32_e32 v128, v157, v128
	s_sub_i32 s46, s46, s58
	s_xor_b64 s[8:9], s[58:59], -1
	v_add_f32_e32 v128, v158, v128
	v_add_f32_e32 v128, v236, v128
	v_mov_b32_e32 v140, v128
	s_nop 1
	v_permlane32_swap_b32_e32 v128, v140
	v_add_f32_e32 v144, v128, v140
	v_cvt_pk_bf16_f32 v140, v129, v130
	v_cvt_pk_bf16_f32 v141, v131, v132
	v_cvt_pk_bf16_f32 v142, v133, v134
	v_cvt_pk_bf16_f32 v143, v135, v136
	v_cvt_pk_bf16_f32 v132, v137, v138
	v_cvt_pk_bf16_f32 v133, v139, v159
	v_cvt_pk_bf16_f32 v134, v232, v233
	v_cvt_pk_bf16_f32 v135, v234, v231
	v_cvt_pk_bf16_f32 v128, v235, v230
	v_cvt_pk_bf16_f32 v129, v146, v147
	v_cvt_pk_bf16_f32 v130, v148, v149
	v_cvt_pk_bf16_f32 v131, v150, v151
	v_cvt_pk_bf16_f32 v136, v152, v153
	v_cvt_pk_bf16_f32 v137, v154, v155
	v_cvt_pk_bf16_f32 v138, v156, v157
	v_cvt_pk_bf16_f32 v139, v158, v236
	s_waitcnt lgkmcnt(0)
	v_fmac_f32_e32 v144, v229, v145
	v_lshl_add_u32 v145, s49, 15, v227
	ds_read_b64_tr_b16 v[146:147], v145 offset:0
	ds_read_b64_tr_b16 v[148:149], v145 offset:0x800
	ds_read_b64_tr_b16 v[150:151], v145 offset:0x1000
	v_permlane32_swap_b32_e32 v140, v142
	v_permlane32_swap_b32_e32 v141, v143
	ds_read_b64_tr_b16 v[152:153], v145 offset:0x1800
	ds_read_b64_tr_b16 v[154:155], v145 offset:0x2000
	ds_read_b64_tr_b16 v[156:157], v145 offset:0x2800
	ds_read_b64_tr_b16 v[230:231], v145 offset:0x3000
	ds_read_b64_tr_b16 v[232:233], v145 offset:0x3800
	v_permlane32_swap_b32_e32 v132, v134
	s_waitcnt lgkmcnt(4)
	v_permlane32_swap_b32_e32 v133, v135
	v_mfma_f32_32x32x16_bf16 v[112:127], v[140:143], v[146:149], v[112:127]
	v_permlane32_swap_b32_e32 v128, v130
	v_permlane32_swap_b32_e32 v129, v131
	ds_read_b64_tr_b16 v[146:147], v145 offset:0x200
	ds_read_b64_tr_b16 v[148:149], v145 offset:0xa00
	v_permlane32_swap_b32_e32 v136, v138
	v_mfma_f32_32x32x16_bf16 v[112:127], v[132:135], v[150:153], v[112:127]
	ds_read_b64_tr_b16 v[150:151], v145 offset:0x1200
	ds_read_b64_tr_b16 v[152:153], v145 offset:0x1a00
	s_waitcnt lgkmcnt(4)
	v_permlane32_swap_b32_e32 v137, v139
	v_add_u32_e32 v158, 0x4000, v145
	s_add_i32 s97, s97, s8
	v_mfma_f32_32x32x16_bf16 v[112:127], v[128:131], v[154:157], v[112:127]
	ds_read_b64_tr_b16 v[154:155], v145 offset:0x2200
	ds_read_b64_tr_b16 v[156:157], v145 offset:0x2a00
	s_xor_b64 s[42:43], s[42:43], -1
	s_cmp_eq_u32 s4, 32
	v_mfma_f32_32x32x16_bf16 v[112:127], v[136:139], v[230:233], v[112:127]
	ds_read_b64_tr_b16 v[230:231], v145 offset:0x3200
	ds_read_b64_tr_b16 v[232:233], v145 offset:0x3a00
	s_waitcnt lgkmcnt(4)
	s_nop 0
	v_mfma_f32_32x32x16_bf16 v[80:95], v[140:143], v[146:149], v[80:95]
	ds_read_b64_tr_b16 v[146:147], v145 offset:0x400
	ds_read_b64_tr_b16 v[148:149], v145 offset:0xc00
	v_mfma_f32_32x32x16_bf16 v[80:95], v[132:135], v[150:153], v[80:95]
	ds_read_b64_tr_b16 v[150:151], v145 offset:0x1400
	ds_read_b64_tr_b16 v[152:153], v145 offset:0x1c00
	s_waitcnt lgkmcnt(4)
	s_nop 0
	v_mfma_f32_32x32x16_bf16 v[80:95], v[128:131], v[154:157], v[80:95]
	ds_read_b64_tr_b16 v[154:155], v145 offset:0x2400
	ds_read_b64_tr_b16 v[156:157], v145 offset:0x2c00
	v_mfma_f32_32x32x16_bf16 v[80:95], v[136:139], v[230:233], v[80:95]
	ds_read_b64_tr_b16 v[230:231], v145 offset:0x3400
	ds_read_b64_tr_b16 v[232:233], v145 offset:0x3c00
	s_waitcnt lgkmcnt(4)
; #define PVR(S, VB, D0, K0) do { S##l0 = tr_read<v_rd_off(D0, K0, 0)>(VB); S##h0 = tr_read<v_rd_off(D0, K0, 1)>(VB); S##l1 = tr_read<v_rd_off(D0, (K0) + 1, 0)>(VB); S##h1 = tr_read<v_rd_off(D0, (K0) + 1, 1)>(VB); } while (0)
; #define PVW(S, N) asm volatile("s_waitcnt lgkmcnt(" #N ")" : "+v"(S##l0), "+v"(S##h0), "+v"(S##l1), "+v"(S##h1) :: "memory")
; #define PVM(O, S, PA, PB) do { O = __builtin_amdgcn_mfma_f32_32x32x16_bf16(PA, PVK(S##l0, S##h0), O, 0, 0, 0); O = __builtin_amdgcn_mfma_f32_32x32x16_bf16(PB, PVK(S##l1, S##h1), O, 0, 0, 0); } while (0)
; __device__ __forceinline__ void pv_256(f32x16* o0, f32x16* o1, int v0, int v1, bf16x8 pa0, bf16x8 pa1, bf16x8 pa2, bf16x8 pa3) {
;   s16x4 Al0, Ah0, Al1, Ah1, Bl0, Bh0, Bl1, Bh1;
;   PVR(A, v0, 0, 0); PVR(B, v0, 0, 2);
;   PVW(A, 4); PVM(o0[0], A, pa0, pa1); PVR(A, v0, 1, 0);
;   PVW(B, 4); PVM(o0[0], B, pa2, pa3); PVR(B, v0, 1, 2);
;   PVW(A, 4); PVM(o0[1], A, pa0, pa1); PVR(A, v0, 2, 0);
;   PVW(B, 4); PVM(o0[1], B, pa2, pa3); PVR(B, v0, 2, 2);
;   PVW(A, 4); PVM(o0[2], A, pa0, pa1); PVR(A, v0, 3, 0);
;   PVW(B, 4); PVM(o0[2], B, pa2, pa3); PVR(B, v0, 3, 2);
;   PVW(A, 4); PVM(o0[3], A, pa0, pa1); PVR(A, v1, 0, 0);
;   PVW(B, 4); PVM(o0[3], B, pa2, pa3); PVR(B, v1, 0, 2);
;   PVW(A, 4); PVM(o1[0], A, pa0, pa1); PVR(A, v1, 1, 0);
;   PVW(B, 4); PVM(o1[0], B, pa2, pa3); PVR(B, v1, 1, 2);
;   PVW(A, 4); PVM(o1[1], A, pa0, pa1); PVR(A, v1, 2, 0);
;   PVW(B, 4); PVM(o1[1], B, pa2, pa3); PVR(B, v1, 2, 2);
;   PVW(A, 4); PVM(o1[2], A, pa0, pa1); PVR(A, v1, 3, 0);
;   PVW(B, 4); PVM(o1[2], B, pa2, pa3); PVR(B, v1, 3, 2);
;   PVW(A, 4); PVM(o1[3], A, pa0, pa1);
;   PVW(B, 0); PVM(o1[3], B, pa2, pa3);
; }
	s_nop 0
	v_mfma_f32_32x32x16_bf16 v[64:79], v[140:143], v[146:149], v[64:79]
	ds_read_b64_tr_b16 v[146:147], v145 offset:0x600
	ds_read_b64_tr_b16 v[148:149], v145 offset:0xe00
	v_mfma_f32_32x32x16_bf16 v[64:79], v[132:135], v[150:153], v[64:79]
	ds_read_b64_tr_b16 v[150:151], v145 offset:0x1600
	ds_read_b64_tr_b16 v[152:153], v145 offset:0x1e00
	s_waitcnt lgkmcnt(4)
	s_nop 0
	v_mfma_f32_32x32x16_bf16 v[64:79], v[128:131], v[154:157], v[64:79]
	ds_read_b64_tr_b16 v[154:155], v145 offset:0x2600
	ds_read_b64_tr_b16 v[156:157], v145 offset:0x2e00
	v_mfma_f32_32x32x16_bf16 v[64:79], v[136:139], v[230:233], v[64:79]
	ds_read_b64_tr_b16 v[230:231], v145 offset:0x3600
	ds_read_b64_tr_b16 v[232:233], v145 offset:0x3e00
	s_waitcnt lgkmcnt(4)
	s_nop 0
	v_mfma_f32_32x32x16_bf16 v[48:63], v[140:143], v[146:149], v[48:63]
	ds_read_b64_tr_b16 v[146:147], v158 offset:0
	ds_read_b64_tr_b16 v[148:149], v158 offset:0x800
	v_mfma_f32_32x32x16_bf16 v[48:63], v[132:135], v[150:153], v[48:63]
	ds_read_b64_tr_b16 v[150:151], v158 offset:0x1000
	ds_read_b64_tr_b16 v[152:153], v158 offset:0x1800
	s_waitcnt lgkmcnt(4)
	s_nop 0
	v_mfma_f32_32x32x16_bf16 v[48:63], v[128:131], v[154:157], v[48:63]
	ds_read_b64_tr_b16 v[154:155], v158 offset:0x2000
	ds_read_b64_tr_b16 v[156:157], v158 offset:0x2800
	v_mfma_f32_32x32x16_bf16 v[48:63], v[136:139], v[230:233], v[48:63]
	ds_read_b64_tr_b16 v[230:231], v158 offset:0x3000
	ds_read_b64_tr_b16 v[232:233], v158 offset:0x3800
	s_waitcnt lgkmcnt(4)
	s_nop 0
	v_mfma_f32_32x32x16_bf16 v[96:111], v[140:143], v[146:149], v[96:111]
	ds_read_b64_tr_b16 v[146:147], v158 offset:0x200
	ds_read_b64_tr_b16 v[148:149], v158 offset:0xa00
	v_mfma_f32_32x32x16_bf16 v[96:111], v[132:135], v[150:153], v[96:111]
	ds_read_b64_tr_b16 v[150:151], v158 offset:0x1200
	ds_read_b64_tr_b16 v[152:153], v158 offset:0x1a00
	s_waitcnt lgkmcnt(4)
	s_nop 0
	v_mfma_f32_32x32x16_bf16 v[96:111], v[128:131], v[154:157], v[96:111]
	ds_read_b64_tr_b16 v[154:155], v158 offset:0x2200
	ds_read_b64_tr_b16 v[156:157], v158 offset:0x2a00
	v_mfma_f32_32x32x16_bf16 v[96:111], v[136:139], v[230:233], v[96:111]
	ds_read_b64_tr_b16 v[230:231], v158 offset:0x3200
	ds_read_b64_tr_b16 v[232:233], v158 offset:0x3a00
	s_waitcnt lgkmcnt(4)
	s_nop 0
	v_mfma_f32_32x32x16_bf16 v[32:47], v[140:143], v[146:149], v[32:47]
	ds_read_b64_tr_b16 v[146:147], v158 offset:0x400
	ds_read_b64_tr_b16 v[148:149], v158 offset:0xc00
	v_mfma_f32_32x32x16_bf16 v[32:47], v[132:135], v[150:153], v[32:47]
	ds_read_b64_tr_b16 v[150:151], v158 offset:0x1400
	ds_read_b64_tr_b16 v[152:153], v158 offset:0x1c00
	s_waitcnt lgkmcnt(4)
	s_nop 0
	v_mfma_f32_32x32x16_bf16 v[32:47], v[128:131], v[154:157], v[32:47]
	ds_read_b64_tr_b16 v[154:155], v158 offset:0x2400
	ds_read_b64_tr_b16 v[156:157], v158 offset:0x2c00
	v_mfma_f32_32x32x16_bf16 v[32:47], v[136:139], v[230:233], v[32:47]
	ds_read_b64_tr_b16 v[230:231], v158 offset:0x3400
	ds_read_b64_tr_b16 v[232:233], v158 offset:0x3c00
	s_waitcnt lgkmcnt(4)
	s_nop 0
	v_mfma_f32_32x32x16_bf16 v[16:31], v[140:143], v[146:149], v[16:31]
	ds_read_b64_tr_b16 v[146:147], v158 offset:0x600
	ds_read_b64_tr_b16 v[148:149], v158 offset:0xe00
	v_mfma_f32_32x32x16_bf16 v[16:31], v[132:135], v[150:153], v[16:31]
	ds_read_b64_tr_b16 v[150:151], v158 offset:0x1600
	ds_read_b64_tr_b16 v[152:153], v158 offset:0x1e00
	s_waitcnt lgkmcnt(4)
	s_nop 0
	v_mfma_f32_32x32x16_bf16 v[16:31], v[128:131], v[154:157], v[16:31]
	ds_read_b64_tr_b16 v[154:155], v158 offset:0x2600
	ds_read_b64_tr_b16 v[156:157], v158 offset:0x2e00
	v_mfma_f32_32x32x16_bf16 v[16:31], v[136:139], v[230:233], v[16:31]
	ds_read_b64_tr_b16 v[230:231], v158 offset:0x3600
	ds_read_b64_tr_b16 v[232:233], v158 offset:0x3e00
	s_waitcnt lgkmcnt(4)
	s_nop 0
	s_waitcnt lgkmcnt(0)
	v_mfma_f32_32x32x16_bf16 v[0:15], v[140:143], v[146:149], v[0:15]
	v_mfma_f32_32x32x16_bf16 v[0:15], v[132:135], v[150:153], v[0:15]
	v_mfma_f32_32x32x16_bf16 v[0:15], v[128:131], v[154:157], v[0:15]
	v_mfma_f32_32x32x16_bf16 v[0:15], v[136:139], v[230:233], v[0:15]
	s_cbranch_scc1 .LBB0_1011
	s_mov_b32 s18, s48
	s_mov_b32 s19, s4
	v_mov_b32_e32 v229, v144
	s_branch .LBB0_990

; #define ALAS __attribute__((address_space(3)))
; __device__ __forceinline__ void qkt(f32x16& p0, f32x16& p1, const ALAS char* Ks, const bf16x8* qr, int r32, int hi) {
;   p0 = f32x16{}; p1 = f32x16{};
; #pragma unroll
;   for (int d0 = 0; d0 < 8; ++d0) { int cb = (d0 * 16 + hi * 8) * 2;
;     bf16x8 b0 = *(const ALAS bf16x8*)(Ks + KSWZ(r32, cb));
;     bf16x8 b1 = *(const ALAS bf16x8*)(Ks + KSWZ(32 + r32, cb));
;     p0 = __builtin_amdgcn_mfma_f32_32x32x16_bf16(b0, qr[d0], p0, 0, 0, 0);
;     p1 = __builtin_amdgcn_mfma_f32_32x32x16_bf16(b1, qr[d0], p1, 0, 0, 0); }
; template <int MODE> __device__ __forceinline__ void modify2(f32x16& p0, f32x16& p1, const Mod& M, int j, float& boff) {
;   const float dq = M.a0 - (float)(j * 64); const float nsl = -M.a1;
; #pragma unroll
;   for (int r = 0; r < 16; ++r) { const float cr = (float)((r & 3) + 8 * (r >> 2));
;     p0[r] = fmaf(fabsf(dq - cr), nsl, p0[r]); p1[r] = fmaf(fabsf(dq - (cr + 32.f)), nsl, p1[r]); }
;   boff = 0.f;
; }
.LBB0_1613:
	s_and_b32 s61, s79, 1
	v_mov_b32_e32 v128, v215
	v_mov_b32_e32 v129, v214
	s_lshl_b32 s8, s61, 14
	s_add_i32 s8, s8, 0
	s_add_i32 s8, s8, 0x10000
	v_lshlrev_b32_e32 v242, 4, v128
	v_lshlrev_b32_e32 v243, 4, v129
	v_and_b32_e32 v243, 0x70, v243
	v_lshl_add_u32 v241, v129, 8, s8
	v_xad_u32 v244, v242, v243, v241
	v_add_u32_e32 v240, 32, v242
	v_xad_u32 v245, v240, v243, v241
	v_add_u32_e32 v240, 64, v242
	v_xad_u32 v246, v240, v243, v241
	v_add_u32_e32 v240, 0x60, v242
	v_xad_u32 v247, v240, v243, v241
	s_lshl_b32 s8, s80, 6
	ds_read_b128 v[148:151], v244
	ds_read_b128 v[152:155], v245
	ds_read_b128 v[156:159], v246
	ds_read_b128 v[230:233], v247
	ds_read_b128 v[234:237], v244 offset:128
	ds_read_b128 v[238:241], v245 offset:128
	s_waitcnt lgkmcnt(5)
	v_mfma_f32_32x32x16_bf16 v[128:143], v[148:151], v[160:163], 0
	ds_read_b128 v[148:151], v246 offset:128
	s_waitcnt lgkmcnt(5)
	v_mfma_f32_32x32x16_bf16 v[128:143], v[152:155], v[164:167], v[128:143]
	ds_read_b128 v[152:155], v247 offset:128
	s_waitcnt lgkmcnt(5)
	v_mfma_f32_32x32x16_bf16 v[128:143], v[156:159], v[168:171], v[128:143]
	ds_read_b128 v[144:147], v244 offset:8192
	s_waitcnt lgkmcnt(5)
	v_mfma_f32_32x32x16_bf16 v[128:143], v[230:233], v[172:175], v[128:143]
	ds_read_b128 v[230:233], v245 offset:8192
	s_waitcnt lgkmcnt(5)
	v_mfma_f32_32x32x16_bf16 v[128:143], v[234:237], v[176:179], v[128:143]
	ds_read_b128 v[234:237], v246 offset:8192
	s_waitcnt lgkmcnt(5)
	v_mfma_f32_32x32x16_bf16 v[128:143], v[238:241], v[180:183], v[128:143]
	ds_read_b128 v[238:241], v247 offset:8192
	s_waitcnt lgkmcnt(5)
	v_mfma_f32_32x32x16_bf16 v[128:143], v[148:151], v[184:187], v[128:143]
	s_waitcnt lgkmcnt(4)
	v_mfma_f32_32x32x16_bf16 v[128:143], v[152:155], v[188:191], v[128:143]
	s_waitcnt lgkmcnt(3)
	v_mfma_f32_32x32x16_bf16 v[144:159], v[144:147], v[160:163], 0
	s_waitcnt lgkmcnt(2)
	v_mfma_f32_32x32x16_bf16 v[144:159], v[230:233], v[164:167], v[144:159]
	ds_read_b128 v[230:233], v244 offset:8320
	s_waitcnt lgkmcnt(2)
	v_mfma_f32_32x32x16_bf16 v[144:159], v[234:237], v[168:171], v[144:159]
	ds_read_b128 v[234:237], v245 offset:8320
	s_waitcnt lgkmcnt(2)
	v_mfma_f32_32x32x16_bf16 v[144:159], v[238:241], v[172:175], v[144:159]
	ds_read_b128 v[238:241], v246 offset:8320
	s_waitcnt lgkmcnt(2)
	v_mfma_f32_32x32x16_bf16 v[144:159], v[230:233], v[176:179], v[144:159]
	ds_read_b128 v[230:233], v247 offset:8320
	s_waitcnt lgkmcnt(2)
	v_mfma_f32_32x32x16_bf16 v[144:159], v[234:237], v[180:183], v[144:159]
	s_waitcnt lgkmcnt(1)
	v_mfma_f32_32x32x16_bf16 v[144:159], v[238:241], v[184:187], v[144:159]
	s_waitcnt lgkmcnt(0)
	v_mfma_f32_32x32x16_bf16 v[144:159], v[230:233], v[188:191], v[144:159]
	v_cvt_f32_i32_e32 v230, s8
	v_mov_b32_e32 v231, v212
	s_nop 0
	v_sub_f32_e32 v247, v231, v230
	v_fma_f32 v231, |v247|, v213, v128
	v_add_f32_e32 v128, -1.0, v247
	v_fma_f32 v232, |v128|, v213, v129
	v_add_f32_e32 v128, -2.0, v247
	v_fma_f32 v233, |v128|, v213, v130
	v_add_f32_e32 v128, 0xc0400000, v247
	v_fma_f32 v234, |v128|, v213, v131
	v_add_f32_e32 v128, 0xc1000000, v247
	v_fma_f32 v235, |v128|, v213, v132
	v_add_f32_e32 v128, 0xc1100000, v247
	v_fma_f32 v236, |v128|, v213, v133
	v_add_f32_e32 v128, 0xc1200000, v247
	v_fma_f32 v237, |v128|, v213, v134
	v_add_f32_e32 v128, 0xc1300000, v247
	v_fma_f32 v238, |v128|, v213, v135
	v_add_f32_e32 v128, 0xc1800000, v247
	v_fma_f32 v239, |v128|, v213, v136
	v_add_f32_e32 v128, 0xc1880000, v247
	v_fma_f32 v240, |v128|, v213, v137
	v_add_f32_e32 v128, 0xc1900000, v247
	v_fma_f32 v241, |v128|, v213, v138
	v_add_f32_e32 v128, 0xc1980000, v247
	v_fma_f32 v242, |v128|, v213, v139
	v_add_f32_e32 v128, 0xc1c00000, v247
	v_fma_f32 v243, |v128|, v213, v140
	v_add_f32_e32 v128, 0xc1c80000, v247
	v_fma_f32 v244, |v128|, v213, v141
	v_add_f32_e32 v128, 0xc1d00000, v247
	v_fma_f32 v245, |v128|, v213, v142
	v_add_f32_e32 v128, 0xc1d80000, v247
	v_fma_f32 v246, |v128|, v213, v143
	v_add_f32_e32 v128, 0xc2000000, v247
	v_fma_f32 v144, |v128|, v213, v144
	v_add_f32_e32 v128, 0xc2040000, v247
	v_fma_f32 v230, |v128|, v213, v145
	v_add_f32_e32 v128, 0xc2080000, v247
	v_fma_f32 v146, |v128|, v213, v146
	v_add_f32_e32 v128, 0xc20c0000, v247
	v_fma_f32 v147, |v128|, v213, v147
	v_add_f32_e32 v128, 0xc2200000, v247
	v_fma_f32 v148, |v128|, v213, v148
	v_add_f32_e32 v128, 0xc2240000, v247
	v_fma_f32 v149, |v128|, v213, v149
	v_add_f32_e32 v128, 0xc2280000, v247
	v_fma_f32 v150, |v128|, v213, v150
	v_add_f32_e32 v128, 0xc22c0000, v247
	v_fma_f32 v151, |v128|, v213, v151
	v_add_f32_e32 v128, 0xc2400000, v247
	v_fma_f32 v152, |v128|, v213, v152
	v_add_f32_e32 v128, 0xc2440000, v247
	v_fma_f32 v153, |v128|, v213, v153
	v_add_f32_e32 v128, 0xc2480000, v247
	v_fma_f32 v154, |v128|, v213, v154
	v_add_f32_e32 v128, 0xc24c0000, v247
	v_fma_f32 v155, |v128|, v213, v155
	v_add_f32_e32 v128, 0xc2600000, v247
	v_fma_f32 v156, |v128|, v213, v156
	v_add_f32_e32 v128, 0xc2640000, v247
	v_fma_f32 v157, |v128|, v213, v157
	v_add_f32_e32 v128, 0xc2680000, v247
	v_fma_f32 v158, |v128|, v213, v158
	v_add_f32_e32 v128, 0xc26c0000, v247
	v_fma_f32 v159, |v128|, v213, v159
	v_max_f32_e32 v128, v231, v232
	v_max3_f32 v128, v128, v233, v234
	v_max3_f32 v128, v128, v235, v236
	v_max3_f32 v128, v128, v237, v238
	v_max3_f32 v128, v128, v239, v240
	v_max3_f32 v128, v128, v241, v242
	v_max3_f32 v128, v128, v243, v244
	v_max3_f32 v128, v128, v245, v246
	v_max3_f32 v128, v128, v144, v230
	v_max3_f32 v128, v128, v146, v147
	v_max3_f32 v128, v128, v148, v149
	v_max3_f32 v128, v128, v150, v151
	v_max3_f32 v128, v128, v152, v153
	v_max3_f32 v128, v128, v154, v155
	v_max3_f32 v128, v128, v156, v157
	v_max3_f32 v128, v128, v158, v159
	v_mov_b32_e32 v129, v128
	s_nop 1
	v_permlane32_swap_b32_e32 v128, v129
	v_max_f32_e32 v129, v129, v129
	v_max_f32_e32 v128, v128, v128
	v_max_f32_e32 v128, v128, v129
	v_max_f32_e32 v130, v228, v228
	v_max_f32_e32 v247, v130, v128
	v_sub_f32_e32 v129, v128, v228
	v_sub_f32_e32 v128, v228, v247
	v_mul_f32_e32 v128, 0x3e0293ee, v128
	v_exp_f32_e32 v128, v128
	v_cmp_ge_f32_e32 vcc, s56, v129
	s_cmp_eq_u64 vcc, exec
	s_cselect_b64 s[8:9], -1, 0
	v_cndmask_b32_e64 v145, v128, 1.0, s[8:9]
	s_cbranch_scc1 .LBB0_1617
; __device__ __forceinline__ int crow(int r, int hi) { return (r & 3) + 8 * (r >> 2) + 4 * hi; }
; template <bool OFF>
; __device__ __forceinline__ void partialSM(f32x16& p0, f32x16& p1, float& m_reg, float& mn, float& alpha, float boff) {
;     ...
;   else { mn = fmaxf(m_reg, pmax); alpha = __builtin_amdgcn_exp2f((m_reg - mn) * C); m_reg = mn; }
;   const float mnC = (OFF ? boff - mn : -mn) * C;
; #pragma unroll
;   for (int r = 0; r < 16; ++r) p0[r] = fmaf(p0[r], C, mnC);
; #pragma unroll
;   for (int r = 0; r < 16; ++r) p1[r] = fmaf(p1[r], C, mnC);
; #pragma unroll
;   for (int r = 0; r < 16; ++r) p0[r] = __builtin_amdgcn_exp2f(p0[r]);
; }
; __device__ __forceinline__ void finishSM(f32x16& p0, f32x16& p1, float alpha, float& l_reg, bf16x8& pa0, bf16x8& pa1, bf16x8& pa2, bf16x8& pa3) {
; #pragma unroll
;   for (int r = 0; r < 16; ++r) p1[r] = __builtin_amdgcn_exp2f(p1[r]);
;   float ps = 0;
; #pragma unroll
;   for (int r = 0; r < 16; ++r) ps += p0[r];
; #pragma unroll
;   for (int r = 0; r < 16; ++r) ps += p1[r];
; __device__ __forceinline__ void b3_map(f32x16 (&o0)[4], f32x16 (&o1)[4], const AGAS bf16* __restrict__ Qb, const AGAS bf16* __restrict__ Kh, const AGAS bf16* __restrict__ V0h, const AGAS bf16* __restrict__ V1h, int NT, Mod M, ALAS char* lds) {
;     ...
;     if (__any(alpha < 1.f)) { if (hi == 0) al_l[r32] = alpha; asm volatile("s_waitcnt lgkmcnt(0)" ::: "memory");
; #pragma unroll
;       for (int r = 0; r < 16; ++r) { const float al = al_l[crow(r, hi)];
; #pragma unroll
;         for (int d = 0; d < 4; ++d) { o0[d][r] *= al; o1[d][r] *= al; } } }
	s_and_saveexec_b64 s[64:65], s[4:5]
	ds_write_b32 v218, v145 offset:128
	s_or_b64 exec, exec, s[64:65]
	s_waitcnt lgkmcnt(0)
	v_add_u32_e32 v128, s89, v196
	ds_read_b128 v[140:143], v128 offset:224
	ds_read_b128 v[136:139], v128 offset:192
	ds_read_b128 v[132:135], v128 offset:160
	ds_read_b128 v[128:131], v128 offset:128
	s_waitcnt lgkmcnt(0)
	v_pk_mul_f32 v[124:125], v[124:125], v[140:141]
	v_pk_mul_f32 v[120:121], v[120:121], v[136:137]
	v_pk_mul_f32 v[116:117], v[116:117], v[132:133]
	v_pk_mul_f32 v[126:127], v[126:127], v[142:143]
	v_pk_mul_f32 v[122:123], v[122:123], v[138:139]
	v_pk_mul_f32 v[118:119], v[118:119], v[134:135]
	v_pk_mul_f32 v[114:115], v[114:115], v[130:131]
	v_pk_mul_f32 v[112:113], v[112:113], v[128:129]
	v_pk_mul_f32 v[12:13], v[12:13], v[140:141]
	v_pk_mul_f32 v[8:9], v[8:9], v[136:137]
	v_pk_mul_f32 v[4:5], v[4:5], v[132:133]
	v_pk_mul_f32 v[14:15], v[14:15], v[142:143]
	v_pk_mul_f32 v[10:11], v[10:11], v[138:139]
	v_pk_mul_f32 v[6:7], v[6:7], v[134:135]
	v_pk_mul_f32 v[2:3], v[2:3], v[130:131]
	v_pk_mul_f32 v[0:1], v[0:1], v[128:129]
	v_pk_mul_f32 v[108:109], v[108:109], v[140:141]
	v_pk_mul_f32 v[104:105], v[104:105], v[136:137]
	v_pk_mul_f32 v[100:101], v[100:101], v[132:133]
	v_pk_mul_f32 v[110:111], v[110:111], v[142:143]
	v_pk_mul_f32 v[106:107], v[106:107], v[138:139]
	v_pk_mul_f32 v[102:103], v[102:103], v[134:135]
	v_pk_mul_f32 v[98:99], v[98:99], v[130:131]
	v_pk_mul_f32 v[96:97], v[96:97], v[128:129]
	v_pk_mul_f32 v[60:61], v[60:61], v[140:141]
	v_pk_mul_f32 v[56:57], v[56:57], v[136:137]
	v_pk_mul_f32 v[52:53], v[52:53], v[132:133]
	v_pk_mul_f32 v[62:63], v[62:63], v[142:143]
	v_pk_mul_f32 v[58:59], v[58:59], v[138:139]
	v_pk_mul_f32 v[54:55], v[54:55], v[134:135]
	v_pk_mul_f32 v[50:51], v[50:51], v[130:131]
	v_pk_mul_f32 v[48:49], v[48:49], v[128:129]
	v_pk_mul_f32 v[92:93], v[92:93], v[140:141]
	v_pk_mul_f32 v[88:89], v[88:89], v[136:137]
	v_pk_mul_f32 v[84:85], v[84:85], v[132:133]
	v_pk_mul_f32 v[94:95], v[94:95], v[142:143]
	v_pk_mul_f32 v[90:91], v[90:91], v[138:139]
	v_pk_mul_f32 v[86:87], v[86:87], v[134:135]
	v_pk_mul_f32 v[82:83], v[82:83], v[130:131]
	v_pk_mul_f32 v[80:81], v[80:81], v[128:129]
	v_pk_mul_f32 v[44:45], v[44:45], v[140:141]
	v_pk_mul_f32 v[40:41], v[40:41], v[136:137]
	v_pk_mul_f32 v[36:37], v[36:37], v[132:133]
	v_pk_mul_f32 v[46:47], v[46:47], v[142:143]
	v_pk_mul_f32 v[42:43], v[42:43], v[138:139]
	v_pk_mul_f32 v[38:39], v[38:39], v[134:135]
	v_pk_mul_f32 v[34:35], v[34:35], v[130:131]
	v_pk_mul_f32 v[32:33], v[32:33], v[128:129]
	v_pk_mul_f32 v[76:77], v[76:77], v[140:141]
	v_pk_mul_f32 v[72:73], v[72:73], v[136:137]
	v_pk_mul_f32 v[68:69], v[68:69], v[132:133]
	v_pk_mul_f32 v[78:79], v[78:79], v[142:143]
	v_pk_mul_f32 v[74:75], v[74:75], v[138:139]
	v_pk_mul_f32 v[70:71], v[70:71], v[134:135]
	v_pk_mul_f32 v[66:67], v[66:67], v[130:131]
	v_pk_mul_f32 v[64:65], v[64:65], v[128:129]
	v_pk_mul_f32 v[28:29], v[28:29], v[140:141]
	v_pk_mul_f32 v[24:25], v[24:25], v[136:137]
	v_pk_mul_f32 v[20:21], v[20:21], v[132:133]
	v_pk_mul_f32 v[30:31], v[30:31], v[142:143]
	v_pk_mul_f32 v[26:27], v[26:27], v[138:139]
	v_pk_mul_f32 v[22:23], v[22:23], v[134:135]
	v_pk_mul_f32 v[18:19], v[18:19], v[130:131]
	v_pk_mul_f32 v[16:17], v[16:17], v[128:129]
.LBB0_1617:
	v_cndmask_b32_e64 v228, v247, v228, s[8:9]
	v_mul_f32_e32 v128, 0xbe0293ee, v228
	v_fmamk_f32 v129, v231, 0x3e0293ee, v128
	v_fmamk_f32 v130, v232, 0x3e0293ee, v128
	v_exp_f32_e32 v129, v129
	v_fmamk_f32 v131, v233, 0x3e0293ee, v128
	v_exp_f32_e32 v130, v130
	v_fmamk_f32 v132, v234, 0x3e0293ee, v128
	v_exp_f32_e32 v131, v131
	v_fmamk_f32 v133, v235, 0x3e0293ee, v128
	v_fmamk_f32 v134, v236, 0x3e0293ee, v128
	v_fmamk_f32 v135, v237, 0x3e0293ee, v128
	v_fmamk_f32 v136, v238, 0x3e0293ee, v128
	v_fmamk_f32 v137, v239, 0x3e0293ee, v128
	v_fmamk_f32 v138, v240, 0x3e0293ee, v128
	v_fmamk_f32 v139, v241, 0x3e0293ee, v128
	v_fmamk_f32 v140, v242, 0x3e0293ee, v128
	v_fmamk_f32 v141, v243, 0x3e0293ee, v128
	v_fmamk_f32 v142, v244, 0x3e0293ee, v128
	v_fmamk_f32 v143, v245, 0x3e0293ee, v128
	v_fmamk_f32 v231, v246, 0x3e0293ee, v128
	v_fmamk_f32 v144, v144, 0x3e0293ee, v128
	v_fmamk_f32 v230, v230, 0x3e0293ee, v128
	v_fmamk_f32 v146, v146, 0x3e0293ee, v128
	v_fmamk_f32 v147, v147, 0x3e0293ee, v128
	v_fmamk_f32 v148, v148, 0x3e0293ee, v128
	v_fmamk_f32 v149, v149, 0x3e0293ee, v128
	v_fmamk_f32 v150, v150, 0x3e0293ee, v128
	v_fmamk_f32 v151, v151, 0x3e0293ee, v128
	v_fmamk_f32 v152, v152, 0x3e0293ee, v128
	v_fmamk_f32 v153, v153, 0x3e0293ee, v128
	v_fmamk_f32 v154, v154, 0x3e0293ee, v128
	v_fmamk_f32 v155, v155, 0x3e0293ee, v128
	v_fmamk_f32 v156, v156, 0x3e0293ee, v128
	v_fmamk_f32 v157, v157, 0x3e0293ee, v128
	v_fmamk_f32 v158, v158, 0x3e0293ee, v128
	v_fmac_f32_e32 v128, 0x3e0293ee, v159
	v_exp_f32_e32 v132, v132
	v_exp_f32_e32 v133, v133
	v_exp_f32_e32 v236, v128
	v_add_f32_e32 v128, 0, v129
	v_exp_f32_e32 v134, v134
	v_add_f32_e32 v128, v130, v128
	v_exp_f32_e32 v135, v135
	v_add_f32_e32 v128, v131, v128
	v_exp_f32_e32 v136, v136
	v_add_f32_e32 v128, v132, v128
	v_exp_f32_e32 v137, v137
	v_add_f32_e32 v128, v133, v128
	v_exp_f32_e32 v138, v138
	v_add_f32_e32 v128, v134, v128
	v_exp_f32_e32 v139, v139
	v_add_f32_e32 v128, v135, v128
	v_exp_f32_e32 v159, v140
	v_add_f32_e32 v128, v136, v128
	v_exp_f32_e32 v232, v141
	v_add_f32_e32 v128, v137, v128
	v_exp_f32_e32 v233, v142
	v_add_f32_e32 v128, v138, v128
	v_exp_f32_e32 v234, v143
	v_add_f32_e32 v128, v139, v128
	v_exp_f32_e32 v231, v231
	v_add_f32_e32 v128, v159, v128
	v_exp_f32_e32 v235, v144
	v_add_f32_e32 v128, v232, v128
	v_exp_f32_e32 v230, v230
	v_add_f32_e32 v128, v233, v128
; __device__ __forceinline__ void finishSM(f32x16& p0, f32x16& p1, float alpha, float& l_reg, bf16x8& pa0, bf16x8& pa1, bf16x8& pa2, bf16x8& pa3) {
; #pragma unroll
;   for (int r = 0; r < 16; ++r) p1[r] = __builtin_amdgcn_exp2f(p1[r]);
;   float ps = 0;
; #pragma unroll
;   for (int r = 0; r < 16; ++r) ps += p0[r];
; #pragma unroll
;   for (int r = 0; r < 16; ++r) ps += p1[r];
;   { auto rr = __builtin_amdgcn_permlane32_swap(__float_as_uint(ps), __float_as_uint(ps), false, false);
;     ps = __uint_as_float(rr[0]) + __uint_as_float(rr[1]); }
;   l_reg = l_reg * alpha + ps;
;     ...
;   PK4(p0, 0, pa0); PK4(p0, 8, pa1); PK4(p1, 0, pa2); PK4(p1, 8, pa3);
	v_exp_f32_e32 v146, v146
	v_add_f32_e32 v128, v234, v128
	v_exp_f32_e32 v147, v147
	v_add_f32_e32 v128, v231, v128
	v_exp_f32_e32 v148, v148
	v_add_f32_e32 v128, v235, v128
	v_exp_f32_e32 v149, v149
	v_add_f32_e32 v128, v230, v128
	v_exp_f32_e32 v150, v150
	v_add_f32_e32 v128, v146, v128
	v_exp_f32_e32 v151, v151
	v_add_f32_e32 v128, v147, v128
	v_exp_f32_e32 v152, v152
	v_add_f32_e32 v128, v148, v128
	v_exp_f32_e32 v153, v153
	v_add_f32_e32 v128, v149, v128
	v_exp_f32_e32 v154, v154
	v_add_f32_e32 v128, v150, v128
	v_exp_f32_e32 v155, v155
	v_add_f32_e32 v128, v151, v128
	v_exp_f32_e32 v156, v156
	v_add_f32_e32 v128, v152, v128
	v_exp_f32_e32 v157, v157
	v_add_f32_e32 v128, v153, v128
	v_exp_f32_e32 v158, v158
	v_add_f32_e32 v128, v154, v128
	v_add_f32_e32 v128, v155, v128
	v_add_f32_e32 v128, v156, v128
	v_add_f32_e32 v128, v157, v128
	s_sub_i32 s86, s86, s62
	s_xor_b64 s[8:9], s[62:63], -1
	v_add_f32_e32 v128, v158, v128
	v_add_f32_e32 v128, v236, v128
	v_mov_b32_e32 v140, v128
	s_nop 1
	v_permlane32_swap_b32_e32 v128, v140
	v_add_f32_e32 v144, v128, v140
	v_cvt_pk_bf16_f32 v140, v129, v130
	v_cvt_pk_bf16_f32 v141, v131, v132
	v_cvt_pk_bf16_f32 v142, v133, v134
	v_cvt_pk_bf16_f32 v143, v135, v136
	v_cvt_pk_bf16_f32 v132, v137, v138
	v_cvt_pk_bf16_f32 v133, v139, v159
	v_cvt_pk_bf16_f32 v134, v232, v233
	v_cvt_pk_bf16_f32 v135, v234, v231
	v_cvt_pk_bf16_f32 v128, v235, v230
	v_cvt_pk_bf16_f32 v129, v146, v147
	v_cvt_pk_bf16_f32 v130, v148, v149
	v_cvt_pk_bf16_f32 v131, v150, v151
	v_cvt_pk_bf16_f32 v136, v152, v153
	v_cvt_pk_bf16_f32 v137, v154, v155
	v_cvt_pk_bf16_f32 v138, v156, v157
	v_cvt_pk_bf16_f32 v139, v158, v236
	s_waitcnt lgkmcnt(0)
	v_fmac_f32_e32 v144, v229, v145
	v_lshl_add_u32 v145, s61, 15, v227
	ds_read_b64_tr_b16 v[146:147], v145 offset:0
	ds_read_b64_tr_b16 v[148:149], v145 offset:0x800
	ds_read_b64_tr_b16 v[150:151], v145 offset:0x1000
	v_permlane32_swap_b32_e32 v140, v142
	v_permlane32_swap_b32_e32 v141, v143
	ds_read_b64_tr_b16 v[152:153], v145 offset:0x1800
	ds_read_b64_tr_b16 v[154:155], v145 offset:0x2000
	ds_read_b64_tr_b16 v[156:157], v145 offset:0x2800
	ds_read_b64_tr_b16 v[230:231], v145 offset:0x3000
	ds_read_b64_tr_b16 v[232:233], v145 offset:0x3800
	v_permlane32_swap_b32_e32 v132, v134
	s_waitcnt lgkmcnt(4)
	v_permlane32_swap_b32_e32 v133, v135
	v_mfma_f32_32x32x16_bf16 v[112:127], v[140:143], v[146:149], v[112:127]
	v_permlane32_swap_b32_e32 v128, v130
	v_permlane32_swap_b32_e32 v129, v131
	ds_read_b64_tr_b16 v[146:147], v145 offset:0x200
	ds_read_b64_tr_b16 v[148:149], v145 offset:0xa00
	v_permlane32_swap_b32_e32 v136, v138
	v_mfma_f32_32x32x16_bf16 v[112:127], v[132:135], v[150:153], v[112:127]
	ds_read_b64_tr_b16 v[150:151], v145 offset:0x1200
	ds_read_b64_tr_b16 v[152:153], v145 offset:0x1a00
	s_waitcnt lgkmcnt(4)
	v_permlane32_swap_b32_e32 v137, v139
	v_add_u32_e32 v158, 0x4000, v145
	s_add_i32 s85, s85, s8
	v_mfma_f32_32x32x16_bf16 v[112:127], v[128:131], v[154:157], v[112:127]
	ds_read_b64_tr_b16 v[154:155], v145 offset:0x2200
	ds_read_b64_tr_b16 v[156:157], v145 offset:0x2a00
	s_xor_b64 s[58:59], s[58:59], -1
	s_cmp_eq_u32 s81, 32
	v_mfma_f32_32x32x16_bf16 v[112:127], v[136:139], v[230:233], v[112:127]
	ds_read_b64_tr_b16 v[230:231], v145 offset:0x3200
	ds_read_b64_tr_b16 v[232:233], v145 offset:0x3a00
	s_waitcnt lgkmcnt(4)
	s_nop 0
	v_mfma_f32_32x32x16_bf16 v[96:111], v[140:143], v[146:149], v[96:111]
	ds_read_b64_tr_b16 v[146:147], v145 offset:0x400
	ds_read_b64_tr_b16 v[148:149], v145 offset:0xc00
	v_mfma_f32_32x32x16_bf16 v[96:111], v[132:135], v[150:153], v[96:111]
	ds_read_b64_tr_b16 v[150:151], v145 offset:0x1400
	ds_read_b64_tr_b16 v[152:153], v145 offset:0x1c00
	s_waitcnt lgkmcnt(4)
	s_nop 0
	v_mfma_f32_32x32x16_bf16 v[96:111], v[128:131], v[154:157], v[96:111]
	ds_read_b64_tr_b16 v[154:155], v145 offset:0x2400
	ds_read_b64_tr_b16 v[156:157], v145 offset:0x2c00
	v_mfma_f32_32x32x16_bf16 v[96:111], v[136:139], v[230:233], v[96:111]
	ds_read_b64_tr_b16 v[230:231], v145 offset:0x3400
	ds_read_b64_tr_b16 v[232:233], v145 offset:0x3c00
	s_waitcnt lgkmcnt(4)
; #define PVR(S, VB, D0, K0) do { S##l0 = tr_read<v_rd_off(D0, K0, 0)>(VB); S##h0 = tr_read<v_rd_off(D0, K0, 1)>(VB); S##l1 = tr_read<v_rd_off(D0, (K0) + 1, 0)>(VB); S##h1 = tr_read<v_rd_off(D0, (K0) + 1, 1)>(VB); } while (0)
; #define PVW(S, N) asm volatile("s_waitcnt lgkmcnt(" #N ")" : "+v"(S##l0), "+v"(S##h0), "+v"(S##l1), "+v"(S##h1) :: "memory")
; #define PVM(O, S, PA, PB) do { O = __builtin_amdgcn_mfma_f32_32x32x16_bf16(PA, PVK(S##l0, S##h0), O, 0, 0, 0); O = __builtin_amdgcn_mfma_f32_32x32x16_bf16(PB, PVK(S##l1, S##h1), O, 0, 0, 0); } while (0)
; __device__ __forceinline__ void pv_256(f32x16* o0, f32x16* o1, int v0, int v1, bf16x8 pa0, bf16x8 pa1, bf16x8 pa2, bf16x8 pa3) {
;   s16x4 Al0, Ah0, Al1, Ah1, Bl0, Bh0, Bl1, Bh1;
;   PVR(A, v0, 0, 0); PVR(B, v0, 0, 2);
;   PVW(A, 4); PVM(o0[0], A, pa0, pa1); PVR(A, v0, 1, 0);
;   PVW(B, 4); PVM(o0[0], B, pa2, pa3); PVR(B, v0, 1, 2);
;   PVW(A, 4); PVM(o0[1], A, pa0, pa1); PVR(A, v0, 2, 0);
;   PVW(B, 4); PVM(o0[1], B, pa2, pa3); PVR(B, v0, 2, 2);
;   PVW(A, 4); PVM(o0[2], A, pa0, pa1); PVR(A, v0, 3, 0);
;   PVW(B, 4); PVM(o0[2], B, pa2, pa3); PVR(B, v0, 3, 2);
;   PVW(A, 4); PVM(o0[3], A, pa0, pa1); PVR(A, v1, 0, 0);
;   PVW(B, 4); PVM(o0[3], B, pa2, pa3); PVR(B, v1, 0, 2);
;   PVW(A, 4); PVM(o1[0], A, pa0, pa1); PVR(A, v1, 1, 0);
;   PVW(B, 4); PVM(o1[0], B, pa2, pa3); PVR(B, v1, 1, 2);
;   PVW(A, 4); PVM(o1[1], A, pa0, pa1); PVR(A, v1, 2, 0);
;   PVW(B, 4); PVM(o1[1], B, pa2, pa3); PVR(B, v1, 2, 2);
;   PVW(A, 4); PVM(o1[2], A, pa0, pa1); PVR(A, v1, 3, 0);
;   PVW(B, 4); PVM(o1[2], B, pa2, pa3); PVR(B, v1, 3, 2);
;   PVW(A, 4); PVM(o1[3], A, pa0, pa1);
;   PVW(B, 0); PVM(o1[3], B, pa2, pa3);
; }
	s_nop 0
	v_mfma_f32_32x32x16_bf16 v[80:95], v[140:143], v[146:149], v[80:95]
	ds_read_b64_tr_b16 v[146:147], v145 offset:0x600
	ds_read_b64_tr_b16 v[148:149], v145 offset:0xe00
	v_mfma_f32_32x32x16_bf16 v[80:95], v[132:135], v[150:153], v[80:95]
	ds_read_b64_tr_b16 v[150:151], v145 offset:0x1600
	ds_read_b64_tr_b16 v[152:153], v145 offset:0x1e00
	s_waitcnt lgkmcnt(4)
	s_nop 0
	v_mfma_f32_32x32x16_bf16 v[80:95], v[128:131], v[154:157], v[80:95]
	ds_read_b64_tr_b16 v[154:155], v145 offset:0x2600
	ds_read_b64_tr_b16 v[156:157], v145 offset:0x2e00
	v_mfma_f32_32x32x16_bf16 v[80:95], v[136:139], v[230:233], v[80:95]
	ds_read_b64_tr_b16 v[230:231], v145 offset:0x3600
	ds_read_b64_tr_b16 v[232:233], v145 offset:0x3e00
	s_waitcnt lgkmcnt(4)
	s_nop 0
	v_mfma_f32_32x32x16_bf16 v[64:79], v[140:143], v[146:149], v[64:79]
	ds_read_b64_tr_b16 v[146:147], v158 offset:0
	ds_read_b64_tr_b16 v[148:149], v158 offset:0x800
	v_mfma_f32_32x32x16_bf16 v[64:79], v[132:135], v[150:153], v[64:79]
	ds_read_b64_tr_b16 v[150:151], v158 offset:0x1000
	ds_read_b64_tr_b16 v[152:153], v158 offset:0x1800
	s_waitcnt lgkmcnt(4)
	s_nop 0
	v_mfma_f32_32x32x16_bf16 v[64:79], v[128:131], v[154:157], v[64:79]
	ds_read_b64_tr_b16 v[154:155], v158 offset:0x2000
	ds_read_b64_tr_b16 v[156:157], v158 offset:0x2800
	v_mfma_f32_32x32x16_bf16 v[64:79], v[136:139], v[230:233], v[64:79]
	ds_read_b64_tr_b16 v[230:231], v158 offset:0x3000
	ds_read_b64_tr_b16 v[232:233], v158 offset:0x3800
	s_waitcnt lgkmcnt(4)
	s_nop 0
	v_mfma_f32_32x32x16_bf16 v[0:15], v[140:143], v[146:149], v[0:15]
	ds_read_b64_tr_b16 v[146:147], v158 offset:0x200
	ds_read_b64_tr_b16 v[148:149], v158 offset:0xa00
	v_mfma_f32_32x32x16_bf16 v[0:15], v[132:135], v[150:153], v[0:15]
	ds_read_b64_tr_b16 v[150:151], v158 offset:0x1200
	ds_read_b64_tr_b16 v[152:153], v158 offset:0x1a00
	s_waitcnt lgkmcnt(4)
	s_nop 0
	v_mfma_f32_32x32x16_bf16 v[0:15], v[128:131], v[154:157], v[0:15]
	ds_read_b64_tr_b16 v[154:155], v158 offset:0x2200
	ds_read_b64_tr_b16 v[156:157], v158 offset:0x2a00
	v_mfma_f32_32x32x16_bf16 v[0:15], v[136:139], v[230:233], v[0:15]
	ds_read_b64_tr_b16 v[230:231], v158 offset:0x3200
	ds_read_b64_tr_b16 v[232:233], v158 offset:0x3a00
	s_waitcnt lgkmcnt(4)
	s_nop 0
	v_mfma_f32_32x32x16_bf16 v[48:63], v[140:143], v[146:149], v[48:63]
	ds_read_b64_tr_b16 v[146:147], v158 offset:0x400
	ds_read_b64_tr_b16 v[148:149], v158 offset:0xc00
	v_mfma_f32_32x32x16_bf16 v[48:63], v[132:135], v[150:153], v[48:63]
	ds_read_b64_tr_b16 v[150:151], v158 offset:0x1400
	ds_read_b64_tr_b16 v[152:153], v158 offset:0x1c00
	s_waitcnt lgkmcnt(4)
	s_nop 0
	v_mfma_f32_32x32x16_bf16 v[48:63], v[128:131], v[154:157], v[48:63]
	ds_read_b64_tr_b16 v[154:155], v158 offset:0x2400
	ds_read_b64_tr_b16 v[156:157], v158 offset:0x2c00
	v_mfma_f32_32x32x16_bf16 v[48:63], v[136:139], v[230:233], v[48:63]
	ds_read_b64_tr_b16 v[230:231], v158 offset:0x3400
	ds_read_b64_tr_b16 v[232:233], v158 offset:0x3c00
	s_waitcnt lgkmcnt(4)
	s_nop 0
	v_mfma_f32_32x32x16_bf16 v[32:47], v[140:143], v[146:149], v[32:47]
	ds_read_b64_tr_b16 v[146:147], v158 offset:0x600
	ds_read_b64_tr_b16 v[148:149], v158 offset:0xe00
	v_mfma_f32_32x32x16_bf16 v[32:47], v[132:135], v[150:153], v[32:47]
	ds_read_b64_tr_b16 v[150:151], v158 offset:0x1600
	ds_read_b64_tr_b16 v[152:153], v158 offset:0x1e00
	s_waitcnt lgkmcnt(4)
	s_nop 0
	v_mfma_f32_32x32x16_bf16 v[32:47], v[128:131], v[154:157], v[32:47]
	ds_read_b64_tr_b16 v[154:155], v158 offset:0x2600
	ds_read_b64_tr_b16 v[156:157], v158 offset:0x2e00
	v_mfma_f32_32x32x16_bf16 v[32:47], v[136:139], v[230:233], v[32:47]
	ds_read_b64_tr_b16 v[230:231], v158 offset:0x3600
	ds_read_b64_tr_b16 v[232:233], v158 offset:0x3e00
	s_waitcnt lgkmcnt(4)
	s_nop 0
	s_waitcnt lgkmcnt(0)
	v_mfma_f32_32x32x16_bf16 v[16:31], v[140:143], v[146:149], v[16:31]
	v_mfma_f32_32x32x16_bf16 v[16:31], v[132:135], v[150:153], v[16:31]
	v_mfma_f32_32x32x16_bf16 v[16:31], v[128:131], v[154:157], v[16:31]
	v_mfma_f32_32x32x16_bf16 v[16:31], v[136:139], v[230:233], v[16:31]
	s_cbranch_scc1 .LBB0_1619
	s_mov_b32 s80, s60
	s_mov_b32 s79, s81
	v_mov_b32_e32 v229, v144
	s_branch .LBB0_1598

; #define ALAS __attribute__((address_space(3)))
; __device__ __forceinline__ void qkt(f32x16& p0, f32x16& p1, const ALAS char* Ks, const bf16x8* qr, int r32, int hi) {
;   p0 = f32x16{}; p1 = f32x16{};
; #pragma unroll
;   for (int d0 = 0; d0 < 8; ++d0) { int cb = (d0 * 16 + hi * 8) * 2;
;     bf16x8 b0 = *(const ALAS bf16x8*)(Ks + KSWZ(r32, cb));
;     bf16x8 b1 = *(const ALAS bf16x8*)(Ks + KSWZ(32 + r32, cb));
;     p0 = __builtin_amdgcn_mfma_f32_32x32x16_bf16(b0, qr[d0], p0, 0, 0, 0);
;     p1 = __builtin_amdgcn_mfma_f32_32x32x16_bf16(b1, qr[d0], p1, 0, 0, 0); }
; template <int MODE> __device__ __forceinline__ void modify2(f32x16& p0, f32x16& p1, const Mod& M, int j, float& boff) {
;   const float dq = M.a0 - (float)(j * 64); const float nsl = -M.a1;
; #pragma unroll
;   for (int r = 0; r < 16; ++r) { const float cr = (float)((r & 3) + 8 * (r >> 2));
;     p0[r] = fmaf(fabsf(dq - cr), nsl, p0[r]); p1[r] = fmaf(fabsf(dq - (cr + 32.f)), nsl, p1[r]); }
;   boff = 0.f;
; }
.LBB0_1661:
	s_and_b32 s47, s19, 1
	v_mov_b32_e32 v128, v215
	v_mov_b32_e32 v129, v214
	s_lshl_b32 s8, s47, 14
	s_add_i32 s8, s8, 0
	s_add_i32 s8, s8, 0x10000
	v_lshlrev_b32_e32 v242, 4, v128
	v_lshlrev_b32_e32 v243, 4, v129
	v_and_b32_e32 v243, 0x70, v243
	v_lshl_add_u32 v241, v129, 8, s8
	v_xad_u32 v244, v242, v243, v241
	v_add_u32_e32 v240, 32, v242
	v_xad_u32 v245, v240, v243, v241
	v_add_u32_e32 v240, 64, v242
	v_xad_u32 v246, v240, v243, v241
	v_add_u32_e32 v240, 0x60, v242
	v_xad_u32 v247, v240, v243, v241
	s_lshl_b32 s8, s18, 6
	ds_read_b128 v[148:151], v244
	ds_read_b128 v[152:155], v245
	ds_read_b128 v[156:159], v246
	ds_read_b128 v[230:233], v247
	ds_read_b128 v[234:237], v244 offset:128
	ds_read_b128 v[238:241], v245 offset:128
	s_waitcnt lgkmcnt(5)
	v_mfma_f32_32x32x16_bf16 v[128:143], v[148:151], v[160:163], 0
	ds_read_b128 v[148:151], v246 offset:128
	s_waitcnt lgkmcnt(5)
	v_mfma_f32_32x32x16_bf16 v[128:143], v[152:155], v[164:167], v[128:143]
	ds_read_b128 v[152:155], v247 offset:128
	s_waitcnt lgkmcnt(5)
	v_mfma_f32_32x32x16_bf16 v[128:143], v[156:159], v[168:171], v[128:143]
	ds_read_b128 v[144:147], v244 offset:8192
	s_waitcnt lgkmcnt(5)
	v_mfma_f32_32x32x16_bf16 v[128:143], v[230:233], v[172:175], v[128:143]
	ds_read_b128 v[230:233], v245 offset:8192
	s_waitcnt lgkmcnt(5)
	v_mfma_f32_32x32x16_bf16 v[128:143], v[234:237], v[176:179], v[128:143]
	ds_read_b128 v[234:237], v246 offset:8192
	s_waitcnt lgkmcnt(5)
	v_mfma_f32_32x32x16_bf16 v[128:143], v[238:241], v[180:183], v[128:143]
	ds_read_b128 v[238:241], v247 offset:8192
	s_waitcnt lgkmcnt(5)
	v_mfma_f32_32x32x16_bf16 v[128:143], v[148:151], v[184:187], v[128:143]
	s_waitcnt lgkmcnt(4)
	v_mfma_f32_32x32x16_bf16 v[128:143], v[152:155], v[188:191], v[128:143]
	s_waitcnt lgkmcnt(3)
	v_mfma_f32_32x32x16_bf16 v[144:159], v[144:147], v[160:163], 0
	s_waitcnt lgkmcnt(2)
	v_mfma_f32_32x32x16_bf16 v[144:159], v[230:233], v[164:167], v[144:159]
	ds_read_b128 v[230:233], v244 offset:8320
	s_waitcnt lgkmcnt(2)
	v_mfma_f32_32x32x16_bf16 v[144:159], v[234:237], v[168:171], v[144:159]
	ds_read_b128 v[234:237], v245 offset:8320
	s_waitcnt lgkmcnt(2)
	v_mfma_f32_32x32x16_bf16 v[144:159], v[238:241], v[172:175], v[144:159]
	ds_read_b128 v[238:241], v246 offset:8320
	s_waitcnt lgkmcnt(2)
	v_mfma_f32_32x32x16_bf16 v[144:159], v[230:233], v[176:179], v[144:159]
	ds_read_b128 v[230:233], v247 offset:8320
	s_waitcnt lgkmcnt(2)
	v_mfma_f32_32x32x16_bf16 v[144:159], v[234:237], v[180:183], v[144:159]
	s_waitcnt lgkmcnt(1)
	v_mfma_f32_32x32x16_bf16 v[144:159], v[238:241], v[184:187], v[144:159]
	s_waitcnt lgkmcnt(0)
	v_mfma_f32_32x32x16_bf16 v[144:159], v[230:233], v[188:191], v[144:159]
	v_cvt_f32_i32_e32 v230, s8
	v_mov_b32_e32 v231, v212
	s_nop 0
	v_sub_f32_e32 v247, v231, v230
	v_fma_f32 v231, |v247|, v213, v128
	v_add_f32_e32 v128, -1.0, v247
	v_fma_f32 v232, |v128|, v213, v129
	v_add_f32_e32 v128, -2.0, v247
	v_fma_f32 v233, |v128|, v213, v130
	v_add_f32_e32 v128, 0xc0400000, v247
	v_fma_f32 v234, |v128|, v213, v131
	v_add_f32_e32 v128, 0xc1000000, v247
	v_fma_f32 v235, |v128|, v213, v132
	v_add_f32_e32 v128, 0xc1100000, v247
	v_fma_f32 v236, |v128|, v213, v133
	v_add_f32_e32 v128, 0xc1200000, v247
	v_fma_f32 v237, |v128|, v213, v134
	v_add_f32_e32 v128, 0xc1300000, v247
	v_fma_f32 v238, |v128|, v213, v135
	v_add_f32_e32 v128, 0xc1800000, v247
	v_fma_f32 v239, |v128|, v213, v136
	v_add_f32_e32 v128, 0xc1880000, v247
	v_fma_f32 v240, |v128|, v213, v137
	v_add_f32_e32 v128, 0xc1900000, v247
	v_fma_f32 v241, |v128|, v213, v138
	v_add_f32_e32 v128, 0xc1980000, v247
	v_fma_f32 v242, |v128|, v213, v139
	v_add_f32_e32 v128, 0xc1c00000, v247
	v_fma_f32 v243, |v128|, v213, v140
	v_add_f32_e32 v128, 0xc1c80000, v247
	v_fma_f32 v244, |v128|, v213, v141
	v_add_f32_e32 v128, 0xc1d00000, v247
	v_fma_f32 v245, |v128|, v213, v142
	v_add_f32_e32 v128, 0xc1d80000, v247
	v_fma_f32 v246, |v128|, v213, v143
	v_add_f32_e32 v128, 0xc2000000, v247
	v_fma_f32 v144, |v128|, v213, v144
	v_add_f32_e32 v128, 0xc2040000, v247
	v_fma_f32 v230, |v128|, v213, v145
	v_add_f32_e32 v128, 0xc2080000, v247
	v_fma_f32 v146, |v128|, v213, v146
	v_add_f32_e32 v128, 0xc20c0000, v247
	v_fma_f32 v147, |v128|, v213, v147
	v_add_f32_e32 v128, 0xc2200000, v247
	v_fma_f32 v148, |v128|, v213, v148
	v_add_f32_e32 v128, 0xc2240000, v247
	v_fma_f32 v149, |v128|, v213, v149
	v_add_f32_e32 v128, 0xc2280000, v247
	v_fma_f32 v150, |v128|, v213, v150
	v_add_f32_e32 v128, 0xc22c0000, v247
	v_fma_f32 v151, |v128|, v213, v151
	v_add_f32_e32 v128, 0xc2400000, v247
	v_fma_f32 v152, |v128|, v213, v152
	v_add_f32_e32 v128, 0xc2440000, v247
	v_fma_f32 v153, |v128|, v213, v153
	v_add_f32_e32 v128, 0xc2480000, v247
	v_fma_f32 v154, |v128|, v213, v154
	v_add_f32_e32 v128, 0xc24c0000, v247
	v_fma_f32 v155, |v128|, v213, v155
	v_add_f32_e32 v128, 0xc2600000, v247
	v_fma_f32 v156, |v128|, v213, v156
	v_add_f32_e32 v128, 0xc2640000, v247
	v_fma_f32 v157, |v128|, v213, v157
	v_add_f32_e32 v128, 0xc2680000, v247
	v_fma_f32 v158, |v128|, v213, v158
	v_add_f32_e32 v128, 0xc26c0000, v247
	v_fma_f32 v159, |v128|, v213, v159
	v_max_f32_e32 v128, v231, v232
	v_max3_f32 v128, v128, v233, v234
	v_max3_f32 v128, v128, v235, v236
	v_max3_f32 v128, v128, v237, v238
	v_max3_f32 v128, v128, v239, v240
	v_max3_f32 v128, v128, v241, v242
	v_max3_f32 v128, v128, v243, v244
	v_max3_f32 v128, v128, v245, v246
	v_max3_f32 v128, v128, v144, v230
	v_max3_f32 v128, v128, v146, v147
	v_max3_f32 v128, v128, v148, v149
	v_max3_f32 v128, v128, v150, v151
	v_max3_f32 v128, v128, v152, v153
	v_max3_f32 v128, v128, v154, v155
	v_max3_f32 v128, v128, v156, v157
	v_max3_f32 v128, v128, v158, v159
	v_mov_b32_e32 v129, v128
	s_nop 1
	v_permlane32_swap_b32_e32 v128, v129
	v_max_f32_e32 v129, v129, v129
	v_max_f32_e32 v128, v128, v128
	v_max_f32_e32 v128, v128, v129
	v_max_f32_e32 v130, v228, v228
	v_max_f32_e32 v247, v130, v128
	v_sub_f32_e32 v129, v128, v228
	v_sub_f32_e32 v128, v228, v247
	v_mul_f32_e32 v128, 0x3e0293ee, v128
	v_exp_f32_e32 v128, v128
	v_cmp_ge_f32_e32 vcc, s56, v129
	s_cmp_eq_u64 vcc, exec
	s_cselect_b64 s[8:9], -1, 0
	v_cndmask_b32_e64 v145, v128, 1.0, s[8:9]
	s_cbranch_scc1 .LBB0_1665
; __device__ __forceinline__ int crow(int r, int hi) { return (r & 3) + 8 * (r >> 2) + 4 * hi; }
; template <bool OFF>
; __device__ __forceinline__ void partialSM(f32x16& p0, f32x16& p1, float& m_reg, float& mn, float& alpha, float boff) {
;     ...
;   else { mn = fmaxf(m_reg, pmax); alpha = __builtin_amdgcn_exp2f((m_reg - mn) * C); m_reg = mn; }
;   const float mnC = (OFF ? boff - mn : -mn) * C;
; #pragma unroll
;   for (int r = 0; r < 16; ++r) p0[r] = fmaf(p0[r], C, mnC);
; #pragma unroll
;   for (int r = 0; r < 16; ++r) p1[r] = fmaf(p1[r], C, mnC);
; #pragma unroll
;   for (int r = 0; r < 16; ++r) p0[r] = __builtin_amdgcn_exp2f(p0[r]);
; }
; __device__ __forceinline__ void finishSM(f32x16& p0, f32x16& p1, float alpha, float& l_reg, bf16x8& pa0, bf16x8& pa1, bf16x8& pa2, bf16x8& pa3) {
; #pragma unroll
;   for (int r = 0; r < 16; ++r) p1[r] = __builtin_amdgcn_exp2f(p1[r]);
;   float ps = 0;
; #pragma unroll
;   for (int r = 0; r < 16; ++r) ps += p0[r];
; #pragma unroll
;   for (int r = 0; r < 16; ++r) ps += p1[r];
; __device__ __forceinline__ void b3_map(f32x16 (&o0)[4], f32x16 (&o1)[4], const AGAS bf16* __restrict__ Qb, const AGAS bf16* __restrict__ Kh, const AGAS bf16* __restrict__ V0h, const AGAS bf16* __restrict__ V1h, int NT, Mod M, ALAS char* lds) {
;     ...
;     if (__any(alpha < 1.f)) { if (hi == 0) al_l[r32] = alpha; asm volatile("s_waitcnt lgkmcnt(0)" ::: "memory");
; #pragma unroll
;       for (int r = 0; r < 16; ++r) { const float al = al_l[crow(r, hi)];
; #pragma unroll
;         for (int d = 0; d < 4; ++d) { o0[d][r] *= al; o1[d][r] *= al; } } }
	s_and_saveexec_b64 s[18:19], s[4:5]
	ds_write_b32 v218, v145 offset:128
	s_or_b64 exec, exec, s[18:19]
	s_waitcnt lgkmcnt(0)
	v_add_u32_e32 v128, s89, v196
	ds_read_b128 v[140:143], v128 offset:224
	ds_read_b128 v[136:139], v128 offset:192
	ds_read_b128 v[132:135], v128 offset:160
	ds_read_b128 v[128:131], v128 offset:128
	s_waitcnt lgkmcnt(0)
	v_pk_mul_f32 v[124:125], v[124:125], v[140:141]
	v_pk_mul_f32 v[120:121], v[120:121], v[136:137]
	v_pk_mul_f32 v[116:117], v[116:117], v[132:133]
	v_pk_mul_f32 v[126:127], v[126:127], v[142:143]
	v_pk_mul_f32 v[122:123], v[122:123], v[138:139]
	v_pk_mul_f32 v[118:119], v[118:119], v[134:135]
	v_pk_mul_f32 v[114:115], v[114:115], v[130:131]
	v_pk_mul_f32 v[112:113], v[112:113], v[128:129]
	v_pk_mul_f32 v[108:109], v[108:109], v[140:141]
	v_pk_mul_f32 v[104:105], v[104:105], v[136:137]
	v_pk_mul_f32 v[100:101], v[100:101], v[132:133]
	v_pk_mul_f32 v[110:111], v[110:111], v[142:143]
	v_pk_mul_f32 v[106:107], v[106:107], v[138:139]
	v_pk_mul_f32 v[102:103], v[102:103], v[134:135]
	v_pk_mul_f32 v[98:99], v[98:99], v[130:131]
	v_pk_mul_f32 v[96:97], v[96:97], v[128:129]
	v_pk_mul_f32 v[92:93], v[92:93], v[140:141]
	v_pk_mul_f32 v[88:89], v[88:89], v[136:137]
	v_pk_mul_f32 v[84:85], v[84:85], v[132:133]
	v_pk_mul_f32 v[94:95], v[94:95], v[142:143]
	v_pk_mul_f32 v[90:91], v[90:91], v[138:139]
	v_pk_mul_f32 v[86:87], v[86:87], v[134:135]
	v_pk_mul_f32 v[82:83], v[82:83], v[130:131]
	v_pk_mul_f32 v[80:81], v[80:81], v[128:129]
	v_pk_mul_f32 v[44:45], v[44:45], v[140:141]
	v_pk_mul_f32 v[40:41], v[40:41], v[136:137]
	v_pk_mul_f32 v[36:37], v[36:37], v[132:133]
	v_pk_mul_f32 v[46:47], v[46:47], v[142:143]
	v_pk_mul_f32 v[42:43], v[42:43], v[138:139]
	v_pk_mul_f32 v[38:39], v[38:39], v[134:135]
	v_pk_mul_f32 v[34:35], v[34:35], v[130:131]
	v_pk_mul_f32 v[32:33], v[32:33], v[128:129]
	v_pk_mul_f32 v[76:77], v[76:77], v[140:141]
	v_pk_mul_f32 v[72:73], v[72:73], v[136:137]
	v_pk_mul_f32 v[68:69], v[68:69], v[132:133]
	v_pk_mul_f32 v[78:79], v[78:79], v[142:143]
	v_pk_mul_f32 v[74:75], v[74:75], v[138:139]
	v_pk_mul_f32 v[70:71], v[70:71], v[134:135]
	v_pk_mul_f32 v[66:67], v[66:67], v[130:131]
	v_pk_mul_f32 v[64:65], v[64:65], v[128:129]
	v_pk_mul_f32 v[28:29], v[28:29], v[140:141]
	v_pk_mul_f32 v[24:25], v[24:25], v[136:137]
	v_pk_mul_f32 v[20:21], v[20:21], v[132:133]
	v_pk_mul_f32 v[30:31], v[30:31], v[142:143]
	v_pk_mul_f32 v[26:27], v[26:27], v[138:139]
	v_pk_mul_f32 v[22:23], v[22:23], v[134:135]
	v_pk_mul_f32 v[18:19], v[18:19], v[130:131]
	v_pk_mul_f32 v[16:17], v[16:17], v[128:129]
	v_pk_mul_f32 v[60:61], v[60:61], v[140:141]
	v_pk_mul_f32 v[56:57], v[56:57], v[136:137]
	v_pk_mul_f32 v[52:53], v[52:53], v[132:133]
	v_pk_mul_f32 v[62:63], v[62:63], v[142:143]
	v_pk_mul_f32 v[58:59], v[58:59], v[138:139]
	v_pk_mul_f32 v[54:55], v[54:55], v[134:135]
	v_pk_mul_f32 v[50:51], v[50:51], v[130:131]
	v_pk_mul_f32 v[48:49], v[48:49], v[128:129]
	v_pk_mul_f32 v[12:13], v[12:13], v[140:141]
	v_pk_mul_f32 v[8:9], v[8:9], v[136:137]
	v_pk_mul_f32 v[4:5], v[4:5], v[132:133]
	v_pk_mul_f32 v[14:15], v[14:15], v[142:143]
	v_pk_mul_f32 v[10:11], v[10:11], v[138:139]
	v_pk_mul_f32 v[6:7], v[6:7], v[134:135]
	v_pk_mul_f32 v[2:3], v[2:3], v[130:131]
	v_pk_mul_f32 v[0:1], v[0:1], v[128:129]
.LBB0_1665:
	v_cndmask_b32_e64 v228, v247, v228, s[8:9]
	v_mul_f32_e32 v128, 0xbe0293ee, v228
	v_fmamk_f32 v129, v231, 0x3e0293ee, v128
	v_fmamk_f32 v130, v232, 0x3e0293ee, v128
	v_exp_f32_e32 v129, v129
	v_fmamk_f32 v131, v233, 0x3e0293ee, v128
	v_exp_f32_e32 v130, v130
	v_fmamk_f32 v132, v234, 0x3e0293ee, v128
	v_exp_f32_e32 v131, v131
	v_fmamk_f32 v133, v235, 0x3e0293ee, v128
	v_fmamk_f32 v134, v236, 0x3e0293ee, v128
	v_fmamk_f32 v135, v237, 0x3e0293ee, v128
	v_fmamk_f32 v136, v238, 0x3e0293ee, v128
	v_fmamk_f32 v137, v239, 0x3e0293ee, v128
	v_fmamk_f32 v138, v240, 0x3e0293ee, v128
	v_fmamk_f32 v139, v241, 0x3e0293ee, v128
	v_fmamk_f32 v140, v242, 0x3e0293ee, v128
	v_fmamk_f32 v141, v243, 0x3e0293ee, v128
	v_fmamk_f32 v142, v244, 0x3e0293ee, v128
	v_fmamk_f32 v143, v245, 0x3e0293ee, v128
	v_fmamk_f32 v231, v246, 0x3e0293ee, v128
	v_fmamk_f32 v144, v144, 0x3e0293ee, v128
	v_fmamk_f32 v230, v230, 0x3e0293ee, v128
	v_fmamk_f32 v146, v146, 0x3e0293ee, v128
	v_fmamk_f32 v147, v147, 0x3e0293ee, v128
	v_fmamk_f32 v148, v148, 0x3e0293ee, v128
	v_fmamk_f32 v149, v149, 0x3e0293ee, v128
	v_fmamk_f32 v150, v150, 0x3e0293ee, v128
	v_fmamk_f32 v151, v151, 0x3e0293ee, v128
	v_fmamk_f32 v152, v152, 0x3e0293ee, v128
	v_fmamk_f32 v153, v153, 0x3e0293ee, v128
	v_fmamk_f32 v154, v154, 0x3e0293ee, v128
	v_fmamk_f32 v155, v155, 0x3e0293ee, v128
	v_fmamk_f32 v156, v156, 0x3e0293ee, v128
	v_fmamk_f32 v157, v157, 0x3e0293ee, v128
	v_fmamk_f32 v158, v158, 0x3e0293ee, v128
	v_fmac_f32_e32 v128, 0x3e0293ee, v159
	v_exp_f32_e32 v132, v132
	v_exp_f32_e32 v133, v133
	v_exp_f32_e32 v236, v128
	v_add_f32_e32 v128, 0, v129
	v_exp_f32_e32 v134, v134
	v_add_f32_e32 v128, v130, v128
	v_exp_f32_e32 v135, v135
	v_add_f32_e32 v128, v131, v128
	v_exp_f32_e32 v136, v136
	v_add_f32_e32 v128, v132, v128
	v_exp_f32_e32 v137, v137
	v_add_f32_e32 v128, v133, v128
	v_exp_f32_e32 v138, v138
	v_add_f32_e32 v128, v134, v128
	v_exp_f32_e32 v139, v139
	v_add_f32_e32 v128, v135, v128
	v_exp_f32_e32 v159, v140
	v_add_f32_e32 v128, v136, v128
	v_exp_f32_e32 v232, v141
	v_add_f32_e32 v128, v137, v128
	v_exp_f32_e32 v233, v142
	v_add_f32_e32 v128, v138, v128
	v_exp_f32_e32 v234, v143
	v_add_f32_e32 v128, v139, v128
	v_exp_f32_e32 v231, v231
	v_add_f32_e32 v128, v159, v128
	v_exp_f32_e32 v235, v144
	v_add_f32_e32 v128, v232, v128
	v_exp_f32_e32 v230, v230
	v_add_f32_e32 v128, v233, v128
; __device__ __forceinline__ void finishSM(f32x16& p0, f32x16& p1, float alpha, float& l_reg, bf16x8& pa0, bf16x8& pa1, bf16x8& pa2, bf16x8& pa3) {
; #pragma unroll
;   for (int r = 0; r < 16; ++r) p1[r] = __builtin_amdgcn_exp2f(p1[r]);
;   float ps = 0;
; #pragma unroll
;   for (int r = 0; r < 16; ++r) ps += p0[r];
; #pragma unroll
;   for (int r = 0; r < 16; ++r) ps += p1[r];
;   { auto rr = __builtin_amdgcn_permlane32_swap(__float_as_uint(ps), __float_as_uint(ps), false, false);
;     ps = __uint_as_float(rr[0]) + __uint_as_float(rr[1]); }
;   l_reg = l_reg * alpha + ps;
;     ...
;   PK4(p0, 0, pa0); PK4(p0, 8, pa1); PK4(p1, 0, pa2); PK4(p1, 8, pa3);
	v_exp_f32_e32 v146, v146
	v_add_f32_e32 v128, v234, v128
	v_exp_f32_e32 v147, v147
	v_add_f32_e32 v128, v231, v128
	v_exp_f32_e32 v148, v148
	v_add_f32_e32 v128, v235, v128
	v_exp_f32_e32 v149, v149
	v_add_f32_e32 v128, v230, v128
	v_exp_f32_e32 v150, v150
	v_add_f32_e32 v128, v146, v128
	v_exp_f32_e32 v151, v151
	v_add_f32_e32 v128, v147, v128
	v_exp_f32_e32 v152, v152
	v_add_f32_e32 v128, v148, v128
	v_exp_f32_e32 v153, v153
	v_add_f32_e32 v128, v149, v128
	v_exp_f32_e32 v154, v154
	v_add_f32_e32 v128, v150, v128
	v_exp_f32_e32 v155, v155
	v_add_f32_e32 v128, v151, v128
	v_exp_f32_e32 v156, v156
	v_add_f32_e32 v128, v152, v128
	v_exp_f32_e32 v157, v157
	v_add_f32_e32 v128, v153, v128
	v_exp_f32_e32 v158, v158
	v_add_f32_e32 v128, v154, v128
	v_add_f32_e32 v128, v155, v128
	v_add_f32_e32 v128, v156, v128
	v_add_f32_e32 v128, v157, v128
	s_sub_i32 s78, s78, s48
	s_xor_b64 s[8:9], s[48:49], -1
	v_add_f32_e32 v128, v158, v128
	v_add_f32_e32 v128, v236, v128
	v_mov_b32_e32 v140, v128
	s_nop 1
	v_permlane32_swap_b32_e32 v128, v140
	v_add_f32_e32 v144, v128, v140
	v_cvt_pk_bf16_f32 v140, v129, v130
	v_cvt_pk_bf16_f32 v141, v131, v132
	v_cvt_pk_bf16_f32 v142, v133, v134
	v_cvt_pk_bf16_f32 v143, v135, v136
	v_cvt_pk_bf16_f32 v132, v137, v138
	v_cvt_pk_bf16_f32 v133, v139, v159
	v_cvt_pk_bf16_f32 v134, v232, v233
	v_cvt_pk_bf16_f32 v135, v234, v231
	v_cvt_pk_bf16_f32 v128, v235, v230
	v_cvt_pk_bf16_f32 v129, v146, v147
	v_cvt_pk_bf16_f32 v130, v148, v149
	v_cvt_pk_bf16_f32 v131, v150, v151
	v_cvt_pk_bf16_f32 v136, v152, v153
	v_cvt_pk_bf16_f32 v137, v154, v155
	v_cvt_pk_bf16_f32 v138, v156, v157
	v_cvt_pk_bf16_f32 v139, v158, v236
	s_waitcnt lgkmcnt(0)
	v_fmac_f32_e32 v144, v229, v145
	v_lshl_add_u32 v145, s47, 15, v227
	ds_read_b64_tr_b16 v[146:147], v145 offset:0
	ds_read_b64_tr_b16 v[148:149], v145 offset:0x800
	ds_read_b64_tr_b16 v[150:151], v145 offset:0x1000
	v_permlane32_swap_b32_e32 v140, v142
	v_permlane32_swap_b32_e32 v141, v143
	ds_read_b64_tr_b16 v[152:153], v145 offset:0x1800
	ds_read_b64_tr_b16 v[154:155], v145 offset:0x2000
	ds_read_b64_tr_b16 v[156:157], v145 offset:0x2800
	ds_read_b64_tr_b16 v[230:231], v145 offset:0x3000
	ds_read_b64_tr_b16 v[232:233], v145 offset:0x3800
	v_permlane32_swap_b32_e32 v132, v134
	s_waitcnt lgkmcnt(4)
	v_permlane32_swap_b32_e32 v133, v135
	v_mfma_f32_32x32x16_bf16 v[112:127], v[140:143], v[146:149], v[112:127]
	v_permlane32_swap_b32_e32 v128, v130
	v_permlane32_swap_b32_e32 v129, v131
	ds_read_b64_tr_b16 v[146:147], v145 offset:0x200
	ds_read_b64_tr_b16 v[148:149], v145 offset:0xa00
	v_permlane32_swap_b32_e32 v136, v138
	v_mfma_f32_32x32x16_bf16 v[112:127], v[132:135], v[150:153], v[112:127]
	ds_read_b64_tr_b16 v[150:151], v145 offset:0x1200
	ds_read_b64_tr_b16 v[152:153], v145 offset:0x1a00
	s_waitcnt lgkmcnt(4)
	v_permlane32_swap_b32_e32 v137, v139
	v_add_u32_e32 v158, 0x4000, v145
	s_add_i32 s70, s70, s8
	v_mfma_f32_32x32x16_bf16 v[112:127], v[128:131], v[154:157], v[112:127]
	ds_read_b64_tr_b16 v[154:155], v145 offset:0x2200
	ds_read_b64_tr_b16 v[156:157], v145 offset:0x2a00
	s_xor_b64 s[42:43], s[42:43], -1
	s_cmp_eq_u32 s57, 32
	v_mfma_f32_32x32x16_bf16 v[112:127], v[136:139], v[230:233], v[112:127]
	ds_read_b64_tr_b16 v[230:231], v145 offset:0x3200
	ds_read_b64_tr_b16 v[232:233], v145 offset:0x3a00
	s_waitcnt lgkmcnt(4)
	s_nop 0
	v_mfma_f32_32x32x16_bf16 v[80:95], v[140:143], v[146:149], v[80:95]
	ds_read_b64_tr_b16 v[146:147], v145 offset:0x400
	ds_read_b64_tr_b16 v[148:149], v145 offset:0xc00
	v_mfma_f32_32x32x16_bf16 v[80:95], v[132:135], v[150:153], v[80:95]
	ds_read_b64_tr_b16 v[150:151], v145 offset:0x1400
	ds_read_b64_tr_b16 v[152:153], v145 offset:0x1c00
	s_waitcnt lgkmcnt(4)
	s_nop 0
	v_mfma_f32_32x32x16_bf16 v[80:95], v[128:131], v[154:157], v[80:95]
	ds_read_b64_tr_b16 v[154:155], v145 offset:0x2400
	ds_read_b64_tr_b16 v[156:157], v145 offset:0x2c00
	v_mfma_f32_32x32x16_bf16 v[80:95], v[136:139], v[230:233], v[80:95]
	ds_read_b64_tr_b16 v[230:231], v145 offset:0x3400
	ds_read_b64_tr_b16 v[232:233], v145 offset:0x3c00
	s_waitcnt lgkmcnt(4)
; #define PVR(S, VB, D0, K0) do { S##l0 = tr_read<v_rd_off(D0, K0, 0)>(VB); S##h0 = tr_read<v_rd_off(D0, K0, 1)>(VB); S##l1 = tr_read<v_rd_off(D0, (K0) + 1, 0)>(VB); S##h1 = tr_read<v_rd_off(D0, (K0) + 1, 1)>(VB); } while (0)
; #define PVW(S, N) asm volatile("s_waitcnt lgkmcnt(" #N ")" : "+v"(S##l0), "+v"(S##h0), "+v"(S##l1), "+v"(S##h1) :: "memory")
; #define PVM(O, S, PA, PB) do { O = __builtin_amdgcn_mfma_f32_32x32x16_bf16(PA, PVK(S##l0, S##h0), O, 0, 0, 0); O = __builtin_amdgcn_mfma_f32_32x32x16_bf16(PB, PVK(S##l1, S##h1), O, 0, 0, 0); } while (0)
; __device__ __forceinline__ void pv_256(f32x16* o0, f32x16* o1, int v0, int v1, bf16x8 pa0, bf16x8 pa1, bf16x8 pa2, bf16x8 pa3) {
;   s16x4 Al0, Ah0, Al1, Ah1, Bl0, Bh0, Bl1, Bh1;
;   PVR(A, v0, 0, 0); PVR(B, v0, 0, 2);
;   PVW(A, 4); PVM(o0[0], A, pa0, pa1); PVR(A, v0, 1, 0);
;   PVW(B, 4); PVM(o0[0], B, pa2, pa3); PVR(B, v0, 1, 2);
;   PVW(A, 4); PVM(o0[1], A, pa0, pa1); PVR(A, v0, 2, 0);
;   PVW(B, 4); PVM(o0[1], B, pa2, pa3); PVR(B, v0, 2, 2);
;   PVW(A, 4); PVM(o0[2], A, pa0, pa1); PVR(A, v0, 3, 0);
;   PVW(B, 4); PVM(o0[2], B, pa2, pa3); PVR(B, v0, 3, 2);
;   PVW(A, 4); PVM(o0[3], A, pa0, pa1); PVR(A, v1, 0, 0);
;   PVW(B, 4); PVM(o0[3], B, pa2, pa3); PVR(B, v1, 0, 2);
;   PVW(A, 4); PVM(o1[0], A, pa0, pa1); PVR(A, v1, 1, 0);
;   PVW(B, 4); PVM(o1[0], B, pa2, pa3); PVR(B, v1, 1, 2);
;   PVW(A, 4); PVM(o1[1], A, pa0, pa1); PVR(A, v1, 2, 0);
;   PVW(B, 4); PVM(o1[1], B, pa2, pa3); PVR(B, v1, 2, 2);
;   PVW(A, 4); PVM(o1[2], A, pa0, pa1); PVR(A, v1, 3, 0);
;   PVW(B, 4); PVM(o1[2], B, pa2, pa3); PVR(B, v1, 3, 2);
;   PVW(A, 4); PVM(o1[3], A, pa0, pa1);
;   PVW(B, 0); PVM(o1[3], B, pa2, pa3);
; }
	s_nop 0
	v_mfma_f32_32x32x16_bf16 v[64:79], v[140:143], v[146:149], v[64:79]
	ds_read_b64_tr_b16 v[146:147], v145 offset:0x600
	ds_read_b64_tr_b16 v[148:149], v145 offset:0xe00
	v_mfma_f32_32x32x16_bf16 v[64:79], v[132:135], v[150:153], v[64:79]
	ds_read_b64_tr_b16 v[150:151], v145 offset:0x1600
	ds_read_b64_tr_b16 v[152:153], v145 offset:0x1e00
	s_waitcnt lgkmcnt(4)
	s_nop 0
	v_mfma_f32_32x32x16_bf16 v[64:79], v[128:131], v[154:157], v[64:79]
	ds_read_b64_tr_b16 v[154:155], v145 offset:0x2600
	ds_read_b64_tr_b16 v[156:157], v145 offset:0x2e00
	v_mfma_f32_32x32x16_bf16 v[64:79], v[136:139], v[230:233], v[64:79]
	ds_read_b64_tr_b16 v[230:231], v145 offset:0x3600
	ds_read_b64_tr_b16 v[232:233], v145 offset:0x3e00
	s_waitcnt lgkmcnt(4)
	s_nop 0
	v_mfma_f32_32x32x16_bf16 v[48:63], v[140:143], v[146:149], v[48:63]
	ds_read_b64_tr_b16 v[146:147], v158 offset:0
	ds_read_b64_tr_b16 v[148:149], v158 offset:0x800
	v_mfma_f32_32x32x16_bf16 v[48:63], v[132:135], v[150:153], v[48:63]
	ds_read_b64_tr_b16 v[150:151], v158 offset:0x1000
	ds_read_b64_tr_b16 v[152:153], v158 offset:0x1800
	s_waitcnt lgkmcnt(4)
	s_nop 0
	v_mfma_f32_32x32x16_bf16 v[48:63], v[128:131], v[154:157], v[48:63]
	ds_read_b64_tr_b16 v[154:155], v158 offset:0x2000
	ds_read_b64_tr_b16 v[156:157], v158 offset:0x2800
	v_mfma_f32_32x32x16_bf16 v[48:63], v[136:139], v[230:233], v[48:63]
	ds_read_b64_tr_b16 v[230:231], v158 offset:0x3000
	ds_read_b64_tr_b16 v[232:233], v158 offset:0x3800
	s_waitcnt lgkmcnt(4)
	s_nop 0
	v_mfma_f32_32x32x16_bf16 v[96:111], v[140:143], v[146:149], v[96:111]
	ds_read_b64_tr_b16 v[146:147], v158 offset:0x200
	ds_read_b64_tr_b16 v[148:149], v158 offset:0xa00
	v_mfma_f32_32x32x16_bf16 v[96:111], v[132:135], v[150:153], v[96:111]
	ds_read_b64_tr_b16 v[150:151], v158 offset:0x1200
	ds_read_b64_tr_b16 v[152:153], v158 offset:0x1a00
	s_waitcnt lgkmcnt(4)
	s_nop 0
	v_mfma_f32_32x32x16_bf16 v[96:111], v[128:131], v[154:157], v[96:111]
	ds_read_b64_tr_b16 v[154:155], v158 offset:0x2200
	ds_read_b64_tr_b16 v[156:157], v158 offset:0x2a00
	v_mfma_f32_32x32x16_bf16 v[96:111], v[136:139], v[230:233], v[96:111]
	ds_read_b64_tr_b16 v[230:231], v158 offset:0x3200
	ds_read_b64_tr_b16 v[232:233], v158 offset:0x3a00
	s_waitcnt lgkmcnt(4)
	s_nop 0
	v_mfma_f32_32x32x16_bf16 v[32:47], v[140:143], v[146:149], v[32:47]
	ds_read_b64_tr_b16 v[146:147], v158 offset:0x400
	ds_read_b64_tr_b16 v[148:149], v158 offset:0xc00
	v_mfma_f32_32x32x16_bf16 v[32:47], v[132:135], v[150:153], v[32:47]
	ds_read_b64_tr_b16 v[150:151], v158 offset:0x1400
	ds_read_b64_tr_b16 v[152:153], v158 offset:0x1c00
	s_waitcnt lgkmcnt(4)
	s_nop 0
	v_mfma_f32_32x32x16_bf16 v[32:47], v[128:131], v[154:157], v[32:47]
	ds_read_b64_tr_b16 v[154:155], v158 offset:0x2400
	ds_read_b64_tr_b16 v[156:157], v158 offset:0x2c00
	v_mfma_f32_32x32x16_bf16 v[32:47], v[136:139], v[230:233], v[32:47]
	ds_read_b64_tr_b16 v[230:231], v158 offset:0x3400
	ds_read_b64_tr_b16 v[232:233], v158 offset:0x3c00
	s_waitcnt lgkmcnt(4)
	s_nop 0
	v_mfma_f32_32x32x16_bf16 v[16:31], v[140:143], v[146:149], v[16:31]
	ds_read_b64_tr_b16 v[146:147], v158 offset:0x600
	ds_read_b64_tr_b16 v[148:149], v158 offset:0xe00
	v_mfma_f32_32x32x16_bf16 v[16:31], v[132:135], v[150:153], v[16:31]
	ds_read_b64_tr_b16 v[150:151], v158 offset:0x1600
	ds_read_b64_tr_b16 v[152:153], v158 offset:0x1e00
	s_waitcnt lgkmcnt(4)
	s_nop 0
	v_mfma_f32_32x32x16_bf16 v[16:31], v[128:131], v[154:157], v[16:31]
	ds_read_b64_tr_b16 v[154:155], v158 offset:0x2600
	ds_read_b64_tr_b16 v[156:157], v158 offset:0x2e00
	v_mfma_f32_32x32x16_bf16 v[16:31], v[136:139], v[230:233], v[16:31]
	ds_read_b64_tr_b16 v[230:231], v158 offset:0x3600
	ds_read_b64_tr_b16 v[232:233], v158 offset:0x3e00
	s_waitcnt lgkmcnt(4)
	s_nop 0
	s_waitcnt lgkmcnt(0)
	v_mfma_f32_32x32x16_bf16 v[0:15], v[140:143], v[146:149], v[0:15]
	v_mfma_f32_32x32x16_bf16 v[0:15], v[132:135], v[150:153], v[0:15]
	v_mfma_f32_32x32x16_bf16 v[0:15], v[128:131], v[154:157], v[0:15]
	v_mfma_f32_32x32x16_bf16 v[0:15], v[136:139], v[230:233], v[0:15]
	s_cbranch_scc1 .LBB0_1667
	s_mov_b32 s18, s46
	s_mov_b32 s19, s57
	v_mov_b32_e32 v229, v144
	s_branch .LBB0_1646
